# v29: v18 plus GEMM compute segments raise priority before the opening barrier and drop the redundant lgkmcnt(0) after it, so the first MFMA issues right after release
# speedup vs baseline: 1.0004x; 1.0004x over previous
; #define PG8_STAGE(bufoff, gbase, voff) do { _Pragma("unroll") for (int _i = 0; _i < 2; ++_i) \
;         __builtin_amdgcn_global_load_lds((const unsigned*)((const char*)(gbase) + (voff)[_i]), (PG8_LAS unsigned*)(lds + (bufoff) + ldsw + _i * 8192), 16, 0, 0); } while (0)
; #define PG8_LDA(dst, b, h) do { _Pragma("unroll") for (int m = 0; m < 4; ++m) _Pragma("unroll") for (int k = 0; k < 2; ++k) dst[m][k] = *(const PG8_LAS bf16x8*)(lds + PG8_SA(b, h) + aoff + m * 2048 + k * 1024); } while (0)
; #define PG8_LDB(dst, b, h) do { _Pragma("unroll") for (int n = 0; n < 2; ++n) _Pragma("unroll") for (int k = 0; k < 2; ++k) dst[n][k] = *(const PG8_LAS bf16x8*)(lds + PG8_SB(b, h) + boff + n * 2048 + k * 1024); } while (0)
; #define PG8_MMA(ai, bj, At, Bt) do { __builtin_amdgcn_s_setprio(1); _Pragma("unroll") for (int m = 0; m < 4; ++m) _Pragma("unroll") for (int n = 0; n < 2; ++n) _Pragma("unroll") for (int k = 0; k < 2; ++k) \
;         acc[ai][bj][m][n] = __builtin_amdgcn_mfma_f32_16x16x32_bf16(Bt[n][k], At[m][k], acc[ai][bj][m][n], 0, 0, 0); __builtin_amdgcn_s_setprio(0); } while (0)
; #define PG8_WAIT_V(n) asm volatile("s_waitcnt vmcnt(" #n ")" ::: "memory")
; #define PG8_BAR __builtin_amdgcn_s_barrier()
; template <class Epi, class Sched, bool ALIGN_EPI = false, bool SP2 = false>
; __device__ __forceinline__ void gemm_phase(PG8_LAS unsigned char* lds, const Gemm g, const Sched& S, const Epi& E, const int wid) {
;     ...
;         for (int t = 0; t < nt; t += 2) {
;             const bool last = (t == nt - 2);
;             const char* a1 = cA + (size_t)(t + 1) * kstep;
;             const char* a2 = last ? nA : cA + (size_t)(t + 2) * kstep; const char* b2 = last ? nB : cB + (size_t)(t + 2) * kstep;
;             const char* a3 = a2 + kstep; const char* b3 = b2 + kstep;
;             if (last && has_next) S.a_ready(nxt);
;             if constexpr (SP2) {
;             PG8_LDB(B0, 0, 0); PG8_LDB(B1, 0, 1); PG8_SCHED; PG8_LDA(At, 0, 0); PG8_STAGE(PG8_SA(1, 1), a1 + hstep, voffA);
;             PG8_WAIT_V(8); PG8_WAIT_L(0); PG8_BAR; PG8_MMA(0, 0, At, B0); PG8_MMA(0, 1, At, B1); PG8_BAR; PG8_SCHED;
;             PG8_LDA(At, 0, 1); PG8_STAGE(PG8_SB(0, 0), b2, voffB); PG8_STAGE(PG8_SB(0, 1), b2 + hstep, voffB); PG8_STAGE(PG8_SA(0, 0), a2, voffA);
;             PG8_WAIT_V(8); PG8_WAIT_L(0); PG8_BAR; PG8_MMA(1, 0, At, B0); PG8_MMA(1, 1, At, B1); PG8_BAR; PG8_SCHED;
.LBB0_188:
	s_add_u32 s37, s28, s36
	s_addc_u32 s42, s29, 0
	s_add_u32 s40, s37, 0x100
	s_addc_u32 s41, s42, 0
	s_and_b64 s[38:39], s[34:35], exec
	s_cselect_b32 s39, s19, s41
	s_cselect_b32 s38, s93, s40
	s_add_u32 s36, s24, s36
	s_addc_u32 s40, s25, 0
	s_add_u32 s36, s36, 0x100
	s_addc_u32 s40, s40, 0
	s_add_i32 vcc_lo, 0, 0x10000
	s_and_b64 s[34:35], s[34:35], exec
	s_cselect_b32 s41, s17, s40
	s_cselect_b32 s40, s94, s36
	s_add_i32 s35, 0, 0x14000
	s_add_u32 s44, s37, 0x10080
	s_addc_u32 s45, s42, 0
	s_add_i32 s97, vcc_lo, s85
	s_add_i32 m0, s46, 0xc000
	s_add_i32 s21, s46, 0xe000
	s_add_i32 s63, s97, 0x2000
	v_add_u32_e32 v143, vcc_lo, v141
	s_add_u32 s42, s40, 0x10000
	ds_read_b128 v[136:139], v143
	ds_read_b128 v[144:147], v143 offset:1024
	ds_read_b128 v[148:151], v143 offset:2048
	ds_read_b128 v[152:155], v143 offset:3072
	v_add_u32_e32 v143, s35, v141
	s_addc_u32 s43, s41, 0
	s_add_i32 s96, s35, s85
	ds_read_b128 v[156:159], v143
	ds_read_b128 v[160:163], v143 offset:1024
	ds_read_b128 v[164:167], v143 offset:2048
	ds_read_b128 v[168:171], v143 offset:3072
	s_add_i32 s95, s96, 0x2000
	s_add_i32 s62, 0, 0x18000
	s_add_i32 s61, 0, 0x1c000
	s_add_u32 s36, s38, 0x10000
	s_addc_u32 s37, s39, 0
	s_add_i32 s60, s62, s85
	s_add_i32 s54, s60, 0x2000
	s_add_u32 s34, s40, 0x10080
	s_addc_u32 s35, s41, 0
	s_add_i32 vcc_hi, s61, s85
	s_add_i32 vcc_lo, vcc_hi, 0x2000
	v_lshl_add_u64 v[200:201], s[44:45], 0, v[130:131]
	ds_read_b128 v[172:175], v142
	ds_read_b128 v[176:179], v142 offset:1024
	ds_read_b128 v[180:183], v142 offset:2048
	ds_read_b128 v[184:187], v142 offset:3072
	ds_read_b128 v[188:191], v142 offset:4096
	ds_read_b128 v[192:195], v142 offset:5120
	ds_read_b128 v[212:215], v142 offset:6144
	ds_read_b128 v[216:219], v142 offset:7168
	global_load_lds_dwordx4 v[200:201], off
	v_lshl_add_u64 v[200:201], s[44:45], 0, v[132:133]
	s_mov_b32 m0, s21
	s_nop 0
	global_load_lds_dwordx4 v[200:201], off
	s_waitcnt vmcnt(8)
	s_waitcnt lgkmcnt(0)
	s_setprio 1
	s_barrier
	v_mfma_f32_16x16x32_bf16 v[126:129], v[136:139], v[172:175], v[126:129]
	v_mfma_f32_16x16x32_bf16 v[122:125], v[148:151], v[172:175], v[122:125]
	v_mfma_f32_16x16x32_bf16 v[118:121], v[136:139], v[180:183], v[118:121]
	v_mfma_f32_16x16x32_bf16 v[110:113], v[148:151], v[180:183], v[110:113]
	v_mfma_f32_16x16x32_bf16 v[102:105], v[136:139], v[188:191], v[102:105]
	v_mfma_f32_16x16x32_bf16 v[94:97], v[148:151], v[188:191], v[94:97]
	v_mfma_f32_16x16x32_bf16 v[86:89], v[136:139], v[212:215], v[86:89]
	v_mfma_f32_16x16x32_bf16 v[78:81], v[148:151], v[212:215], v[78:81]
	v_mfma_f32_16x16x32_bf16 v[126:129], v[144:147], v[176:179], v[126:129]
	v_mfma_f32_16x16x32_bf16 v[122:125], v[152:155], v[176:179], v[122:125]
	v_mfma_f32_16x16x32_bf16 v[118:121], v[144:147], v[184:187], v[118:121]
	v_mfma_f32_16x16x32_bf16 v[110:113], v[152:155], v[184:187], v[110:113]
	v_mfma_f32_16x16x32_bf16 v[102:105], v[144:147], v[192:195], v[102:105]
	v_mfma_f32_16x16x32_bf16 v[94:97], v[152:155], v[192:195], v[94:97]
	v_mfma_f32_16x16x32_bf16 v[86:89], v[144:147], v[216:219], v[86:89]
	v_mfma_f32_16x16x32_bf16 v[78:81], v[152:155], v[216:219], v[78:81]
	s_setprio 0
	s_setprio 1
	v_mfma_f32_16x16x32_bf16 v[114:117], v[156:159], v[172:175], v[114:117]
	v_mfma_f32_16x16x32_bf16 v[106:109], v[164:167], v[172:175], v[106:109]
	v_mfma_f32_16x16x32_bf16 v[98:101], v[156:159], v[180:183], v[98:101]
	v_mfma_f32_16x16x32_bf16 v[90:93], v[164:167], v[180:183], v[90:93]
	v_mfma_f32_16x16x32_bf16 v[82:85], v[156:159], v[188:191], v[82:85]
	v_mfma_f32_16x16x32_bf16 v[74:77], v[164:167], v[188:191], v[74:77]
	v_mfma_f32_16x16x32_bf16 v[70:73], v[156:159], v[212:215], v[70:73]
	v_mfma_f32_16x16x32_bf16 v[66:69], v[164:167], v[212:215], v[66:69]
	v_mfma_f32_16x16x32_bf16 v[114:117], v[160:163], v[176:179], v[114:117]
	v_mfma_f32_16x16x32_bf16 v[106:109], v[168:171], v[176:179], v[106:109]
	v_mfma_f32_16x16x32_bf16 v[98:101], v[160:163], v[184:187], v[98:101]
	v_mfma_f32_16x16x32_bf16 v[90:93], v[168:171], v[184:187], v[90:93]
	v_mfma_f32_16x16x32_bf16 v[82:85], v[160:163], v[192:195], v[82:85]
	v_mfma_f32_16x16x32_bf16 v[74:77], v[168:171], v[192:195], v[74:77]
	v_mfma_f32_16x16x32_bf16 v[70:73], v[160:163], v[216:219], v[70:73]
	v_mfma_f32_16x16x32_bf16 v[66:69], v[168:171], v[216:219], v[66:69]
	s_setprio 0
	s_barrier
	s_mov_b32 m0, s97
	v_lshl_add_u64 v[200:201], s[40:41], 0, v[0:1]
	ds_read_b128 v[172:175], v142 offset:16384
	ds_read_b128 v[176:179], v142 offset:17408
	ds_read_b128 v[180:183], v142 offset:18432
	ds_read_b128 v[184:187], v142 offset:19456
	ds_read_b128 v[188:191], v142 offset:20480
	ds_read_b128 v[192:195], v142 offset:21504
	ds_read_b128 v[212:215], v142 offset:22528
	ds_read_b128 v[216:219], v142 offset:23552
	global_load_lds_dwordx4 v[200:201], off
	v_lshl_add_u64 v[202:203], s[40:41], 0, v[134:135]
	s_mov_b32 m0, s63
	v_lshl_add_u64 v[208:209], s[42:43], 0, v[0:1]
	global_load_lds_dwordx4 v[202:203], off
	s_mov_b32 m0, s96
	v_lshl_add_u64 v[210:211], s[38:39], 0, v[132:133]
	global_load_lds_dwordx4 v[208:209], off
	v_lshl_add_u64 v[208:209], s[42:43], 0, v[134:135]
	s_mov_b32 m0, s95
	s_nop 0
	global_load_lds_dwordx4 v[208:209], off
	v_lshl_add_u64 v[208:209], s[38:39], 0, v[130:131]
	s_mov_b32 m0, s46
	s_nop 0
	global_load_lds_dwordx4 v[208:209], off
	s_mov_b32 m0, s67
	s_nop 0
	global_load_lds_dwordx4 v[210:211], off
	s_waitcnt vmcnt(8)
	s_waitcnt lgkmcnt(0)
	s_setprio 1
	s_barrier
; #define PG8_STAGE(bufoff, gbase, voff) do { _Pragma("unroll") for (int _i = 0; _i < 2; ++_i) \
;         __builtin_amdgcn_global_load_lds((const unsigned*)((const char*)(gbase) + (voff)[_i]), (PG8_LAS unsigned*)(lds + (bufoff) + ldsw + _i * 8192), 16, 0, 0); } while (0)
; #define PG8_LDA(dst, b, h) do { _Pragma("unroll") for (int m = 0; m < 4; ++m) _Pragma("unroll") for (int k = 0; k < 2; ++k) dst[m][k] = *(const PG8_LAS bf16x8*)(lds + PG8_SA(b, h) + aoff + m * 2048 + k * 1024); } while (0)
; #define PG8_LDB(dst, b, h) do { _Pragma("unroll") for (int n = 0; n < 2; ++n) _Pragma("unroll") for (int k = 0; k < 2; ++k) dst[n][k] = *(const PG8_LAS bf16x8*)(lds + PG8_SB(b, h) + boff + n * 2048 + k * 1024); } while (0)
; #define PG8_MMA(ai, bj, At, Bt) do { __builtin_amdgcn_s_setprio(1); _Pragma("unroll") for (int m = 0; m < 4; ++m) _Pragma("unroll") for (int n = 0; n < 2; ++n) _Pragma("unroll") for (int k = 0; k < 2; ++k) \
;         acc[ai][bj][m][n] = __builtin_amdgcn_mfma_f32_16x16x32_bf16(Bt[n][k], At[m][k], acc[ai][bj][m][n], 0, 0, 0); __builtin_amdgcn_s_setprio(0); } while (0)
; #define PG8_WAIT_V(n) asm volatile("s_waitcnt vmcnt(" #n ")" ::: "memory")
; #define PG8_WAIT_L(n) asm volatile("s_waitcnt lgkmcnt(" #n ")" ::: "memory")
; #define PG8_BAR __builtin_amdgcn_s_barrier()
; #define PG8_SCHED __builtin_amdgcn_sched_barrier(0)
; template <class Epi, class Sched, bool ALIGN_EPI = false, bool SP2 = false>
; __device__ __forceinline__ void gemm_phase(PG8_LAS unsigned char* lds, const Gemm g, const Sched& S, const Epi& E, const int wid) {
;     ...
;             PG8_WAIT_V(8); PG8_WAIT_L(0); PG8_BAR; PG8_MMA(1, 0, At, B0); PG8_MMA(1, 1, At, B1); PG8_BAR; PG8_SCHED;
;             PG8_LDB(B0, 1, 0); PG8_LDB(B1, 1, 1); PG8_SCHED; PG8_LDA(At, 1, 0); PG8_STAGE(PG8_SA(0, 1), a2 + hstep, voffA);
;             PG8_WAIT_V(8); PG8_WAIT_L(0); PG8_BAR; PG8_MMA(0, 0, At, B0); PG8_MMA(0, 1, At, B1); PG8_BAR; PG8_SCHED;
	v_mfma_f32_16x16x32_bf16 v[62:65], v[136:139], v[172:175], v[62:65]
	v_mfma_f32_16x16x32_bf16 v[58:61], v[148:151], v[172:175], v[58:61]
	v_mfma_f32_16x16x32_bf16 v[54:57], v[136:139], v[180:183], v[54:57]
	v_mfma_f32_16x16x32_bf16 v[46:49], v[148:151], v[180:183], v[46:49]
	v_mfma_f32_16x16x32_bf16 v[38:41], v[136:139], v[188:191], v[38:41]
	v_mfma_f32_16x16x32_bf16 v[30:33], v[148:151], v[188:191], v[30:33]
	v_mfma_f32_16x16x32_bf16 v[22:25], v[136:139], v[212:215], v[22:25]
	v_mfma_f32_16x16x32_bf16 v[14:17], v[148:151], v[212:215], v[14:17]
	v_mfma_f32_16x16x32_bf16 v[62:65], v[144:147], v[176:179], v[62:65]
	v_mfma_f32_16x16x32_bf16 v[58:61], v[152:155], v[176:179], v[58:61]
	v_mfma_f32_16x16x32_bf16 v[54:57], v[144:147], v[184:187], v[54:57]
	v_mfma_f32_16x16x32_bf16 v[46:49], v[152:155], v[184:187], v[46:49]
	v_mfma_f32_16x16x32_bf16 v[38:41], v[144:147], v[192:195], v[38:41]
	v_mfma_f32_16x16x32_bf16 v[30:33], v[152:155], v[192:195], v[30:33]
	v_mfma_f32_16x16x32_bf16 v[22:25], v[144:147], v[216:219], v[22:25]
	v_mfma_f32_16x16x32_bf16 v[14:17], v[152:155], v[216:219], v[14:17]
	s_setprio 0
	s_setprio 1
	v_mfma_f32_16x16x32_bf16 v[50:53], v[156:159], v[172:175], v[50:53]
	v_mfma_f32_16x16x32_bf16 v[42:45], v[164:167], v[172:175], v[42:45]
	v_mfma_f32_16x16x32_bf16 v[34:37], v[156:159], v[180:183], v[34:37]
	v_mfma_f32_16x16x32_bf16 v[26:29], v[164:167], v[180:183], v[26:29]
	v_mfma_f32_16x16x32_bf16 v[18:21], v[156:159], v[188:191], v[18:21]
	v_mfma_f32_16x16x32_bf16 v[10:13], v[164:167], v[188:191], v[10:13]
	v_mfma_f32_16x16x32_bf16 v[6:9], v[156:159], v[212:215], v[6:9]
	v_mfma_f32_16x16x32_bf16 v[2:5], v[164:167], v[212:215], v[2:5]
	v_mfma_f32_16x16x32_bf16 v[50:53], v[160:163], v[176:179], v[50:53]
	v_mfma_f32_16x16x32_bf16 v[42:45], v[168:171], v[176:179], v[42:45]
	v_mfma_f32_16x16x32_bf16 v[34:37], v[160:163], v[184:187], v[34:37]
	v_mfma_f32_16x16x32_bf16 v[26:29], v[168:171], v[184:187], v[26:29]
	v_mfma_f32_16x16x32_bf16 v[18:21], v[160:163], v[192:195], v[18:21]
	v_mfma_f32_16x16x32_bf16 v[10:13], v[168:171], v[192:195], v[10:13]
	v_mfma_f32_16x16x32_bf16 v[6:9], v[160:163], v[216:219], v[6:9]
	v_mfma_f32_16x16x32_bf16 v[2:5], v[168:171], v[216:219], v[2:5]
	s_setprio 0
	s_barrier
	v_add_u32_e32 v143, s62, v141
	ds_read_b128 v[136:139], v143
	ds_read_b128 v[144:147], v143 offset:1024
	ds_read_b128 v[148:151], v143 offset:2048
	ds_read_b128 v[152:155], v143 offset:3072
	v_add_u32_e32 v143, s61, v141
	ds_read_b128 v[156:159], v143
	ds_read_b128 v[160:163], v143 offset:1024
	ds_read_b128 v[164:167], v143 offset:2048
	ds_read_b128 v[168:171], v143 offset:3072
	s_mov_b32 m0, s68
	v_lshl_add_u64 v[220:221], s[36:37], 0, v[130:131]
	ds_read_b128 v[172:175], v142 offset:32768
	ds_read_b128 v[176:179], v142 offset:33792
	ds_read_b128 v[180:183], v142 offset:34816
	ds_read_b128 v[184:187], v142 offset:35840
	ds_read_b128 v[188:191], v142 offset:36864
	ds_read_b128 v[192:195], v142 offset:37888
	ds_read_b128 v[212:215], v142 offset:38912
	ds_read_b128 v[216:219], v142 offset:39936
	global_load_lds_dwordx4 v[220:221], off
	v_lshl_add_u64 v[220:221], s[36:37], 0, v[132:133]
	s_mov_b32 m0, s79
	s_nop 0
	global_load_lds_dwordx4 v[220:221], off
	s_waitcnt vmcnt(8)
	s_waitcnt lgkmcnt(0)
	s_setprio 1
	s_barrier
	v_mfma_f32_16x16x32_bf16 v[126:129], v[136:139], v[172:175], v[126:129]
	v_mfma_f32_16x16x32_bf16 v[122:125], v[148:151], v[172:175], v[122:125]
	v_mfma_f32_16x16x32_bf16 v[118:121], v[136:139], v[180:183], v[118:121]
	v_mfma_f32_16x16x32_bf16 v[110:113], v[148:151], v[180:183], v[110:113]
	v_mfma_f32_16x16x32_bf16 v[102:105], v[136:139], v[188:191], v[102:105]
	v_mfma_f32_16x16x32_bf16 v[94:97], v[148:151], v[188:191], v[94:97]
	v_mfma_f32_16x16x32_bf16 v[86:89], v[136:139], v[212:215], v[86:89]
	v_mfma_f32_16x16x32_bf16 v[78:81], v[148:151], v[212:215], v[78:81]
	v_mfma_f32_16x16x32_bf16 v[126:129], v[144:147], v[176:179], v[126:129]
	v_mfma_f32_16x16x32_bf16 v[122:125], v[152:155], v[176:179], v[122:125]
	v_mfma_f32_16x16x32_bf16 v[118:121], v[144:147], v[184:187], v[118:121]
	v_mfma_f32_16x16x32_bf16 v[110:113], v[152:155], v[184:187], v[110:113]
	v_mfma_f32_16x16x32_bf16 v[102:105], v[144:147], v[192:195], v[102:105]
	v_mfma_f32_16x16x32_bf16 v[94:97], v[152:155], v[192:195], v[94:97]
	v_mfma_f32_16x16x32_bf16 v[86:89], v[144:147], v[216:219], v[86:89]
	v_mfma_f32_16x16x32_bf16 v[78:81], v[152:155], v[216:219], v[78:81]
	s_setprio 0
	s_setprio 1
	v_mfma_f32_16x16x32_bf16 v[114:117], v[156:159], v[172:175], v[114:117]
	v_mfma_f32_16x16x32_bf16 v[106:109], v[164:167], v[172:175], v[106:109]
	v_mfma_f32_16x16x32_bf16 v[98:101], v[156:159], v[180:183], v[98:101]
	v_mfma_f32_16x16x32_bf16 v[90:93], v[164:167], v[180:183], v[90:93]
	v_mfma_f32_16x16x32_bf16 v[82:85], v[156:159], v[188:191], v[82:85]
	v_mfma_f32_16x16x32_bf16 v[74:77], v[164:167], v[188:191], v[74:77]
	v_mfma_f32_16x16x32_bf16 v[70:73], v[156:159], v[212:215], v[70:73]
	v_mfma_f32_16x16x32_bf16 v[66:69], v[164:167], v[212:215], v[66:69]
	v_mfma_f32_16x16x32_bf16 v[114:117], v[160:163], v[176:179], v[114:117]
	v_mfma_f32_16x16x32_bf16 v[106:109], v[168:171], v[176:179], v[106:109]
	v_mfma_f32_16x16x32_bf16 v[98:101], v[160:163], v[184:187], v[98:101]
	v_mfma_f32_16x16x32_bf16 v[90:93], v[168:171], v[184:187], v[90:93]
	v_mfma_f32_16x16x32_bf16 v[82:85], v[160:163], v[192:195], v[82:85]
	v_mfma_f32_16x16x32_bf16 v[74:77], v[168:171], v[192:195], v[74:77]
	v_mfma_f32_16x16x32_bf16 v[70:73], v[160:163], v[216:219], v[70:73]
	v_mfma_f32_16x16x32_bf16 v[66:69], v[168:171], v[216:219], v[66:69]
	s_setprio 0
	s_barrier
; #define PG8_STAGE(bufoff, gbase, voff) do { _Pragma("unroll") for (int _i = 0; _i < 2; ++_i) \
;         __builtin_amdgcn_global_load_lds((const unsigned*)((const char*)(gbase) + (voff)[_i]), (PG8_LAS unsigned*)(lds + (bufoff) + ldsw + _i * 8192), 16, 0, 0); } while (0)
; #define PG8_LDA(dst, b, h) do { _Pragma("unroll") for (int m = 0; m < 4; ++m) _Pragma("unroll") for (int k = 0; k < 2; ++k) dst[m][k] = *(const PG8_LAS bf16x8*)(lds + PG8_SA(b, h) + aoff + m * 2048 + k * 1024); } while (0)
; #define PG8_MMA(ai, bj, At, Bt) do { __builtin_amdgcn_s_setprio(1); _Pragma("unroll") for (int m = 0; m < 4; ++m) _Pragma("unroll") for (int n = 0; n < 2; ++n) _Pragma("unroll") for (int k = 0; k < 2; ++k) \
;         acc[ai][bj][m][n] = __builtin_amdgcn_mfma_f32_16x16x32_bf16(Bt[n][k], At[m][k], acc[ai][bj][m][n], 0, 0, 0); __builtin_amdgcn_s_setprio(0); } while (0)
; #define PG8_WAIT_V(n) asm volatile("s_waitcnt vmcnt(" #n ")" ::: "memory")
; #define PG8_WAIT_L(n) asm volatile("s_waitcnt lgkmcnt(" #n ")" ::: "memory")
; #define PG8_BAR __builtin_amdgcn_s_barrier()
; #define PG8_SCHED __builtin_amdgcn_sched_barrier(0)
; template <class Epi, class Sched, bool ALIGN_EPI = false, bool SP2 = false>
; __device__ __forceinline__ void gemm_phase(PG8_LAS unsigned char* lds, const Gemm g, const Sched& S, const Epi& E, const int wid) {
;     ...
;             PG8_LDA(At, 1, 1); PG8_STAGE(PG8_SB(1, 0), b3, voffB); PG8_STAGE(PG8_SB(1, 1), b3 + hstep, voffB); PG8_STAGE(PG8_SA(1, 0), a3, voffA);
;             PG8_WAIT_V(8); PG8_WAIT_L(0); PG8_BAR; PG8_MMA(1, 0, At, B0); PG8_MMA(1, 1, At, B1); PG8_BAR; PG8_SCHED;
	s_mov_b32 m0, s60
	v_lshl_add_u64 v[200:201], v[200:201], 0, s[58:59]
	ds_read_b128 v[172:175], v142 offset:49152
	ds_read_b128 v[176:179], v142 offset:50176
	ds_read_b128 v[180:183], v142 offset:51200
	ds_read_b128 v[184:187], v142 offset:52224
	ds_read_b128 v[188:191], v142 offset:53248
	ds_read_b128 v[192:195], v142 offset:54272
	ds_read_b128 v[212:215], v142 offset:55296
	ds_read_b128 v[216:219], v142 offset:56320
	global_load_lds_dwordx4 v[200:201], off
	v_lshl_add_u64 v[200:201], v[202:203], 0, s[58:59]
	s_mov_b32 m0, s54
	s_nop 0
	global_load_lds_dwordx4 v[200:201], off
	v_lshl_add_u64 v[200:201], s[34:35], 0, v[0:1]
	s_mov_b32 m0, vcc_hi
	s_nop 0
	global_load_lds_dwordx4 v[200:201], off
	v_lshl_add_u64 v[200:201], s[34:35], 0, v[134:135]
	s_mov_b32 m0, vcc_lo
	s_nop 0
	global_load_lds_dwordx4 v[200:201], off
	v_lshl_add_u64 v[200:201], v[208:209], 0, s[58:59]
	s_mov_b32 m0, s86
	s_nop 0
	global_load_lds_dwordx4 v[200:201], off
	v_lshl_add_u64 v[200:201], v[210:211], 0, s[58:59]
	s_mov_b32 m0, s87
	s_nop 0
	global_load_lds_dwordx4 v[200:201], off
	s_waitcnt vmcnt(8)
	s_waitcnt lgkmcnt(0)
	s_setprio 1
	s_barrier
	v_mfma_f32_16x16x32_bf16 v[62:65], v[136:139], v[172:175], v[62:65]
	v_mfma_f32_16x16x32_bf16 v[58:61], v[148:151], v[172:175], v[58:61]
	v_mfma_f32_16x16x32_bf16 v[54:57], v[136:139], v[180:183], v[54:57]
	v_mfma_f32_16x16x32_bf16 v[46:49], v[148:151], v[180:183], v[46:49]
	v_mfma_f32_16x16x32_bf16 v[38:41], v[136:139], v[188:191], v[38:41]
	v_mfma_f32_16x16x32_bf16 v[30:33], v[148:151], v[188:191], v[30:33]
	v_mfma_f32_16x16x32_bf16 v[22:25], v[136:139], v[212:215], v[22:25]
	v_mfma_f32_16x16x32_bf16 v[14:17], v[148:151], v[212:215], v[14:17]
	v_mfma_f32_16x16x32_bf16 v[62:65], v[144:147], v[176:179], v[62:65]
	v_mfma_f32_16x16x32_bf16 v[58:61], v[152:155], v[176:179], v[58:61]
	v_mfma_f32_16x16x32_bf16 v[54:57], v[144:147], v[184:187], v[54:57]
	v_mfma_f32_16x16x32_bf16 v[46:49], v[152:155], v[184:187], v[46:49]
	v_mfma_f32_16x16x32_bf16 v[38:41], v[144:147], v[192:195], v[38:41]
	v_mfma_f32_16x16x32_bf16 v[30:33], v[152:155], v[192:195], v[30:33]
	v_mfma_f32_16x16x32_bf16 v[22:25], v[144:147], v[216:219], v[22:25]
	v_mfma_f32_16x16x32_bf16 v[14:17], v[152:155], v[216:219], v[14:17]
	s_setprio 0
	s_setprio 1
	v_mfma_f32_16x16x32_bf16 v[50:53], v[156:159], v[172:175], v[50:53]
	v_mfma_f32_16x16x32_bf16 v[42:45], v[164:167], v[172:175], v[42:45]
	v_mfma_f32_16x16x32_bf16 v[34:37], v[156:159], v[180:183], v[34:37]
	v_mfma_f32_16x16x32_bf16 v[26:29], v[164:167], v[180:183], v[26:29]
	v_mfma_f32_16x16x32_bf16 v[18:21], v[156:159], v[188:191], v[18:21]
	v_mfma_f32_16x16x32_bf16 v[10:13], v[164:167], v[188:191], v[10:13]
	v_mfma_f32_16x16x32_bf16 v[6:9], v[156:159], v[212:215], v[6:9]
	v_mfma_f32_16x16x32_bf16 v[2:5], v[164:167], v[212:215], v[2:5]
	v_mfma_f32_16x16x32_bf16 v[50:53], v[160:163], v[176:179], v[50:53]
	v_mfma_f32_16x16x32_bf16 v[42:45], v[168:171], v[176:179], v[42:45]
	v_mfma_f32_16x16x32_bf16 v[34:37], v[160:163], v[184:187], v[34:37]
	v_mfma_f32_16x16x32_bf16 v[26:29], v[168:171], v[184:187], v[26:29]
	v_mfma_f32_16x16x32_bf16 v[18:21], v[160:163], v[192:195], v[18:21]
	v_mfma_f32_16x16x32_bf16 v[10:13], v[168:171], v[192:195], v[10:13]
	v_mfma_f32_16x16x32_bf16 v[6:9], v[160:163], v[216:219], v[6:9]
	v_mfma_f32_16x16x32_bf16 v[2:5], v[168:171], v[216:219], v[2:5]
	s_setprio 0
	s_barrier
	s_movk_i32 s36, 0x100
	s_andn2_b64 vcc, exec, s[30:31]
	s_mov_b64 s[34:35], -1
	s_mov_b64 s[30:31], 0
	s_cbranch_vccz .LBB0_188
	s_and_b64 vcc, exec, s[14:15]
	v_readlane_b32 s93, v255, 22
	s_cbranch_vccz .LBB0_191
	s_barrier

; #define PG8_STAGE(bufoff, gbase, voff) do { _Pragma("unroll") for (int _i = 0; _i < 2; ++_i) \
;         __builtin_amdgcn_global_load_lds((const unsigned*)((const char*)(gbase) + (voff)[_i]), (PG8_LAS unsigned*)(lds + (bufoff) + ldsw + _i * 8192), 16, 0, 0); } while (0)
; #define PG8_LDA(dst, b, h) do { _Pragma("unroll") for (int m = 0; m < 4; ++m) _Pragma("unroll") for (int k = 0; k < 2; ++k) dst[m][k] = *(const PG8_LAS bf16x8*)(lds + PG8_SA(b, h) + aoff + m * 2048 + k * 1024); } while (0)
; #define PG8_LDB(dst, b, h) do { _Pragma("unroll") for (int n = 0; n < 2; ++n) _Pragma("unroll") for (int k = 0; k < 2; ++k) dst[n][k] = *(const PG8_LAS bf16x8*)(lds + PG8_SB(b, h) + boff + n * 2048 + k * 1024); } while (0)
; #define PG8_MMA(ai, bj, At, Bt) do { __builtin_amdgcn_s_setprio(1); _Pragma("unroll") for (int m = 0; m < 4; ++m) _Pragma("unroll") for (int n = 0; n < 2; ++n) _Pragma("unroll") for (int k = 0; k < 2; ++k) \
;         acc[ai][bj][m][n] = __builtin_amdgcn_mfma_f32_16x16x32_bf16(Bt[n][k], At[m][k], acc[ai][bj][m][n], 0, 0, 0); __builtin_amdgcn_s_setprio(0); } while (0)
; #define PG8_WAIT_V(n) asm volatile("s_waitcnt vmcnt(" #n ")" ::: "memory")
; #define PG8_BAR __builtin_amdgcn_s_barrier()
; template <class Epi, class Sched, bool ALIGN_EPI = false, bool SP2 = false>
; __device__ __forceinline__ void gemm_phase(PG8_LAS unsigned char* lds, const Gemm g, const Sched& S, const Epi& E, const int wid) {
;     ...
;         for (int t = 0; t < nt; t += 2) {
;             const bool last = (t == nt - 2);
;             const char* a1 = cA + (size_t)(t + 1) * kstep;
;             const char* a2 = last ? nA : cA + (size_t)(t + 2) * kstep; const char* b2 = last ? nB : cB + (size_t)(t + 2) * kstep;
;             const char* a3 = a2 + kstep; const char* b3 = b2 + kstep;
;             if (last && has_next) S.a_ready(nxt);
;             if constexpr (SP2) {
;             PG8_LDB(B0, 0, 0); PG8_LDB(B1, 0, 1); PG8_SCHED; PG8_LDA(At, 0, 0); PG8_STAGE(PG8_SA(1, 1), a1 + hstep, voffA);
;             PG8_WAIT_V(8); PG8_WAIT_L(0); PG8_BAR; PG8_MMA(0, 0, At, B0); PG8_MMA(0, 1, At, B1); PG8_BAR; PG8_SCHED;
;             PG8_LDA(At, 0, 1); PG8_STAGE(PG8_SB(0, 0), b2, voffB); PG8_STAGE(PG8_SB(0, 1), b2 + hstep, voffB); PG8_STAGE(PG8_SA(0, 0), a2, voffA);
;             PG8_WAIT_V(8); PG8_WAIT_L(0); PG8_BAR; PG8_MMA(1, 0, At, B0); PG8_MMA(1, 1, At, B1); PG8_BAR; PG8_SCHED;
.LBB0_214:
	s_add_u32 s40, s38, 0xfff80080
	s_addc_u32 s41, s39, -1
	s_add_i32 s47, 0, 0x10000
	s_cmp_eq_u32 s46, 28
	s_cselect_b32 s43, s3, s41
	s_cselect_b32 s42, s23, s40
	s_waitcnt lgkmcnt(0)
	v_add_u32_e32 v0, s47, v171
	s_cselect_b32 s41, s25, s37
	s_cselect_b32 s40, s27, s35
	s_add_i32 s52, 0, 0x14000
	ds_read_b128 v[130:133], v0
	ds_read_b128 v[134:137], v0 offset:1024
	ds_read_b128 v[138:141], v0 offset:2048
	ds_read_b128 v[142:145], v0 offset:3072
	v_add_u32_e32 v0, s52, v171
	ds_read_b128 v[158:161], v0
	ds_read_b128 v[162:165], v0 offset:1024
	ds_read_b128 v[166:169], v0 offset:2048
	ds_read_b128 v[174:177], v0 offset:3072
	v_lshl_add_u64 v[194:195], s[38:39], 0, v[154:155]
	s_add_i32 m0, s68, 0xc000
	ds_read_b128 v[178:181], v172
	ds_read_b128 v[182:185], v172 offset:1024
	ds_read_b128 v[186:189], v172 offset:2048
	ds_read_b128 v[190:193], v172 offset:3072
	ds_read_b128 v[212:215], v172 offset:4096
	ds_read_b128 v[216:219], v172 offset:5120
	ds_read_b128 v[220:223], v172 offset:6144
	ds_read_b128 v[224:227], v172 offset:7168
	global_load_lds_dwordx4 v[194:195], off
	v_lshl_add_u64 v[194:195], s[38:39], 0, v[156:157]
	s_add_i32 m0, s68, 0xe000
	s_nop 0
	global_load_lds_dwordx4 v[194:195], off
	s_waitcnt vmcnt(8)
	s_waitcnt lgkmcnt(0)
	s_setprio 1
	s_barrier
	v_mfma_f32_16x16x32_bf16 v[126:129], v[130:133], v[178:181], v[126:129]
	v_mfma_f32_16x16x32_bf16 v[122:125], v[138:141], v[178:181], v[122:125]
	v_mfma_f32_16x16x32_bf16 v[110:113], v[130:133], v[186:189], v[110:113]
	v_mfma_f32_16x16x32_bf16 v[106:109], v[138:141], v[186:189], v[106:109]
	v_mfma_f32_16x16x32_bf16 v[94:97], v[130:133], v[212:215], v[94:97]
	v_mfma_f32_16x16x32_bf16 v[90:93], v[138:141], v[212:215], v[90:93]
	v_mfma_f32_16x16x32_bf16 v[78:81], v[130:133], v[220:223], v[78:81]
	v_mfma_f32_16x16x32_bf16 v[74:77], v[138:141], v[220:223], v[74:77]
	v_mfma_f32_16x16x32_bf16 v[126:129], v[134:137], v[182:185], v[126:129]
	v_mfma_f32_16x16x32_bf16 v[122:125], v[142:145], v[182:185], v[122:125]
	v_mfma_f32_16x16x32_bf16 v[110:113], v[134:137], v[190:193], v[110:113]
	v_mfma_f32_16x16x32_bf16 v[106:109], v[142:145], v[190:193], v[106:109]
	v_mfma_f32_16x16x32_bf16 v[94:97], v[134:137], v[216:219], v[94:97]
	v_mfma_f32_16x16x32_bf16 v[90:93], v[142:145], v[216:219], v[90:93]
	v_mfma_f32_16x16x32_bf16 v[78:81], v[134:137], v[224:227], v[78:81]
	v_mfma_f32_16x16x32_bf16 v[74:77], v[142:145], v[224:227], v[74:77]
	s_setprio 0
	s_setprio 1
	v_mfma_f32_16x16x32_bf16 v[118:121], v[158:161], v[178:181], v[118:121]
	v_mfma_f32_16x16x32_bf16 v[114:117], v[166:169], v[178:181], v[114:117]
	v_mfma_f32_16x16x32_bf16 v[102:105], v[158:161], v[186:189], v[102:105]
	v_mfma_f32_16x16x32_bf16 v[98:101], v[166:169], v[186:189], v[98:101]
	v_mfma_f32_16x16x32_bf16 v[86:89], v[158:161], v[212:215], v[86:89]
	v_mfma_f32_16x16x32_bf16 v[82:85], v[166:169], v[212:215], v[82:85]
	v_mfma_f32_16x16x32_bf16 v[70:73], v[158:161], v[220:223], v[70:73]
	v_mfma_f32_16x16x32_bf16 v[66:69], v[166:169], v[220:223], v[66:69]
	v_mfma_f32_16x16x32_bf16 v[118:121], v[162:165], v[182:185], v[118:121]
	v_mfma_f32_16x16x32_bf16 v[114:117], v[174:177], v[182:185], v[114:117]
	v_mfma_f32_16x16x32_bf16 v[102:105], v[162:165], v[190:193], v[102:105]
	v_mfma_f32_16x16x32_bf16 v[98:101], v[174:177], v[190:193], v[98:101]
	v_mfma_f32_16x16x32_bf16 v[86:89], v[162:165], v[216:219], v[86:89]
	v_mfma_f32_16x16x32_bf16 v[82:85], v[174:177], v[216:219], v[82:85]
	v_mfma_f32_16x16x32_bf16 v[70:73], v[162:165], v[224:227], v[70:73]
	v_mfma_f32_16x16x32_bf16 v[66:69], v[174:177], v[224:227], v[66:69]
	s_setprio 0
	s_barrier
	s_add_i32 s47, s47, s85
	v_lshl_add_u64 v[194:195], s[40:41], 0, v[148:149]
	s_mov_b32 m0, s47
	ds_read_b128 v[178:181], v172 offset:16384
	ds_read_b128 v[182:185], v172 offset:17408
	ds_read_b128 v[186:189], v172 offset:18432
	ds_read_b128 v[190:193], v172 offset:19456
	ds_read_b128 v[212:215], v172 offset:20480
	ds_read_b128 v[216:219], v172 offset:21504
	ds_read_b128 v[220:223], v172 offset:22528
	ds_read_b128 v[224:227], v172 offset:23552
	global_load_lds_dwordx4 v[194:195], off
	s_add_i32 m0, s47, 0x2000
	s_add_u32 s60, s40, 0x80000
	v_lshl_add_u64 v[200:201], s[40:41], 0, v[152:153]
	s_addc_u32 s61, s41, 0
	s_add_i32 s47, s52, s85
	global_load_lds_dwordx4 v[200:201], off
	v_lshl_add_u64 v[202:203], s[60:61], 0, v[148:149]
	s_mov_b32 m0, s47
	v_lshl_add_u64 v[208:209], s[42:43], 0, v[150:151]
	global_load_lds_dwordx4 v[202:203], off
	v_lshl_add_u64 v[202:203], s[60:61], 0, v[152:153]
	s_add_i32 m0, s47, 0x2000
	s_nop 0
	global_load_lds_dwordx4 v[202:203], off
	v_lshl_add_u64 v[202:203], s[42:43], 0, v[146:147]
	s_mov_b32 m0, s68
	s_nop 0
	global_load_lds_dwordx4 v[202:203], off
	s_mov_b32 m0, s92
	s_nop 0
	global_load_lds_dwordx4 v[208:209], off
	s_waitcnt vmcnt(8)
	s_waitcnt lgkmcnt(0)
	s_setprio 1
	s_barrier
; #define PG8_STAGE(bufoff, gbase, voff) do { _Pragma("unroll") for (int _i = 0; _i < 2; ++_i) \
;         __builtin_amdgcn_global_load_lds((const unsigned*)((const char*)(gbase) + (voff)[_i]), (PG8_LAS unsigned*)(lds + (bufoff) + ldsw + _i * 8192), 16, 0, 0); } while (0)
; #define PG8_LDA(dst, b, h) do { _Pragma("unroll") for (int m = 0; m < 4; ++m) _Pragma("unroll") for (int k = 0; k < 2; ++k) dst[m][k] = *(const PG8_LAS bf16x8*)(lds + PG8_SA(b, h) + aoff + m * 2048 + k * 1024); } while (0)
; #define PG8_LDB(dst, b, h) do { _Pragma("unroll") for (int n = 0; n < 2; ++n) _Pragma("unroll") for (int k = 0; k < 2; ++k) dst[n][k] = *(const PG8_LAS bf16x8*)(lds + PG8_SB(b, h) + boff + n * 2048 + k * 1024); } while (0)
; #define PG8_MMA(ai, bj, At, Bt) do { __builtin_amdgcn_s_setprio(1); _Pragma("unroll") for (int m = 0; m < 4; ++m) _Pragma("unroll") for (int n = 0; n < 2; ++n) _Pragma("unroll") for (int k = 0; k < 2; ++k) \
;         acc[ai][bj][m][n] = __builtin_amdgcn_mfma_f32_16x16x32_bf16(Bt[n][k], At[m][k], acc[ai][bj][m][n], 0, 0, 0); __builtin_amdgcn_s_setprio(0); } while (0)
; #define PG8_WAIT_V(n) asm volatile("s_waitcnt vmcnt(" #n ")" ::: "memory")
; #define PG8_WAIT_L(n) asm volatile("s_waitcnt lgkmcnt(" #n ")" ::: "memory")
; #define PG8_BAR __builtin_amdgcn_s_barrier()
; #define PG8_SCHED __builtin_amdgcn_sched_barrier(0)
; template <class Epi, class Sched, bool ALIGN_EPI = false, bool SP2 = false>
; __device__ __forceinline__ void gemm_phase(PG8_LAS unsigned char* lds, const Gemm g, const Sched& S, const Epi& E, const int wid) {
;     ...
;             PG8_WAIT_V(8); PG8_WAIT_L(0); PG8_BAR; PG8_MMA(1, 0, At, B0); PG8_MMA(1, 1, At, B1); PG8_BAR; PG8_SCHED;
;             PG8_LDB(B0, 1, 0); PG8_LDB(B1, 1, 1); PG8_SCHED; PG8_LDA(At, 1, 0); PG8_STAGE(PG8_SA(0, 1), a2 + hstep, voffA);
;             PG8_WAIT_V(8); PG8_WAIT_L(0); PG8_BAR; PG8_MMA(0, 0, At, B0); PG8_MMA(0, 1, At, B1); PG8_BAR; PG8_SCHED;
	v_mfma_f32_16x16x32_bf16 v[62:65], v[130:133], v[178:181], v[62:65]
	v_mfma_f32_16x16x32_bf16 v[58:61], v[138:141], v[178:181], v[58:61]
	v_mfma_f32_16x16x32_bf16 v[46:49], v[130:133], v[186:189], v[46:49]
	v_mfma_f32_16x16x32_bf16 v[42:45], v[138:141], v[186:189], v[42:45]
	v_mfma_f32_16x16x32_bf16 v[30:33], v[130:133], v[212:215], v[30:33]
	v_mfma_f32_16x16x32_bf16 v[26:29], v[138:141], v[212:215], v[26:29]
	v_mfma_f32_16x16x32_bf16 v[14:17], v[130:133], v[220:223], v[14:17]
	v_mfma_f32_16x16x32_bf16 v[10:13], v[138:141], v[220:223], v[10:13]
	v_mfma_f32_16x16x32_bf16 v[62:65], v[134:137], v[182:185], v[62:65]
	v_mfma_f32_16x16x32_bf16 v[58:61], v[142:145], v[182:185], v[58:61]
	v_mfma_f32_16x16x32_bf16 v[46:49], v[134:137], v[190:193], v[46:49]
	v_mfma_f32_16x16x32_bf16 v[42:45], v[142:145], v[190:193], v[42:45]
	v_mfma_f32_16x16x32_bf16 v[30:33], v[134:137], v[216:219], v[30:33]
	v_mfma_f32_16x16x32_bf16 v[26:29], v[142:145], v[216:219], v[26:29]
	v_mfma_f32_16x16x32_bf16 v[14:17], v[134:137], v[224:227], v[14:17]
	v_mfma_f32_16x16x32_bf16 v[10:13], v[142:145], v[224:227], v[10:13]
	s_setprio 0
	s_setprio 1
	v_mfma_f32_16x16x32_bf16 v[54:57], v[158:161], v[178:181], v[54:57]
	v_mfma_f32_16x16x32_bf16 v[50:53], v[166:169], v[178:181], v[50:53]
	v_mfma_f32_16x16x32_bf16 v[38:41], v[158:161], v[186:189], v[38:41]
	v_mfma_f32_16x16x32_bf16 v[34:37], v[166:169], v[186:189], v[34:37]
	v_mfma_f32_16x16x32_bf16 v[22:25], v[158:161], v[212:215], v[22:25]
	v_mfma_f32_16x16x32_bf16 v[18:21], v[166:169], v[212:215], v[18:21]
	v_mfma_f32_16x16x32_bf16 v[6:9], v[158:161], v[220:223], v[6:9]
	v_mfma_f32_16x16x32_bf16 v[2:5], v[166:169], v[220:223], v[2:5]
	v_mfma_f32_16x16x32_bf16 v[54:57], v[162:165], v[182:185], v[54:57]
	v_mfma_f32_16x16x32_bf16 v[50:53], v[174:177], v[182:185], v[50:53]
	v_mfma_f32_16x16x32_bf16 v[38:41], v[162:165], v[190:193], v[38:41]
	v_mfma_f32_16x16x32_bf16 v[34:37], v[174:177], v[190:193], v[34:37]
	v_mfma_f32_16x16x32_bf16 v[22:25], v[162:165], v[216:219], v[22:25]
	v_mfma_f32_16x16x32_bf16 v[18:21], v[174:177], v[216:219], v[18:21]
	v_mfma_f32_16x16x32_bf16 v[6:9], v[162:165], v[224:227], v[6:9]
	v_mfma_f32_16x16x32_bf16 v[2:5], v[174:177], v[224:227], v[2:5]
	s_setprio 0
	s_barrier
	s_add_i32 s47, 0, 0x18000
	v_add_u32_e32 v0, s47, v171
	s_add_i32 s52, 0, 0x1c000
	ds_read_b128 v[130:133], v0
	ds_read_b128 v[134:137], v0 offset:1024
	ds_read_b128 v[138:141], v0 offset:2048
	ds_read_b128 v[142:145], v0 offset:3072
	v_add_u32_e32 v0, s52, v171
	ds_read_b128 v[158:161], v0
	ds_read_b128 v[162:165], v0 offset:1024
	ds_read_b128 v[166:169], v0 offset:2048
	ds_read_b128 v[174:177], v0 offset:3072
	s_add_u32 s42, s42, 0x80000
	s_addc_u32 s43, s43, 0
	s_mov_b32 m0, s93
	v_lshl_add_u64 v[210:211], s[42:43], 0, v[146:147]
	ds_read_b128 v[178:181], v172 offset:32768
	ds_read_b128 v[182:185], v172 offset:33792
	ds_read_b128 v[186:189], v172 offset:34816
	ds_read_b128 v[190:193], v172 offset:35840
	ds_read_b128 v[212:215], v172 offset:36864
	ds_read_b128 v[216:219], v172 offset:37888
	ds_read_b128 v[220:223], v172 offset:38912
	ds_read_b128 v[224:227], v172 offset:39936
	global_load_lds_dwordx4 v[210:211], off
	v_lshl_add_u64 v[210:211], s[42:43], 0, v[150:151]
	s_mov_b32 m0, s94
	s_nop 0
	global_load_lds_dwordx4 v[210:211], off
	s_waitcnt vmcnt(8)
	s_waitcnt lgkmcnt(0)
	s_setprio 1
	s_barrier
	v_mfma_f32_16x16x32_bf16 v[126:129], v[130:133], v[178:181], v[126:129]
	v_mfma_f32_16x16x32_bf16 v[122:125], v[138:141], v[178:181], v[122:125]
	v_mfma_f32_16x16x32_bf16 v[110:113], v[130:133], v[186:189], v[110:113]
	v_mfma_f32_16x16x32_bf16 v[106:109], v[138:141], v[186:189], v[106:109]
	v_mfma_f32_16x16x32_bf16 v[94:97], v[130:133], v[212:215], v[94:97]
	v_mfma_f32_16x16x32_bf16 v[90:93], v[138:141], v[212:215], v[90:93]
	v_mfma_f32_16x16x32_bf16 v[78:81], v[130:133], v[220:223], v[78:81]
	v_mfma_f32_16x16x32_bf16 v[74:77], v[138:141], v[220:223], v[74:77]
	v_mfma_f32_16x16x32_bf16 v[126:129], v[134:137], v[182:185], v[126:129]
	v_mfma_f32_16x16x32_bf16 v[122:125], v[142:145], v[182:185], v[122:125]
	v_mfma_f32_16x16x32_bf16 v[110:113], v[134:137], v[190:193], v[110:113]
	v_mfma_f32_16x16x32_bf16 v[106:109], v[142:145], v[190:193], v[106:109]
	v_mfma_f32_16x16x32_bf16 v[94:97], v[134:137], v[216:219], v[94:97]
	v_mfma_f32_16x16x32_bf16 v[90:93], v[142:145], v[216:219], v[90:93]
	v_mfma_f32_16x16x32_bf16 v[78:81], v[134:137], v[224:227], v[78:81]
	v_mfma_f32_16x16x32_bf16 v[74:77], v[142:145], v[224:227], v[74:77]
	s_setprio 0
	s_setprio 1
	v_mfma_f32_16x16x32_bf16 v[118:121], v[158:161], v[178:181], v[118:121]
	v_mfma_f32_16x16x32_bf16 v[114:117], v[166:169], v[178:181], v[114:117]
	v_mfma_f32_16x16x32_bf16 v[102:105], v[158:161], v[186:189], v[102:105]
	v_mfma_f32_16x16x32_bf16 v[98:101], v[166:169], v[186:189], v[98:101]
	v_mfma_f32_16x16x32_bf16 v[86:89], v[158:161], v[212:215], v[86:89]
	v_mfma_f32_16x16x32_bf16 v[82:85], v[166:169], v[212:215], v[82:85]
	v_mfma_f32_16x16x32_bf16 v[70:73], v[158:161], v[220:223], v[70:73]
	v_mfma_f32_16x16x32_bf16 v[66:69], v[166:169], v[220:223], v[66:69]
	v_mfma_f32_16x16x32_bf16 v[118:121], v[162:165], v[182:185], v[118:121]
	v_mfma_f32_16x16x32_bf16 v[114:117], v[174:177], v[182:185], v[114:117]
	v_mfma_f32_16x16x32_bf16 v[102:105], v[162:165], v[190:193], v[102:105]
	v_mfma_f32_16x16x32_bf16 v[98:101], v[174:177], v[190:193], v[98:101]
	v_mfma_f32_16x16x32_bf16 v[86:89], v[162:165], v[216:219], v[86:89]
	v_mfma_f32_16x16x32_bf16 v[82:85], v[174:177], v[216:219], v[82:85]
	v_mfma_f32_16x16x32_bf16 v[70:73], v[162:165], v[224:227], v[70:73]
	v_mfma_f32_16x16x32_bf16 v[66:69], v[174:177], v[224:227], v[66:69]
	s_setprio 0
	s_barrier
; #define PG8_STAGE(bufoff, gbase, voff) do { _Pragma("unroll") for (int _i = 0; _i < 2; ++_i) \
;         __builtin_amdgcn_global_load_lds((const unsigned*)((const char*)(gbase) + (voff)[_i]), (PG8_LAS unsigned*)(lds + (bufoff) + ldsw + _i * 8192), 16, 0, 0); } while (0)
; #define PG8_LDA(dst, b, h) do { _Pragma("unroll") for (int m = 0; m < 4; ++m) _Pragma("unroll") for (int k = 0; k < 2; ++k) dst[m][k] = *(const PG8_LAS bf16x8*)(lds + PG8_SA(b, h) + aoff + m * 2048 + k * 1024); } while (0)
; #define PG8_MMA(ai, bj, At, Bt) do { __builtin_amdgcn_s_setprio(1); _Pragma("unroll") for (int m = 0; m < 4; ++m) _Pragma("unroll") for (int n = 0; n < 2; ++n) _Pragma("unroll") for (int k = 0; k < 2; ++k) \
;         acc[ai][bj][m][n] = __builtin_amdgcn_mfma_f32_16x16x32_bf16(Bt[n][k], At[m][k], acc[ai][bj][m][n], 0, 0, 0); __builtin_amdgcn_s_setprio(0); } while (0)
; #define PG8_WAIT_V(n) asm volatile("s_waitcnt vmcnt(" #n ")" ::: "memory")
; #define PG8_WAIT_L(n) asm volatile("s_waitcnt lgkmcnt(" #n ")" ::: "memory")
; #define PG8_BAR __builtin_amdgcn_s_barrier()
; #define PG8_SCHED __builtin_amdgcn_sched_barrier(0)
; template <class Epi, class Sched, bool ALIGN_EPI = false, bool SP2 = false>
; __device__ __forceinline__ void gemm_phase(PG8_LAS unsigned char* lds, const Gemm g, const Sched& S, const Epi& E, const int wid) {
;     ...
;         for (int t = 0; t < nt; t += 2) {
;     ...
;             PG8_LDA(At, 1, 1); PG8_STAGE(PG8_SB(1, 0), b3, voffB); PG8_STAGE(PG8_SB(1, 1), b3 + hstep, voffB); PG8_STAGE(PG8_SA(1, 0), a3, voffA);
;             PG8_WAIT_V(8); PG8_WAIT_L(0); PG8_BAR; PG8_MMA(1, 0, At, B0); PG8_MMA(1, 1, At, B1); PG8_BAR; PG8_SCHED;
	s_add_i32 s42, s47, s85
	v_lshl_add_u64 v[194:195], v[194:195], 0, s[58:59]
	s_mov_b32 m0, s42
	ds_read_b128 v[178:181], v172 offset:49152
	ds_read_b128 v[182:185], v172 offset:50176
	ds_read_b128 v[186:189], v172 offset:51200
	ds_read_b128 v[190:193], v172 offset:52224
	ds_read_b128 v[212:215], v172 offset:53248
	ds_read_b128 v[216:219], v172 offset:54272
	ds_read_b128 v[220:223], v172 offset:55296
	ds_read_b128 v[224:227], v172 offset:56320
	global_load_lds_dwordx4 v[194:195], off
	s_add_i32 m0, s42, 0x2000
	s_add_u32 s40, s40, 0x80080
	v_lshl_add_u64 v[194:195], v[200:201], 0, s[58:59]
	s_addc_u32 s41, s41, 0
	s_add_i32 s42, s52, s85
	global_load_lds_dwordx4 v[194:195], off
	v_lshl_add_u64 v[194:195], s[40:41], 0, v[148:149]
	s_mov_b32 m0, s42
	s_nop 0
	global_load_lds_dwordx4 v[194:195], off
	v_lshl_add_u64 v[194:195], s[40:41], 0, v[152:153]
	s_add_i32 m0, s42, 0x2000
	s_nop 0
	global_load_lds_dwordx4 v[194:195], off
	v_lshl_add_u64 v[194:195], v[202:203], 0, s[58:59]
	s_mov_b32 m0, s95
	s_nop 0
	global_load_lds_dwordx4 v[194:195], off
	v_lshl_add_u64 v[194:195], v[208:209], 0, s[58:59]
	s_mov_b32 m0, s96
	s_nop 0
	global_load_lds_dwordx4 v[194:195], off
	s_waitcnt vmcnt(8)
	s_waitcnt lgkmcnt(0)
	s_setprio 1
	s_barrier
	v_mfma_f32_16x16x32_bf16 v[62:65], v[130:133], v[178:181], v[62:65]
	v_mfma_f32_16x16x32_bf16 v[58:61], v[138:141], v[178:181], v[58:61]
	v_mfma_f32_16x16x32_bf16 v[46:49], v[130:133], v[186:189], v[46:49]
	v_mfma_f32_16x16x32_bf16 v[42:45], v[138:141], v[186:189], v[42:45]
	v_mfma_f32_16x16x32_bf16 v[30:33], v[130:133], v[212:215], v[30:33]
	v_mfma_f32_16x16x32_bf16 v[26:29], v[138:141], v[212:215], v[26:29]
	v_mfma_f32_16x16x32_bf16 v[14:17], v[130:133], v[220:223], v[14:17]
	v_mfma_f32_16x16x32_bf16 v[10:13], v[138:141], v[220:223], v[10:13]
	v_mfma_f32_16x16x32_bf16 v[62:65], v[134:137], v[182:185], v[62:65]
	v_mfma_f32_16x16x32_bf16 v[58:61], v[142:145], v[182:185], v[58:61]
	v_mfma_f32_16x16x32_bf16 v[46:49], v[134:137], v[190:193], v[46:49]
	v_mfma_f32_16x16x32_bf16 v[42:45], v[142:145], v[190:193], v[42:45]
	v_mfma_f32_16x16x32_bf16 v[30:33], v[134:137], v[216:219], v[30:33]
	v_mfma_f32_16x16x32_bf16 v[26:29], v[142:145], v[216:219], v[26:29]
	v_mfma_f32_16x16x32_bf16 v[14:17], v[134:137], v[224:227], v[14:17]
	v_mfma_f32_16x16x32_bf16 v[10:13], v[142:145], v[224:227], v[10:13]
	s_setprio 0
	s_setprio 1
	v_mfma_f32_16x16x32_bf16 v[54:57], v[158:161], v[178:181], v[54:57]
	v_mfma_f32_16x16x32_bf16 v[50:53], v[166:169], v[178:181], v[50:53]
	v_mfma_f32_16x16x32_bf16 v[38:41], v[158:161], v[186:189], v[38:41]
	v_mfma_f32_16x16x32_bf16 v[34:37], v[166:169], v[186:189], v[34:37]
	v_mfma_f32_16x16x32_bf16 v[22:25], v[158:161], v[212:215], v[22:25]
	v_mfma_f32_16x16x32_bf16 v[18:21], v[166:169], v[212:215], v[18:21]
	v_mfma_f32_16x16x32_bf16 v[6:9], v[158:161], v[220:223], v[6:9]
	v_mfma_f32_16x16x32_bf16 v[2:5], v[166:169], v[220:223], v[2:5]
	v_mfma_f32_16x16x32_bf16 v[54:57], v[162:165], v[182:185], v[54:57]
	v_mfma_f32_16x16x32_bf16 v[50:53], v[174:177], v[182:185], v[50:53]
	v_mfma_f32_16x16x32_bf16 v[38:41], v[162:165], v[190:193], v[38:41]
	v_mfma_f32_16x16x32_bf16 v[34:37], v[174:177], v[190:193], v[34:37]
	v_mfma_f32_16x16x32_bf16 v[22:25], v[162:165], v[216:219], v[22:25]
	v_mfma_f32_16x16x32_bf16 v[18:21], v[174:177], v[216:219], v[18:21]
	v_mfma_f32_16x16x32_bf16 v[6:9], v[162:165], v[224:227], v[6:9]
	v_mfma_f32_16x16x32_bf16 v[2:5], v[174:177], v[224:227], v[2:5]
	s_setprio 0
	s_barrier
	s_add_i32 s46, s46, 2
	s_add_u32 s38, s38, 0x100
	s_addc_u32 s39, s39, 0
	s_add_u32 s35, s35, 0x100
	s_addc_u32 s37, s37, 0
	s_cmp_gt_u32 s46, 29
	s_cbranch_scc0 .LBB0_214
	s_and_b64 vcc, exec, s[20:21]
	s_cbranch_vccz .LBB0_217
	s_barrier

; #define PG8_STAGE(bufoff, gbase, voff) do { _Pragma("unroll") for (int _i = 0; _i < 2; ++_i) \
;         __builtin_amdgcn_global_load_lds((const unsigned*)((const char*)(gbase) + (voff)[_i]), (PG8_LAS unsigned*)(lds + (bufoff) + ldsw + _i * 8192), 16, 0, 0); } while (0)
; #define PG8_LDA(dst, b, h) do { _Pragma("unroll") for (int m = 0; m < 4; ++m) _Pragma("unroll") for (int k = 0; k < 2; ++k) dst[m][k] = *(const PG8_LAS bf16x8*)(lds + PG8_SA(b, h) + aoff + m * 2048 + k * 1024); } while (0)
; #define PG8_LDB(dst, b, h) do { _Pragma("unroll") for (int n = 0; n < 2; ++n) _Pragma("unroll") for (int k = 0; k < 2; ++k) dst[n][k] = *(const PG8_LAS bf16x8*)(lds + PG8_SB(b, h) + boff + n * 2048 + k * 1024); } while (0)
; #define PG8_MMA(ai, bj, At, Bt) do { __builtin_amdgcn_s_setprio(1); _Pragma("unroll") for (int m = 0; m < 4; ++m) _Pragma("unroll") for (int n = 0; n < 2; ++n) _Pragma("unroll") for (int k = 0; k < 2; ++k) \
;         acc[ai][bj][m][n] = __builtin_amdgcn_mfma_f32_16x16x32_bf16(Bt[n][k], At[m][k], acc[ai][bj][m][n], 0, 0, 0); __builtin_amdgcn_s_setprio(0); } while (0)
; #define PG8_WAIT_V(n) asm volatile("s_waitcnt vmcnt(" #n ")" ::: "memory")
; #define PG8_BAR __builtin_amdgcn_s_barrier()
; template <class Epi, class Sched, bool ALIGN_EPI = false, bool SP2 = false>
; __device__ __forceinline__ void gemm_phase(PG8_LAS unsigned char* lds, const Gemm g, const Sched& S, const Epi& E, const int wid) {
;     ...
;         for (int t = 0; t < nt; t += 2) {
;             const bool last = (t == nt - 2);
;             const char* a1 = cA + (size_t)(t + 1) * kstep;
;             const char* a2 = last ? nA : cA + (size_t)(t + 2) * kstep; const char* b2 = last ? nB : cB + (size_t)(t + 2) * kstep;
;             const char* a3 = a2 + kstep; const char* b3 = b2 + kstep;
;             if (last && has_next) S.a_ready(nxt);
;             if constexpr (SP2) {
;             PG8_LDB(B0, 0, 0); PG8_LDB(B1, 0, 1); PG8_SCHED; PG8_LDA(At, 0, 0); PG8_STAGE(PG8_SA(1, 1), a1 + hstep, voffA);
;             PG8_WAIT_V(8); PG8_WAIT_L(0); PG8_BAR; PG8_MMA(0, 0, At, B0); PG8_MMA(0, 1, At, B1); PG8_BAR; PG8_SCHED;
;             PG8_LDA(At, 0, 1); PG8_STAGE(PG8_SB(0, 0), b2, voffB); PG8_STAGE(PG8_SB(0, 1), b2 + hstep, voffB); PG8_STAGE(PG8_SA(0, 0), a2, voffA);
;             PG8_WAIT_V(8); PG8_WAIT_L(0); PG8_BAR; PG8_MMA(1, 0, At, B0); PG8_MMA(1, 1, At, B1); PG8_BAR; PG8_SCHED;
.LBB0_342:
	s_add_u32 s34, s30, 0xfff80080
	s_addc_u32 s35, s31, -1
	s_add_i32 s40, 0, 0x10000
	s_cmp_eq_u32 s91, 28
	s_cselect_b32 s37, s23, s35
	s_cselect_b32 s36, s29, s34
	v_add_u32_e32 v0, s40, v147
	s_cselect_b32 s35, s21, s90
	s_cselect_b32 s34, s88, s89
	s_add_i32 s42, 0, 0x14000
	ds_read_b128 v[142:145], v0
	ds_read_b128 v[150:153], v0 offset:1024
	ds_read_b128 v[154:157], v0 offset:2048
	ds_read_b128 v[158:161], v0 offset:3072
	v_add_u32_e32 v0, s42, v147
	ds_read_b128 v[162:165], v0
	ds_read_b128 v[166:169], v0 offset:1024
	ds_read_b128 v[170:173], v0 offset:2048
	ds_read_b128 v[174:177], v0 offset:3072
	v_lshl_add_u64 v[194:195], s[30:31], 0, v[138:139]
	s_add_i32 m0, s66, 0xc000
	ds_read_b128 v[178:181], v148
	ds_read_b128 v[182:185], v148 offset:1024
	ds_read_b128 v[186:189], v148 offset:2048
	ds_read_b128 v[190:193], v148 offset:3072
	ds_read_b128 v[212:215], v148 offset:4096
	ds_read_b128 v[216:219], v148 offset:5120
	ds_read_b128 v[220:223], v148 offset:6144
	ds_read_b128 v[224:227], v148 offset:7168
	global_load_lds_dwordx4 v[194:195], off
	v_lshl_add_u64 v[194:195], s[30:31], 0, v[140:141]
	s_add_i32 m0, s66, 0xe000
	s_nop 0
	global_load_lds_dwordx4 v[194:195], off
	s_waitcnt vmcnt(8)
	s_waitcnt lgkmcnt(0)
	s_setprio 1
	s_barrier
	v_mfma_f32_16x16x32_bf16 v[126:129], v[142:145], v[178:181], v[126:129]
	v_mfma_f32_16x16x32_bf16 v[122:125], v[154:157], v[178:181], v[122:125]
	v_mfma_f32_16x16x32_bf16 v[110:113], v[142:145], v[186:189], v[110:113]
	v_mfma_f32_16x16x32_bf16 v[106:109], v[154:157], v[186:189], v[106:109]
	v_mfma_f32_16x16x32_bf16 v[94:97], v[142:145], v[212:215], v[94:97]
	v_mfma_f32_16x16x32_bf16 v[90:93], v[154:157], v[212:215], v[90:93]
	v_mfma_f32_16x16x32_bf16 v[78:81], v[142:145], v[220:223], v[78:81]
	v_mfma_f32_16x16x32_bf16 v[74:77], v[154:157], v[220:223], v[74:77]
	v_mfma_f32_16x16x32_bf16 v[126:129], v[150:153], v[182:185], v[126:129]
	v_mfma_f32_16x16x32_bf16 v[122:125], v[158:161], v[182:185], v[122:125]
	v_mfma_f32_16x16x32_bf16 v[110:113], v[150:153], v[190:193], v[110:113]
	v_mfma_f32_16x16x32_bf16 v[106:109], v[158:161], v[190:193], v[106:109]
	v_mfma_f32_16x16x32_bf16 v[94:97], v[150:153], v[216:219], v[94:97]
	v_mfma_f32_16x16x32_bf16 v[90:93], v[158:161], v[216:219], v[90:93]
	v_mfma_f32_16x16x32_bf16 v[78:81], v[150:153], v[224:227], v[78:81]
	v_mfma_f32_16x16x32_bf16 v[74:77], v[158:161], v[224:227], v[74:77]
	s_setprio 0
	s_setprio 1
	v_mfma_f32_16x16x32_bf16 v[118:121], v[162:165], v[178:181], v[118:121]
	v_mfma_f32_16x16x32_bf16 v[114:117], v[170:173], v[178:181], v[114:117]
	v_mfma_f32_16x16x32_bf16 v[102:105], v[162:165], v[186:189], v[102:105]
	v_mfma_f32_16x16x32_bf16 v[98:101], v[170:173], v[186:189], v[98:101]
	v_mfma_f32_16x16x32_bf16 v[86:89], v[162:165], v[212:215], v[86:89]
	v_mfma_f32_16x16x32_bf16 v[82:85], v[170:173], v[212:215], v[82:85]
	v_mfma_f32_16x16x32_bf16 v[70:73], v[162:165], v[220:223], v[70:73]
	v_mfma_f32_16x16x32_bf16 v[66:69], v[170:173], v[220:223], v[66:69]
	v_mfma_f32_16x16x32_bf16 v[118:121], v[166:169], v[182:185], v[118:121]
	v_mfma_f32_16x16x32_bf16 v[114:117], v[174:177], v[182:185], v[114:117]
	v_mfma_f32_16x16x32_bf16 v[102:105], v[166:169], v[190:193], v[102:105]
	v_mfma_f32_16x16x32_bf16 v[98:101], v[174:177], v[190:193], v[98:101]
	v_mfma_f32_16x16x32_bf16 v[86:89], v[166:169], v[216:219], v[86:89]
	v_mfma_f32_16x16x32_bf16 v[82:85], v[174:177], v[216:219], v[82:85]
	v_mfma_f32_16x16x32_bf16 v[70:73], v[166:169], v[224:227], v[70:73]
	v_mfma_f32_16x16x32_bf16 v[66:69], v[174:177], v[224:227], v[66:69]
	s_setprio 0
	s_barrier
	s_add_i32 s40, s40, s44
	v_lshl_add_u64 v[194:195], s[34:35], 0, v[134:135]
	s_mov_b32 m0, s40
	ds_read_b128 v[178:181], v148 offset:16384
	ds_read_b128 v[182:185], v148 offset:17408
	ds_read_b128 v[186:189], v148 offset:18432
	ds_read_b128 v[190:193], v148 offset:19456
	ds_read_b128 v[212:215], v148 offset:20480
	ds_read_b128 v[216:219], v148 offset:21504
	ds_read_b128 v[220:223], v148 offset:22528
	ds_read_b128 v[224:227], v148 offset:23552
	global_load_lds_dwordx4 v[194:195], off
	s_add_i32 m0, s40, 0x2000
	s_add_u32 s40, s34, 0x80000
	v_lshl_add_u64 v[200:201], s[34:35], 0, v[130:131]
	s_addc_u32 s41, s35, 0
	s_add_i32 s42, s42, s44
	global_load_lds_dwordx4 v[200:201], off
	v_lshl_add_u64 v[202:203], s[40:41], 0, v[134:135]
	s_mov_b32 m0, s42
	v_lshl_add_u64 v[208:209], s[36:37], 0, v[132:133]
	global_load_lds_dwordx4 v[202:203], off
	v_lshl_add_u64 v[202:203], s[40:41], 0, v[130:131]
	s_add_i32 m0, s42, 0x2000
	s_nop 0
	global_load_lds_dwordx4 v[202:203], off
	v_lshl_add_u64 v[202:203], s[36:37], 0, v[136:137]
	s_mov_b32 m0, s66
	s_nop 0
	global_load_lds_dwordx4 v[202:203], off
	s_mov_b32 m0, s67
	s_nop 0
	global_load_lds_dwordx4 v[208:209], off
	s_waitcnt vmcnt(8)
	s_waitcnt lgkmcnt(0)
	s_setprio 1
	s_barrier
; #define PG8_STAGE(bufoff, gbase, voff) do { _Pragma("unroll") for (int _i = 0; _i < 2; ++_i) \
;         __builtin_amdgcn_global_load_lds((const unsigned*)((const char*)(gbase) + (voff)[_i]), (PG8_LAS unsigned*)(lds + (bufoff) + ldsw + _i * 8192), 16, 0, 0); } while (0)
; #define PG8_LDA(dst, b, h) do { _Pragma("unroll") for (int m = 0; m < 4; ++m) _Pragma("unroll") for (int k = 0; k < 2; ++k) dst[m][k] = *(const PG8_LAS bf16x8*)(lds + PG8_SA(b, h) + aoff + m * 2048 + k * 1024); } while (0)
; #define PG8_LDB(dst, b, h) do { _Pragma("unroll") for (int n = 0; n < 2; ++n) _Pragma("unroll") for (int k = 0; k < 2; ++k) dst[n][k] = *(const PG8_LAS bf16x8*)(lds + PG8_SB(b, h) + boff + n * 2048 + k * 1024); } while (0)
; #define PG8_MMA(ai, bj, At, Bt) do { __builtin_amdgcn_s_setprio(1); _Pragma("unroll") for (int m = 0; m < 4; ++m) _Pragma("unroll") for (int n = 0; n < 2; ++n) _Pragma("unroll") for (int k = 0; k < 2; ++k) \
;         acc[ai][bj][m][n] = __builtin_amdgcn_mfma_f32_16x16x32_bf16(Bt[n][k], At[m][k], acc[ai][bj][m][n], 0, 0, 0); __builtin_amdgcn_s_setprio(0); } while (0)
; #define PG8_WAIT_V(n) asm volatile("s_waitcnt vmcnt(" #n ")" ::: "memory")
; #define PG8_WAIT_L(n) asm volatile("s_waitcnt lgkmcnt(" #n ")" ::: "memory")
; #define PG8_BAR __builtin_amdgcn_s_barrier()
; #define PG8_SCHED __builtin_amdgcn_sched_barrier(0)
; template <class Epi, class Sched, bool ALIGN_EPI = false, bool SP2 = false>
; __device__ __forceinline__ void gemm_phase(PG8_LAS unsigned char* lds, const Gemm g, const Sched& S, const Epi& E, const int wid) {
;     ...
;             PG8_WAIT_V(8); PG8_WAIT_L(0); PG8_BAR; PG8_MMA(1, 0, At, B0); PG8_MMA(1, 1, At, B1); PG8_BAR; PG8_SCHED;
;             PG8_LDB(B0, 1, 0); PG8_LDB(B1, 1, 1); PG8_SCHED; PG8_LDA(At, 1, 0); PG8_STAGE(PG8_SA(0, 1), a2 + hstep, voffA);
;             PG8_WAIT_V(8); PG8_WAIT_L(0); PG8_BAR; PG8_MMA(0, 0, At, B0); PG8_MMA(0, 1, At, B1); PG8_BAR; PG8_SCHED;
	v_mfma_f32_16x16x32_bf16 v[62:65], v[142:145], v[178:181], v[62:65]
	v_mfma_f32_16x16x32_bf16 v[58:61], v[154:157], v[178:181], v[58:61]
	v_mfma_f32_16x16x32_bf16 v[46:49], v[142:145], v[186:189], v[46:49]
	v_mfma_f32_16x16x32_bf16 v[42:45], v[154:157], v[186:189], v[42:45]
	v_mfma_f32_16x16x32_bf16 v[30:33], v[142:145], v[212:215], v[30:33]
	v_mfma_f32_16x16x32_bf16 v[26:29], v[154:157], v[212:215], v[26:29]
	v_mfma_f32_16x16x32_bf16 v[18:21], v[142:145], v[220:223], v[18:21]
	v_mfma_f32_16x16x32_bf16 v[10:13], v[154:157], v[220:223], v[10:13]
	v_mfma_f32_16x16x32_bf16 v[62:65], v[150:153], v[182:185], v[62:65]
	v_mfma_f32_16x16x32_bf16 v[58:61], v[158:161], v[182:185], v[58:61]
	v_mfma_f32_16x16x32_bf16 v[46:49], v[150:153], v[190:193], v[46:49]
	v_mfma_f32_16x16x32_bf16 v[42:45], v[158:161], v[190:193], v[42:45]
	v_mfma_f32_16x16x32_bf16 v[30:33], v[150:153], v[216:219], v[30:33]
	v_mfma_f32_16x16x32_bf16 v[26:29], v[158:161], v[216:219], v[26:29]
	v_mfma_f32_16x16x32_bf16 v[18:21], v[150:153], v[224:227], v[18:21]
	v_mfma_f32_16x16x32_bf16 v[10:13], v[158:161], v[224:227], v[10:13]
	s_setprio 0
	s_setprio 1
	v_mfma_f32_16x16x32_bf16 v[54:57], v[162:165], v[178:181], v[54:57]
	v_mfma_f32_16x16x32_bf16 v[50:53], v[170:173], v[178:181], v[50:53]
	v_mfma_f32_16x16x32_bf16 v[38:41], v[162:165], v[186:189], v[38:41]
	v_mfma_f32_16x16x32_bf16 v[34:37], v[170:173], v[186:189], v[34:37]
	v_mfma_f32_16x16x32_bf16 v[22:25], v[162:165], v[212:215], v[22:25]
	v_mfma_f32_16x16x32_bf16 v[14:17], v[170:173], v[212:215], v[14:17]
	v_mfma_f32_16x16x32_bf16 v[6:9], v[162:165], v[220:223], v[6:9]
	v_mfma_f32_16x16x32_bf16 v[2:5], v[170:173], v[220:223], v[2:5]
	v_mfma_f32_16x16x32_bf16 v[54:57], v[166:169], v[182:185], v[54:57]
	v_mfma_f32_16x16x32_bf16 v[50:53], v[174:177], v[182:185], v[50:53]
	v_mfma_f32_16x16x32_bf16 v[38:41], v[166:169], v[190:193], v[38:41]
	v_mfma_f32_16x16x32_bf16 v[34:37], v[174:177], v[190:193], v[34:37]
	v_mfma_f32_16x16x32_bf16 v[22:25], v[166:169], v[216:219], v[22:25]
	v_mfma_f32_16x16x32_bf16 v[14:17], v[174:177], v[216:219], v[14:17]
	v_mfma_f32_16x16x32_bf16 v[6:9], v[166:169], v[224:227], v[6:9]
	v_mfma_f32_16x16x32_bf16 v[2:5], v[174:177], v[224:227], v[2:5]
	s_setprio 0
	s_barrier
	s_add_i32 s40, 0, 0x18000
	v_add_u32_e32 v0, s40, v147
	s_add_i32 s41, 0, 0x1c000
	ds_read_b128 v[142:145], v0
	ds_read_b128 v[150:153], v0 offset:1024
	ds_read_b128 v[154:157], v0 offset:2048
	ds_read_b128 v[158:161], v0 offset:3072
	v_add_u32_e32 v0, s41, v147
	ds_read_b128 v[162:165], v0
	ds_read_b128 v[166:169], v0 offset:1024
	ds_read_b128 v[170:173], v0 offset:2048
	ds_read_b128 v[174:177], v0 offset:3072
	s_add_u32 s36, s36, 0x80000
	s_addc_u32 s37, s37, 0
	s_mov_b32 m0, s68
	v_lshl_add_u64 v[210:211], s[36:37], 0, v[136:137]
	ds_read_b128 v[178:181], v148 offset:32768
	ds_read_b128 v[182:185], v148 offset:33792
	ds_read_b128 v[186:189], v148 offset:34816
	ds_read_b128 v[190:193], v148 offset:35840
	ds_read_b128 v[212:215], v148 offset:36864
	ds_read_b128 v[216:219], v148 offset:37888
	ds_read_b128 v[220:223], v148 offset:38912
	ds_read_b128 v[224:227], v148 offset:39936
	global_load_lds_dwordx4 v[210:211], off
	v_lshl_add_u64 v[210:211], s[36:37], 0, v[132:133]
	s_mov_b32 m0, s77
	s_nop 0
	global_load_lds_dwordx4 v[210:211], off
	s_waitcnt vmcnt(8)
	s_waitcnt lgkmcnt(0)
	s_setprio 1
	s_barrier
	v_mfma_f32_16x16x32_bf16 v[126:129], v[142:145], v[178:181], v[126:129]
	v_mfma_f32_16x16x32_bf16 v[122:125], v[154:157], v[178:181], v[122:125]
	v_mfma_f32_16x16x32_bf16 v[110:113], v[142:145], v[186:189], v[110:113]
	v_mfma_f32_16x16x32_bf16 v[106:109], v[154:157], v[186:189], v[106:109]
	v_mfma_f32_16x16x32_bf16 v[94:97], v[142:145], v[212:215], v[94:97]
	v_mfma_f32_16x16x32_bf16 v[90:93], v[154:157], v[212:215], v[90:93]
	v_mfma_f32_16x16x32_bf16 v[78:81], v[142:145], v[220:223], v[78:81]
	v_mfma_f32_16x16x32_bf16 v[74:77], v[154:157], v[220:223], v[74:77]
	v_mfma_f32_16x16x32_bf16 v[126:129], v[150:153], v[182:185], v[126:129]
	v_mfma_f32_16x16x32_bf16 v[122:125], v[158:161], v[182:185], v[122:125]
	v_mfma_f32_16x16x32_bf16 v[110:113], v[150:153], v[190:193], v[110:113]
	v_mfma_f32_16x16x32_bf16 v[106:109], v[158:161], v[190:193], v[106:109]
	v_mfma_f32_16x16x32_bf16 v[94:97], v[150:153], v[216:219], v[94:97]
	v_mfma_f32_16x16x32_bf16 v[90:93], v[158:161], v[216:219], v[90:93]
	v_mfma_f32_16x16x32_bf16 v[78:81], v[150:153], v[224:227], v[78:81]
	v_mfma_f32_16x16x32_bf16 v[74:77], v[158:161], v[224:227], v[74:77]
	s_setprio 0
	s_setprio 1
	v_mfma_f32_16x16x32_bf16 v[118:121], v[162:165], v[178:181], v[118:121]
	v_mfma_f32_16x16x32_bf16 v[114:117], v[170:173], v[178:181], v[114:117]
	v_mfma_f32_16x16x32_bf16 v[102:105], v[162:165], v[186:189], v[102:105]
	v_mfma_f32_16x16x32_bf16 v[98:101], v[170:173], v[186:189], v[98:101]
	v_mfma_f32_16x16x32_bf16 v[86:89], v[162:165], v[212:215], v[86:89]
	v_mfma_f32_16x16x32_bf16 v[82:85], v[170:173], v[212:215], v[82:85]
	v_mfma_f32_16x16x32_bf16 v[70:73], v[162:165], v[220:223], v[70:73]
	v_mfma_f32_16x16x32_bf16 v[66:69], v[170:173], v[220:223], v[66:69]
	v_mfma_f32_16x16x32_bf16 v[118:121], v[166:169], v[182:185], v[118:121]
	v_mfma_f32_16x16x32_bf16 v[114:117], v[174:177], v[182:185], v[114:117]
	v_mfma_f32_16x16x32_bf16 v[102:105], v[166:169], v[190:193], v[102:105]
	v_mfma_f32_16x16x32_bf16 v[98:101], v[174:177], v[190:193], v[98:101]
	v_mfma_f32_16x16x32_bf16 v[86:89], v[166:169], v[216:219], v[86:89]
	v_mfma_f32_16x16x32_bf16 v[82:85], v[174:177], v[216:219], v[82:85]
	v_mfma_f32_16x16x32_bf16 v[70:73], v[166:169], v[224:227], v[70:73]
	v_mfma_f32_16x16x32_bf16 v[66:69], v[174:177], v[224:227], v[66:69]
	s_setprio 0
	s_barrier
; #define PG8_STAGE(bufoff, gbase, voff) do { _Pragma("unroll") for (int _i = 0; _i < 2; ++_i) \
;         __builtin_amdgcn_global_load_lds((const unsigned*)((const char*)(gbase) + (voff)[_i]), (PG8_LAS unsigned*)(lds + (bufoff) + ldsw + _i * 8192), 16, 0, 0); } while (0)
; #define PG8_LDA(dst, b, h) do { _Pragma("unroll") for (int m = 0; m < 4; ++m) _Pragma("unroll") for (int k = 0; k < 2; ++k) dst[m][k] = *(const PG8_LAS bf16x8*)(lds + PG8_SA(b, h) + aoff + m * 2048 + k * 1024); } while (0)
; #define PG8_MMA(ai, bj, At, Bt) do { __builtin_amdgcn_s_setprio(1); _Pragma("unroll") for (int m = 0; m < 4; ++m) _Pragma("unroll") for (int n = 0; n < 2; ++n) _Pragma("unroll") for (int k = 0; k < 2; ++k) \
;         acc[ai][bj][m][n] = __builtin_amdgcn_mfma_f32_16x16x32_bf16(Bt[n][k], At[m][k], acc[ai][bj][m][n], 0, 0, 0); __builtin_amdgcn_s_setprio(0); } while (0)
; #define PG8_WAIT_V(n) asm volatile("s_waitcnt vmcnt(" #n ")" ::: "memory")
; #define PG8_WAIT_L(n) asm volatile("s_waitcnt lgkmcnt(" #n ")" ::: "memory")
; #define PG8_BAR __builtin_amdgcn_s_barrier()
; #define PG8_SCHED __builtin_amdgcn_sched_barrier(0)
; template <class Epi, class Sched, bool ALIGN_EPI = false, bool SP2 = false>
; __device__ __forceinline__ void gemm_phase(PG8_LAS unsigned char* lds, const Gemm g, const Sched& S, const Epi& E, const int wid) {
;     ...
;         for (int t = 0; t < nt; t += 2) {
;     ...
;             PG8_LDA(At, 1, 1); PG8_STAGE(PG8_SB(1, 0), b3, voffB); PG8_STAGE(PG8_SB(1, 1), b3 + hstep, voffB); PG8_STAGE(PG8_SA(1, 0), a3, voffA);
;             PG8_WAIT_V(8); PG8_WAIT_L(0); PG8_BAR; PG8_MMA(1, 0, At, B0); PG8_MMA(1, 1, At, B1); PG8_BAR; PG8_SCHED;
	s_add_i32 s36, s40, s44
	v_lshl_add_u64 v[194:195], v[194:195], 0, s[58:59]
	s_mov_b32 m0, s36
	ds_read_b128 v[178:181], v148 offset:49152
	ds_read_b128 v[182:185], v148 offset:50176
	ds_read_b128 v[186:189], v148 offset:51200
	ds_read_b128 v[190:193], v148 offset:52224
	ds_read_b128 v[212:215], v148 offset:53248
	ds_read_b128 v[216:219], v148 offset:54272
	ds_read_b128 v[220:223], v148 offset:55296
	ds_read_b128 v[224:227], v148 offset:56320
	global_load_lds_dwordx4 v[194:195], off
	s_add_i32 m0, s36, 0x2000
	s_add_u32 s34, s34, 0x80080
	v_lshl_add_u64 v[194:195], v[200:201], 0, s[58:59]
	s_addc_u32 s35, s35, 0
	s_add_i32 s36, s41, s44
	global_load_lds_dwordx4 v[194:195], off
	v_lshl_add_u64 v[194:195], s[34:35], 0, v[134:135]
	s_mov_b32 m0, s36
	s_nop 0
	global_load_lds_dwordx4 v[194:195], off
	v_lshl_add_u64 v[194:195], s[34:35], 0, v[130:131]
	s_add_i32 m0, s36, 0x2000
	s_nop 0
	global_load_lds_dwordx4 v[194:195], off
	v_lshl_add_u64 v[194:195], v[202:203], 0, s[58:59]
	s_mov_b32 m0, s79
	s_nop 0
	global_load_lds_dwordx4 v[194:195], off
	v_lshl_add_u64 v[194:195], v[208:209], 0, s[58:59]
	s_mov_b32 m0, s84
	s_nop 0
	global_load_lds_dwordx4 v[194:195], off
	s_waitcnt vmcnt(8)
	s_waitcnt lgkmcnt(0)
	s_setprio 1
	s_barrier
	v_mfma_f32_16x16x32_bf16 v[62:65], v[142:145], v[178:181], v[62:65]
	v_mfma_f32_16x16x32_bf16 v[58:61], v[154:157], v[178:181], v[58:61]
	v_mfma_f32_16x16x32_bf16 v[46:49], v[142:145], v[186:189], v[46:49]
	v_mfma_f32_16x16x32_bf16 v[42:45], v[154:157], v[186:189], v[42:45]
	v_mfma_f32_16x16x32_bf16 v[30:33], v[142:145], v[212:215], v[30:33]
	v_mfma_f32_16x16x32_bf16 v[26:29], v[154:157], v[212:215], v[26:29]
	v_mfma_f32_16x16x32_bf16 v[18:21], v[142:145], v[220:223], v[18:21]
	v_mfma_f32_16x16x32_bf16 v[10:13], v[154:157], v[220:223], v[10:13]
	v_mfma_f32_16x16x32_bf16 v[62:65], v[150:153], v[182:185], v[62:65]
	v_mfma_f32_16x16x32_bf16 v[58:61], v[158:161], v[182:185], v[58:61]
	v_mfma_f32_16x16x32_bf16 v[46:49], v[150:153], v[190:193], v[46:49]
	v_mfma_f32_16x16x32_bf16 v[42:45], v[158:161], v[190:193], v[42:45]
	v_mfma_f32_16x16x32_bf16 v[30:33], v[150:153], v[216:219], v[30:33]
	v_mfma_f32_16x16x32_bf16 v[26:29], v[158:161], v[216:219], v[26:29]
	v_mfma_f32_16x16x32_bf16 v[18:21], v[150:153], v[224:227], v[18:21]
	v_mfma_f32_16x16x32_bf16 v[10:13], v[158:161], v[224:227], v[10:13]
	s_setprio 0
	s_setprio 1
	v_mfma_f32_16x16x32_bf16 v[54:57], v[162:165], v[178:181], v[54:57]
	v_mfma_f32_16x16x32_bf16 v[50:53], v[170:173], v[178:181], v[50:53]
	v_mfma_f32_16x16x32_bf16 v[38:41], v[162:165], v[186:189], v[38:41]
	v_mfma_f32_16x16x32_bf16 v[34:37], v[170:173], v[186:189], v[34:37]
	v_mfma_f32_16x16x32_bf16 v[22:25], v[162:165], v[212:215], v[22:25]
	v_mfma_f32_16x16x32_bf16 v[14:17], v[170:173], v[212:215], v[14:17]
	v_mfma_f32_16x16x32_bf16 v[6:9], v[162:165], v[220:223], v[6:9]
	v_mfma_f32_16x16x32_bf16 v[2:5], v[170:173], v[220:223], v[2:5]
	v_mfma_f32_16x16x32_bf16 v[54:57], v[166:169], v[182:185], v[54:57]
	v_mfma_f32_16x16x32_bf16 v[50:53], v[174:177], v[182:185], v[50:53]
	v_mfma_f32_16x16x32_bf16 v[38:41], v[166:169], v[190:193], v[38:41]
	v_mfma_f32_16x16x32_bf16 v[34:37], v[174:177], v[190:193], v[34:37]
	v_mfma_f32_16x16x32_bf16 v[22:25], v[166:169], v[216:219], v[22:25]
	v_mfma_f32_16x16x32_bf16 v[14:17], v[174:177], v[216:219], v[14:17]
	v_mfma_f32_16x16x32_bf16 v[6:9], v[166:169], v[224:227], v[6:9]
	v_mfma_f32_16x16x32_bf16 v[2:5], v[174:177], v[224:227], v[2:5]
	s_setprio 0
	s_barrier
	s_add_i32 s91, s91, 2
	s_add_u32 s30, s30, 0x100
	s_addc_u32 s31, s31, 0
	s_add_u32 s89, s89, 0x100
	s_addc_u32 s90, s90, 0
	s_cmp_gt_u32 s91, 29
	s_cbranch_scc0 .LBB0_342
	s_and_b64 vcc, exec, s[16:17]
	s_cbranch_vccz .LBB0_345
	s_barrier

; #define PG8_STAGE(bufoff, gbase, voff) do { _Pragma("unroll") for (int _i = 0; _i < 2; ++_i) \
;         __builtin_amdgcn_global_load_lds((const unsigned*)((const char*)(gbase) + (voff)[_i]), (PG8_LAS unsigned*)(lds + (bufoff) + ldsw + _i * 8192), 16, 0, 0); } while (0)
; #define PG8_LDA(dst, b, h) do { _Pragma("unroll") for (int m = 0; m < 4; ++m) _Pragma("unroll") for (int k = 0; k < 2; ++k) dst[m][k] = *(const PG8_LAS bf16x8*)(lds + PG8_SA(b, h) + aoff + m * 2048 + k * 1024); } while (0)
; #define PG8_LDB(dst, b, h) do { _Pragma("unroll") for (int n = 0; n < 2; ++n) _Pragma("unroll") for (int k = 0; k < 2; ++k) dst[n][k] = *(const PG8_LAS bf16x8*)(lds + PG8_SB(b, h) + boff + n * 2048 + k * 1024); } while (0)
; #define PG8_MMA(ai, bj, At, Bt) do { __builtin_amdgcn_s_setprio(1); _Pragma("unroll") for (int m = 0; m < 4; ++m) _Pragma("unroll") for (int n = 0; n < 2; ++n) _Pragma("unroll") for (int k = 0; k < 2; ++k) \
;         acc[ai][bj][m][n] = __builtin_amdgcn_mfma_f32_16x16x32_bf16(Bt[n][k], At[m][k], acc[ai][bj][m][n], 0, 0, 0); __builtin_amdgcn_s_setprio(0); } while (0)
; #define PG8_WAIT_V(n) asm volatile("s_waitcnt vmcnt(" #n ")" ::: "memory")
; #define PG8_BAR __builtin_amdgcn_s_barrier()
; template <class Epi, class Sched, bool ALIGN_EPI = false, bool SP2 = false>
; __device__ __forceinline__ void gemm_phase(PG8_LAS unsigned char* lds, const Gemm g, const Sched& S, const Epi& E, const int wid) {
;     ...
;         for (int t = 0; t < nt; t += 2) {
;             const bool last = (t == nt - 2);
;             const char* a1 = cA + (size_t)(t + 1) * kstep;
;             const char* a2 = last ? nA : cA + (size_t)(t + 2) * kstep; const char* b2 = last ? nB : cB + (size_t)(t + 2) * kstep;
;             const char* a3 = a2 + kstep; const char* b3 = b2 + kstep;
;             if (last && has_next) S.a_ready(nxt);
;             if constexpr (SP2) {
;             PG8_LDB(B0, 0, 0); PG8_LDB(B1, 0, 1); PG8_SCHED; PG8_LDA(At, 0, 0); PG8_STAGE(PG8_SA(1, 1), a1 + hstep, voffA);
;             PG8_WAIT_V(8); PG8_WAIT_L(0); PG8_BAR; PG8_MMA(0, 0, At, B0); PG8_MMA(0, 1, At, B1); PG8_BAR; PG8_SCHED;
;             PG8_LDA(At, 0, 1); PG8_STAGE(PG8_SB(0, 0), b2, voffB); PG8_STAGE(PG8_SB(0, 1), b2 + hstep, voffB); PG8_STAGE(PG8_SA(0, 0), a2, voffA);
;             PG8_WAIT_V(8); PG8_WAIT_L(0); PG8_BAR; PG8_MMA(1, 0, At, B0); PG8_MMA(1, 1, At, B1); PG8_BAR; PG8_SCHED;
.LBB0_375:
	s_add_u32 s34, s30, 0xfff80080
	s_addc_u32 s35, s31, -1
	s_add_i32 s40, 0, 0x10000
	s_cmp_eq_u32 s88, 28
	s_cselect_b32 s37, s23, s35
	s_cselect_b32 s36, s50, s34
	v_add_u32_e32 v0, s40, v163
	s_cselect_b32 s35, s21, s87
	s_cselect_b32 s34, s85, s86
	s_add_i32 s42, 0, 0x14000
	ds_read_b128 v[130:133], v0
	ds_read_b128 v[134:137], v0 offset:1024
	ds_read_b128 v[138:141], v0 offset:2048
	ds_read_b128 v[142:145], v0 offset:3072
	v_add_u32_e32 v0, s42, v163
	ds_read_b128 v[158:161], v0
	ds_read_b128 v[166:169], v0 offset:1024
	ds_read_b128 v[170:173], v0 offset:2048
	ds_read_b128 v[174:177], v0 offset:3072
	v_lshl_add_u64 v[194:195], s[30:31], 0, v[154:155]
	s_add_i32 m0, s29, 0xc000
	ds_read_b128 v[178:181], v164
	ds_read_b128 v[182:185], v164 offset:1024
	ds_read_b128 v[186:189], v164 offset:2048
	ds_read_b128 v[190:193], v164 offset:3072
	ds_read_b128 v[212:215], v164 offset:4096
	ds_read_b128 v[216:219], v164 offset:5120
	ds_read_b128 v[220:223], v164 offset:6144
	ds_read_b128 v[224:227], v164 offset:7168
	global_load_lds_dwordx4 v[194:195], off
	v_lshl_add_u64 v[194:195], s[30:31], 0, v[156:157]
	s_add_i32 m0, s29, 0xe000
	s_nop 0
	global_load_lds_dwordx4 v[194:195], off
	s_waitcnt vmcnt(8)
	s_waitcnt lgkmcnt(0)
	s_setprio 1
	s_barrier
	v_mfma_f32_16x16x32_bf16 v[126:129], v[130:133], v[178:181], v[126:129]
	v_mfma_f32_16x16x32_bf16 v[122:125], v[138:141], v[178:181], v[122:125]
	v_mfma_f32_16x16x32_bf16 v[118:121], v[130:133], v[186:189], v[118:121]
	v_mfma_f32_16x16x32_bf16 v[110:113], v[138:141], v[186:189], v[110:113]
	v_mfma_f32_16x16x32_bf16 v[102:105], v[130:133], v[212:215], v[102:105]
	v_mfma_f32_16x16x32_bf16 v[94:97], v[138:141], v[212:215], v[94:97]
	v_mfma_f32_16x16x32_bf16 v[86:89], v[130:133], v[220:223], v[86:89]
	v_mfma_f32_16x16x32_bf16 v[78:81], v[138:141], v[220:223], v[78:81]
	v_mfma_f32_16x16x32_bf16 v[126:129], v[134:137], v[182:185], v[126:129]
	v_mfma_f32_16x16x32_bf16 v[122:125], v[142:145], v[182:185], v[122:125]
	v_mfma_f32_16x16x32_bf16 v[118:121], v[134:137], v[190:193], v[118:121]
	v_mfma_f32_16x16x32_bf16 v[110:113], v[142:145], v[190:193], v[110:113]
	v_mfma_f32_16x16x32_bf16 v[102:105], v[134:137], v[216:219], v[102:105]
	v_mfma_f32_16x16x32_bf16 v[94:97], v[142:145], v[216:219], v[94:97]
	v_mfma_f32_16x16x32_bf16 v[86:89], v[134:137], v[224:227], v[86:89]
	v_mfma_f32_16x16x32_bf16 v[78:81], v[142:145], v[224:227], v[78:81]
	s_setprio 0
	s_setprio 1
	v_mfma_f32_16x16x32_bf16 v[114:117], v[158:161], v[178:181], v[114:117]
	v_mfma_f32_16x16x32_bf16 v[106:109], v[170:173], v[178:181], v[106:109]
	v_mfma_f32_16x16x32_bf16 v[98:101], v[158:161], v[186:189], v[98:101]
	v_mfma_f32_16x16x32_bf16 v[90:93], v[170:173], v[186:189], v[90:93]
	v_mfma_f32_16x16x32_bf16 v[82:85], v[158:161], v[212:215], v[82:85]
	v_mfma_f32_16x16x32_bf16 v[74:77], v[170:173], v[212:215], v[74:77]
	v_mfma_f32_16x16x32_bf16 v[70:73], v[158:161], v[220:223], v[70:73]
	v_mfma_f32_16x16x32_bf16 v[66:69], v[170:173], v[220:223], v[66:69]
	v_mfma_f32_16x16x32_bf16 v[114:117], v[166:169], v[182:185], v[114:117]
	v_mfma_f32_16x16x32_bf16 v[106:109], v[174:177], v[182:185], v[106:109]
	v_mfma_f32_16x16x32_bf16 v[98:101], v[166:169], v[190:193], v[98:101]
	v_mfma_f32_16x16x32_bf16 v[90:93], v[174:177], v[190:193], v[90:93]
	v_mfma_f32_16x16x32_bf16 v[82:85], v[166:169], v[216:219], v[82:85]
	v_mfma_f32_16x16x32_bf16 v[74:77], v[174:177], v[216:219], v[74:77]
	v_mfma_f32_16x16x32_bf16 v[70:73], v[166:169], v[224:227], v[70:73]
	v_mfma_f32_16x16x32_bf16 v[66:69], v[174:177], v[224:227], v[66:69]
	s_setprio 0
	s_barrier
	s_add_i32 s40, s40, s44
	v_lshl_add_u64 v[194:195], s[34:35], 0, v[148:149]
	s_mov_b32 m0, s40
	ds_read_b128 v[178:181], v164 offset:16384
	ds_read_b128 v[182:185], v164 offset:17408
	ds_read_b128 v[186:189], v164 offset:18432
	ds_read_b128 v[190:193], v164 offset:19456
	ds_read_b128 v[212:215], v164 offset:20480
	ds_read_b128 v[216:219], v164 offset:21504
	ds_read_b128 v[220:223], v164 offset:22528
	ds_read_b128 v[224:227], v164 offset:23552
	global_load_lds_dwordx4 v[194:195], off
	s_add_i32 m0, s40, 0x2000
	s_add_u32 s40, s34, 0x80000
	v_lshl_add_u64 v[200:201], s[34:35], 0, v[152:153]
	s_addc_u32 s41, s35, 0
	s_add_i32 s42, s42, s44
	global_load_lds_dwordx4 v[200:201], off
	v_lshl_add_u64 v[202:203], s[40:41], 0, v[148:149]
	s_mov_b32 m0, s42
	v_lshl_add_u64 v[208:209], s[36:37], 0, v[150:151]
	global_load_lds_dwordx4 v[202:203], off
	v_lshl_add_u64 v[202:203], s[40:41], 0, v[152:153]
	s_add_i32 m0, s42, 0x2000
	s_nop 0
	global_load_lds_dwordx4 v[202:203], off
	v_lshl_add_u64 v[202:203], s[36:37], 0, v[146:147]
	s_mov_b32 m0, s29
	s_nop 0
	global_load_lds_dwordx4 v[202:203], off
	s_mov_b32 m0, s66
	s_nop 0
	global_load_lds_dwordx4 v[208:209], off
	s_waitcnt vmcnt(8)
	s_waitcnt lgkmcnt(0)
	s_setprio 1
	s_barrier
; #define PG8_STAGE(bufoff, gbase, voff) do { _Pragma("unroll") for (int _i = 0; _i < 2; ++_i) \
;         __builtin_amdgcn_global_load_lds((const unsigned*)((const char*)(gbase) + (voff)[_i]), (PG8_LAS unsigned*)(lds + (bufoff) + ldsw + _i * 8192), 16, 0, 0); } while (0)
; #define PG8_LDA(dst, b, h) do { _Pragma("unroll") for (int m = 0; m < 4; ++m) _Pragma("unroll") for (int k = 0; k < 2; ++k) dst[m][k] = *(const PG8_LAS bf16x8*)(lds + PG8_SA(b, h) + aoff + m * 2048 + k * 1024); } while (0)
; #define PG8_LDB(dst, b, h) do { _Pragma("unroll") for (int n = 0; n < 2; ++n) _Pragma("unroll") for (int k = 0; k < 2; ++k) dst[n][k] = *(const PG8_LAS bf16x8*)(lds + PG8_SB(b, h) + boff + n * 2048 + k * 1024); } while (0)
; #define PG8_MMA(ai, bj, At, Bt) do { __builtin_amdgcn_s_setprio(1); _Pragma("unroll") for (int m = 0; m < 4; ++m) _Pragma("unroll") for (int n = 0; n < 2; ++n) _Pragma("unroll") for (int k = 0; k < 2; ++k) \
;         acc[ai][bj][m][n] = __builtin_amdgcn_mfma_f32_16x16x32_bf16(Bt[n][k], At[m][k], acc[ai][bj][m][n], 0, 0, 0); __builtin_amdgcn_s_setprio(0); } while (0)
; #define PG8_WAIT_V(n) asm volatile("s_waitcnt vmcnt(" #n ")" ::: "memory")
; #define PG8_WAIT_L(n) asm volatile("s_waitcnt lgkmcnt(" #n ")" ::: "memory")
; #define PG8_BAR __builtin_amdgcn_s_barrier()
; #define PG8_SCHED __builtin_amdgcn_sched_barrier(0)
; template <class Epi, class Sched, bool ALIGN_EPI = false, bool SP2 = false>
; __device__ __forceinline__ void gemm_phase(PG8_LAS unsigned char* lds, const Gemm g, const Sched& S, const Epi& E, const int wid) {
;     ...
;             PG8_WAIT_V(8); PG8_WAIT_L(0); PG8_BAR; PG8_MMA(1, 0, At, B0); PG8_MMA(1, 1, At, B1); PG8_BAR; PG8_SCHED;
;             PG8_LDB(B0, 1, 0); PG8_LDB(B1, 1, 1); PG8_SCHED; PG8_LDA(At, 1, 0); PG8_STAGE(PG8_SA(0, 1), a2 + hstep, voffA);
;             PG8_WAIT_V(8); PG8_WAIT_L(0); PG8_BAR; PG8_MMA(0, 0, At, B0); PG8_MMA(0, 1, At, B1); PG8_BAR; PG8_SCHED;
	v_mfma_f32_16x16x32_bf16 v[62:65], v[130:133], v[178:181], v[62:65]
	v_mfma_f32_16x16x32_bf16 v[58:61], v[138:141], v[178:181], v[58:61]
	v_mfma_f32_16x16x32_bf16 v[54:57], v[130:133], v[186:189], v[54:57]
	v_mfma_f32_16x16x32_bf16 v[46:49], v[138:141], v[186:189], v[46:49]
	v_mfma_f32_16x16x32_bf16 v[38:41], v[130:133], v[212:215], v[38:41]
	v_mfma_f32_16x16x32_bf16 v[30:33], v[138:141], v[212:215], v[30:33]
	v_mfma_f32_16x16x32_bf16 v[22:25], v[130:133], v[220:223], v[22:25]
	v_mfma_f32_16x16x32_bf16 v[14:17], v[138:141], v[220:223], v[14:17]
	v_mfma_f32_16x16x32_bf16 v[62:65], v[134:137], v[182:185], v[62:65]
	v_mfma_f32_16x16x32_bf16 v[58:61], v[142:145], v[182:185], v[58:61]
	v_mfma_f32_16x16x32_bf16 v[54:57], v[134:137], v[190:193], v[54:57]
	v_mfma_f32_16x16x32_bf16 v[46:49], v[142:145], v[190:193], v[46:49]
	v_mfma_f32_16x16x32_bf16 v[38:41], v[134:137], v[216:219], v[38:41]
	v_mfma_f32_16x16x32_bf16 v[30:33], v[142:145], v[216:219], v[30:33]
	v_mfma_f32_16x16x32_bf16 v[22:25], v[134:137], v[224:227], v[22:25]
	v_mfma_f32_16x16x32_bf16 v[14:17], v[142:145], v[224:227], v[14:17]
	s_setprio 0
	s_setprio 1
	v_mfma_f32_16x16x32_bf16 v[50:53], v[158:161], v[178:181], v[50:53]
	v_mfma_f32_16x16x32_bf16 v[42:45], v[170:173], v[178:181], v[42:45]
	v_mfma_f32_16x16x32_bf16 v[34:37], v[158:161], v[186:189], v[34:37]
	v_mfma_f32_16x16x32_bf16 v[26:29], v[170:173], v[186:189], v[26:29]
	v_mfma_f32_16x16x32_bf16 v[18:21], v[158:161], v[212:215], v[18:21]
	v_mfma_f32_16x16x32_bf16 v[10:13], v[170:173], v[212:215], v[10:13]
	v_mfma_f32_16x16x32_bf16 v[6:9], v[158:161], v[220:223], v[6:9]
	v_mfma_f32_16x16x32_bf16 v[2:5], v[170:173], v[220:223], v[2:5]
	v_mfma_f32_16x16x32_bf16 v[50:53], v[166:169], v[182:185], v[50:53]
	v_mfma_f32_16x16x32_bf16 v[42:45], v[174:177], v[182:185], v[42:45]
	v_mfma_f32_16x16x32_bf16 v[34:37], v[166:169], v[190:193], v[34:37]
	v_mfma_f32_16x16x32_bf16 v[26:29], v[174:177], v[190:193], v[26:29]
	v_mfma_f32_16x16x32_bf16 v[18:21], v[166:169], v[216:219], v[18:21]
	v_mfma_f32_16x16x32_bf16 v[10:13], v[174:177], v[216:219], v[10:13]
	v_mfma_f32_16x16x32_bf16 v[6:9], v[166:169], v[224:227], v[6:9]
	v_mfma_f32_16x16x32_bf16 v[2:5], v[174:177], v[224:227], v[2:5]
	s_setprio 0
	s_barrier
	s_add_i32 s40, 0, 0x18000
	v_add_u32_e32 v0, s40, v163
	s_add_i32 s41, 0, 0x1c000
	ds_read_b128 v[130:133], v0
	ds_read_b128 v[134:137], v0 offset:1024
	ds_read_b128 v[138:141], v0 offset:2048
	ds_read_b128 v[142:145], v0 offset:3072
	v_add_u32_e32 v0, s41, v163
	ds_read_b128 v[158:161], v0
	ds_read_b128 v[166:169], v0 offset:1024
	ds_read_b128 v[170:173], v0 offset:2048
	ds_read_b128 v[174:177], v0 offset:3072
	s_add_u32 s36, s36, 0x80000
	s_addc_u32 s37, s37, 0
	s_mov_b32 m0, s67
	v_lshl_add_u64 v[210:211], s[36:37], 0, v[146:147]
	ds_read_b128 v[178:181], v164 offset:32768
	ds_read_b128 v[182:185], v164 offset:33792
	ds_read_b128 v[186:189], v164 offset:34816
	ds_read_b128 v[190:193], v164 offset:35840
	ds_read_b128 v[212:215], v164 offset:36864
	ds_read_b128 v[216:219], v164 offset:37888
	ds_read_b128 v[220:223], v164 offset:38912
	ds_read_b128 v[224:227], v164 offset:39936
	global_load_lds_dwordx4 v[210:211], off
	v_lshl_add_u64 v[210:211], s[36:37], 0, v[150:151]
	s_mov_b32 m0, s68
	s_nop 0
	global_load_lds_dwordx4 v[210:211], off
	s_waitcnt vmcnt(8)
	s_waitcnt lgkmcnt(0)
	s_setprio 1
	s_barrier
	v_mfma_f32_16x16x32_bf16 v[126:129], v[130:133], v[178:181], v[126:129]
	v_mfma_f32_16x16x32_bf16 v[122:125], v[138:141], v[178:181], v[122:125]
	v_mfma_f32_16x16x32_bf16 v[118:121], v[130:133], v[186:189], v[118:121]
	v_mfma_f32_16x16x32_bf16 v[110:113], v[138:141], v[186:189], v[110:113]
	v_mfma_f32_16x16x32_bf16 v[102:105], v[130:133], v[212:215], v[102:105]
	v_mfma_f32_16x16x32_bf16 v[94:97], v[138:141], v[212:215], v[94:97]
	v_mfma_f32_16x16x32_bf16 v[86:89], v[130:133], v[220:223], v[86:89]
	v_mfma_f32_16x16x32_bf16 v[78:81], v[138:141], v[220:223], v[78:81]
	v_mfma_f32_16x16x32_bf16 v[126:129], v[134:137], v[182:185], v[126:129]
	v_mfma_f32_16x16x32_bf16 v[122:125], v[142:145], v[182:185], v[122:125]
	v_mfma_f32_16x16x32_bf16 v[118:121], v[134:137], v[190:193], v[118:121]
	v_mfma_f32_16x16x32_bf16 v[110:113], v[142:145], v[190:193], v[110:113]
	v_mfma_f32_16x16x32_bf16 v[102:105], v[134:137], v[216:219], v[102:105]
	v_mfma_f32_16x16x32_bf16 v[94:97], v[142:145], v[216:219], v[94:97]
	v_mfma_f32_16x16x32_bf16 v[86:89], v[134:137], v[224:227], v[86:89]
	v_mfma_f32_16x16x32_bf16 v[78:81], v[142:145], v[224:227], v[78:81]
	s_setprio 0
	s_setprio 1
	v_mfma_f32_16x16x32_bf16 v[114:117], v[158:161], v[178:181], v[114:117]
	v_mfma_f32_16x16x32_bf16 v[106:109], v[170:173], v[178:181], v[106:109]
	v_mfma_f32_16x16x32_bf16 v[98:101], v[158:161], v[186:189], v[98:101]
	v_mfma_f32_16x16x32_bf16 v[90:93], v[170:173], v[186:189], v[90:93]
	v_mfma_f32_16x16x32_bf16 v[82:85], v[158:161], v[212:215], v[82:85]
	v_mfma_f32_16x16x32_bf16 v[74:77], v[170:173], v[212:215], v[74:77]
	v_mfma_f32_16x16x32_bf16 v[70:73], v[158:161], v[220:223], v[70:73]
	v_mfma_f32_16x16x32_bf16 v[66:69], v[170:173], v[220:223], v[66:69]
	v_mfma_f32_16x16x32_bf16 v[114:117], v[166:169], v[182:185], v[114:117]
	v_mfma_f32_16x16x32_bf16 v[106:109], v[174:177], v[182:185], v[106:109]
	v_mfma_f32_16x16x32_bf16 v[98:101], v[166:169], v[190:193], v[98:101]
	v_mfma_f32_16x16x32_bf16 v[90:93], v[174:177], v[190:193], v[90:93]
	v_mfma_f32_16x16x32_bf16 v[82:85], v[166:169], v[216:219], v[82:85]
	v_mfma_f32_16x16x32_bf16 v[74:77], v[174:177], v[216:219], v[74:77]
	v_mfma_f32_16x16x32_bf16 v[70:73], v[166:169], v[224:227], v[70:73]
	v_mfma_f32_16x16x32_bf16 v[66:69], v[174:177], v[224:227], v[66:69]
	s_setprio 0
	s_barrier
; #define PG8_STAGE(bufoff, gbase, voff) do { _Pragma("unroll") for (int _i = 0; _i < 2; ++_i) \
;         __builtin_amdgcn_global_load_lds((const unsigned*)((const char*)(gbase) + (voff)[_i]), (PG8_LAS unsigned*)(lds + (bufoff) + ldsw + _i * 8192), 16, 0, 0); } while (0)
; #define PG8_LDA(dst, b, h) do { _Pragma("unroll") for (int m = 0; m < 4; ++m) _Pragma("unroll") for (int k = 0; k < 2; ++k) dst[m][k] = *(const PG8_LAS bf16x8*)(lds + PG8_SA(b, h) + aoff + m * 2048 + k * 1024); } while (0)
; #define PG8_MMA(ai, bj, At, Bt) do { __builtin_amdgcn_s_setprio(1); _Pragma("unroll") for (int m = 0; m < 4; ++m) _Pragma("unroll") for (int n = 0; n < 2; ++n) _Pragma("unroll") for (int k = 0; k < 2; ++k) \
;         acc[ai][bj][m][n] = __builtin_amdgcn_mfma_f32_16x16x32_bf16(Bt[n][k], At[m][k], acc[ai][bj][m][n], 0, 0, 0); __builtin_amdgcn_s_setprio(0); } while (0)
; #define PG8_WAIT_V(n) asm volatile("s_waitcnt vmcnt(" #n ")" ::: "memory")
; #define PG8_WAIT_L(n) asm volatile("s_waitcnt lgkmcnt(" #n ")" ::: "memory")
; #define PG8_BAR __builtin_amdgcn_s_barrier()
; #define PG8_SCHED __builtin_amdgcn_sched_barrier(0)
; template <class Epi, class Sched, bool ALIGN_EPI = false, bool SP2 = false>
; __device__ __forceinline__ void gemm_phase(PG8_LAS unsigned char* lds, const Gemm g, const Sched& S, const Epi& E, const int wid) {
;     ...
;         for (int t = 0; t < nt; t += 2) {
;     ...
;             PG8_LDA(At, 1, 1); PG8_STAGE(PG8_SB(1, 0), b3, voffB); PG8_STAGE(PG8_SB(1, 1), b3 + hstep, voffB); PG8_STAGE(PG8_SA(1, 0), a3, voffA);
;             PG8_WAIT_V(8); PG8_WAIT_L(0); PG8_BAR; PG8_MMA(1, 0, At, B0); PG8_MMA(1, 1, At, B1); PG8_BAR; PG8_SCHED;
	s_add_i32 s36, s40, s44
	v_lshl_add_u64 v[194:195], v[194:195], 0, s[58:59]
	s_mov_b32 m0, s36
	ds_read_b128 v[178:181], v164 offset:49152
	ds_read_b128 v[182:185], v164 offset:50176
	ds_read_b128 v[186:189], v164 offset:51200
	ds_read_b128 v[190:193], v164 offset:52224
	ds_read_b128 v[212:215], v164 offset:53248
	ds_read_b128 v[216:219], v164 offset:54272
	ds_read_b128 v[220:223], v164 offset:55296
	ds_read_b128 v[224:227], v164 offset:56320
	global_load_lds_dwordx4 v[194:195], off
	s_add_i32 m0, s36, 0x2000
	s_add_u32 s34, s34, 0x80080
	v_lshl_add_u64 v[194:195], v[200:201], 0, s[58:59]
	s_addc_u32 s35, s35, 0
	s_add_i32 s36, s41, s44
	global_load_lds_dwordx4 v[194:195], off
	v_lshl_add_u64 v[194:195], s[34:35], 0, v[148:149]
	s_mov_b32 m0, s36
	s_nop 0
	global_load_lds_dwordx4 v[194:195], off
	v_lshl_add_u64 v[194:195], s[34:35], 0, v[152:153]
	s_add_i32 m0, s36, 0x2000
	s_nop 0
	global_load_lds_dwordx4 v[194:195], off
	v_lshl_add_u64 v[194:195], v[202:203], 0, s[58:59]
	s_mov_b32 m0, s77
	s_nop 0
	global_load_lds_dwordx4 v[194:195], off
	v_lshl_add_u64 v[194:195], v[208:209], 0, s[58:59]
	s_mov_b32 m0, s79
	s_nop 0
	global_load_lds_dwordx4 v[194:195], off
	s_waitcnt vmcnt(8)
	s_waitcnt lgkmcnt(0)
	s_setprio 1
	s_barrier
	v_mfma_f32_16x16x32_bf16 v[62:65], v[130:133], v[178:181], v[62:65]
	v_mfma_f32_16x16x32_bf16 v[58:61], v[138:141], v[178:181], v[58:61]
	v_mfma_f32_16x16x32_bf16 v[54:57], v[130:133], v[186:189], v[54:57]
	v_mfma_f32_16x16x32_bf16 v[46:49], v[138:141], v[186:189], v[46:49]
	v_mfma_f32_16x16x32_bf16 v[38:41], v[130:133], v[212:215], v[38:41]
	v_mfma_f32_16x16x32_bf16 v[30:33], v[138:141], v[212:215], v[30:33]
	v_mfma_f32_16x16x32_bf16 v[22:25], v[130:133], v[220:223], v[22:25]
	v_mfma_f32_16x16x32_bf16 v[14:17], v[138:141], v[220:223], v[14:17]
	v_mfma_f32_16x16x32_bf16 v[62:65], v[134:137], v[182:185], v[62:65]
	v_mfma_f32_16x16x32_bf16 v[58:61], v[142:145], v[182:185], v[58:61]
	v_mfma_f32_16x16x32_bf16 v[54:57], v[134:137], v[190:193], v[54:57]
	v_mfma_f32_16x16x32_bf16 v[46:49], v[142:145], v[190:193], v[46:49]
	v_mfma_f32_16x16x32_bf16 v[38:41], v[134:137], v[216:219], v[38:41]
	v_mfma_f32_16x16x32_bf16 v[30:33], v[142:145], v[216:219], v[30:33]
	v_mfma_f32_16x16x32_bf16 v[22:25], v[134:137], v[224:227], v[22:25]
	v_mfma_f32_16x16x32_bf16 v[14:17], v[142:145], v[224:227], v[14:17]
	s_setprio 0
	s_setprio 1
	v_mfma_f32_16x16x32_bf16 v[50:53], v[158:161], v[178:181], v[50:53]
	v_mfma_f32_16x16x32_bf16 v[42:45], v[170:173], v[178:181], v[42:45]
	v_mfma_f32_16x16x32_bf16 v[34:37], v[158:161], v[186:189], v[34:37]
	v_mfma_f32_16x16x32_bf16 v[26:29], v[170:173], v[186:189], v[26:29]
	v_mfma_f32_16x16x32_bf16 v[18:21], v[158:161], v[212:215], v[18:21]
	v_mfma_f32_16x16x32_bf16 v[10:13], v[170:173], v[212:215], v[10:13]
	v_mfma_f32_16x16x32_bf16 v[6:9], v[158:161], v[220:223], v[6:9]
	v_mfma_f32_16x16x32_bf16 v[2:5], v[170:173], v[220:223], v[2:5]
	v_mfma_f32_16x16x32_bf16 v[50:53], v[166:169], v[182:185], v[50:53]
	v_mfma_f32_16x16x32_bf16 v[42:45], v[174:177], v[182:185], v[42:45]
	v_mfma_f32_16x16x32_bf16 v[34:37], v[166:169], v[190:193], v[34:37]
	v_mfma_f32_16x16x32_bf16 v[26:29], v[174:177], v[190:193], v[26:29]
	v_mfma_f32_16x16x32_bf16 v[18:21], v[166:169], v[216:219], v[18:21]
	v_mfma_f32_16x16x32_bf16 v[10:13], v[174:177], v[216:219], v[10:13]
	v_mfma_f32_16x16x32_bf16 v[6:9], v[166:169], v[224:227], v[6:9]
	v_mfma_f32_16x16x32_bf16 v[2:5], v[174:177], v[224:227], v[2:5]
	s_setprio 0
	s_barrier
	s_add_i32 s88, s88, 2
	s_add_u32 s30, s30, 0x100
	s_addc_u32 s31, s31, 0
	s_add_u32 s86, s86, 0x100
	s_addc_u32 s87, s87, 0
	s_cmp_gt_u32 s88, 29
	s_cbranch_scc0 .LBB0_375
	s_and_b64 vcc, exec, s[16:17]
	s_cbranch_vccz .LBB0_378
	s_barrier

; #define PG8_STAGE(bufoff, gbase, voff) do { _Pragma("unroll") for (int _i = 0; _i < 2; ++_i) \
;         __builtin_amdgcn_global_load_lds((const unsigned*)((const char*)(gbase) + (voff)[_i]), (PG8_LAS unsigned*)(lds + (bufoff) + ldsw + _i * 8192), 16, 0, 0); } while (0)
; #define PG8_LDA(dst, b, h) do { _Pragma("unroll") for (int m = 0; m < 4; ++m) _Pragma("unroll") for (int k = 0; k < 2; ++k) dst[m][k] = *(const PG8_LAS bf16x8*)(lds + PG8_SA(b, h) + aoff + m * 2048 + k * 1024); } while (0)
; #define PG8_LDB(dst, b, h) do { _Pragma("unroll") for (int n = 0; n < 2; ++n) _Pragma("unroll") for (int k = 0; k < 2; ++k) dst[n][k] = *(const PG8_LAS bf16x8*)(lds + PG8_SB(b, h) + boff + n * 2048 + k * 1024); } while (0)
; #define PG8_MMA(ai, bj, At, Bt) do { __builtin_amdgcn_s_setprio(1); _Pragma("unroll") for (int m = 0; m < 4; ++m) _Pragma("unroll") for (int n = 0; n < 2; ++n) _Pragma("unroll") for (int k = 0; k < 2; ++k) \
;         acc[ai][bj][m][n] = __builtin_amdgcn_mfma_f32_16x16x32_bf16(Bt[n][k], At[m][k], acc[ai][bj][m][n], 0, 0, 0); __builtin_amdgcn_s_setprio(0); } while (0)
; #define PG8_WAIT_V(n) asm volatile("s_waitcnt vmcnt(" #n ")" ::: "memory")
; #define PG8_BAR __builtin_amdgcn_s_barrier()
; template <class Epi, class Sched, bool ALIGN_EPI = false, bool SP2 = false>
; __device__ __forceinline__ void gemm_phase(PG8_LAS unsigned char* lds, const Gemm g, const Sched& S, const Epi& E, const int wid) {
;     ...
;         for (int t = 0; t < nt; t += 2) {
;             const bool last = (t == nt - 2);
;             const char* a1 = cA + (size_t)(t + 1) * kstep;
;             const char* a2 = last ? nA : cA + (size_t)(t + 2) * kstep; const char* b2 = last ? nB : cB + (size_t)(t + 2) * kstep;
;             const char* a3 = a2 + kstep; const char* b3 = b2 + kstep;
;             if (last && has_next) S.a_ready(nxt);
;             if constexpr (SP2) {
;             PG8_LDB(B0, 0, 0); PG8_LDB(B1, 0, 1); PG8_SCHED; PG8_LDA(At, 0, 0); PG8_STAGE(PG8_SA(1, 1), a1 + hstep, voffA);
;             PG8_WAIT_V(8); PG8_WAIT_L(0); PG8_BAR; PG8_MMA(0, 0, At, B0); PG8_MMA(0, 1, At, B1); PG8_BAR; PG8_SCHED;
;             PG8_LDA(At, 0, 1); PG8_STAGE(PG8_SB(0, 0), b2, voffB); PG8_STAGE(PG8_SB(0, 1), b2 + hstep, voffB); PG8_STAGE(PG8_SA(0, 0), a2, voffA);
;             PG8_WAIT_V(8); PG8_WAIT_L(0); PG8_BAR; PG8_MMA(1, 0, At, B0); PG8_MMA(1, 1, At, B1); PG8_BAR; PG8_SCHED;
.LBB0_405:
	s_add_u32 s26, s24, 0xfffe0080
	s_addc_u32 s27, s25, -1
	s_add_i32 s40, 0, 0x10000
	s_cmp_eq_u32 s84, 4
	s_cselect_b32 s29, s19, s27
	s_cselect_b32 s28, s64, s26
	v_add_u32_e32 v147, s40, v145
	s_cselect_b32 s27, s17, s67
	s_cselect_b32 s26, s65, s66
	s_add_i32 s42, 0, 0x14000
	ds_read_b128 v[140:143], v147
	ds_read_b128 v[148:151], v147 offset:1024
	ds_read_b128 v[152:155], v147 offset:2048
	ds_read_b128 v[156:159], v147 offset:3072
	v_add_u32_e32 v147, s42, v145
	ds_read_b128 v[160:163], v147
	ds_read_b128 v[164:167], v147 offset:1024
	ds_read_b128 v[168:171], v147 offset:2048
	ds_read_b128 v[172:175], v147 offset:3072
	v_lshl_add_u64 v[200:201], s[24:25], 0, v[136:137]
	s_add_i32 m0, s15, 0xc000
	ds_read_b128 v[176:179], v146
	ds_read_b128 v[180:183], v146 offset:1024
	ds_read_b128 v[184:187], v146 offset:2048
	ds_read_b128 v[188:191], v146 offset:3072
	ds_read_b128 v[192:195], v146 offset:4096
	ds_read_b128 v[212:215], v146 offset:5120
	ds_read_b128 v[216:219], v146 offset:6144
	ds_read_b128 v[220:223], v146 offset:7168
	global_load_lds_dwordx4 v[200:201], off
	v_lshl_add_u64 v[200:201], s[24:25], 0, v[138:139]
	s_add_i32 m0, s15, 0xe000
	s_nop 0
	global_load_lds_dwordx4 v[200:201], off
	s_waitcnt vmcnt(8)
	s_waitcnt lgkmcnt(0)
	s_setprio 1
	s_barrier
	v_mfma_f32_16x16x32_bf16 v[126:129], v[140:143], v[176:179], v[126:129]
	v_mfma_f32_16x16x32_bf16 v[122:125], v[152:155], v[176:179], v[122:125]
	v_mfma_f32_16x16x32_bf16 v[118:121], v[140:143], v[184:187], v[118:121]
	v_mfma_f32_16x16x32_bf16 v[110:113], v[152:155], v[184:187], v[110:113]
	v_mfma_f32_16x16x32_bf16 v[102:105], v[140:143], v[192:195], v[102:105]
	v_mfma_f32_16x16x32_bf16 v[94:97], v[152:155], v[192:195], v[94:97]
	v_mfma_f32_16x16x32_bf16 v[86:89], v[140:143], v[216:219], v[86:89]
	v_mfma_f32_16x16x32_bf16 v[78:81], v[152:155], v[216:219], v[78:81]
	v_mfma_f32_16x16x32_bf16 v[126:129], v[148:151], v[180:183], v[126:129]
	v_mfma_f32_16x16x32_bf16 v[122:125], v[156:159], v[180:183], v[122:125]
	v_mfma_f32_16x16x32_bf16 v[118:121], v[148:151], v[188:191], v[118:121]
	v_mfma_f32_16x16x32_bf16 v[110:113], v[156:159], v[188:191], v[110:113]
	v_mfma_f32_16x16x32_bf16 v[102:105], v[148:151], v[212:215], v[102:105]
	v_mfma_f32_16x16x32_bf16 v[94:97], v[156:159], v[212:215], v[94:97]
	v_mfma_f32_16x16x32_bf16 v[86:89], v[148:151], v[220:223], v[86:89]
	v_mfma_f32_16x16x32_bf16 v[78:81], v[156:159], v[220:223], v[78:81]
	s_setprio 0
	s_setprio 1
	v_mfma_f32_16x16x32_bf16 v[114:117], v[160:163], v[176:179], v[114:117]
	v_mfma_f32_16x16x32_bf16 v[106:109], v[168:171], v[176:179], v[106:109]
	v_mfma_f32_16x16x32_bf16 v[98:101], v[160:163], v[184:187], v[98:101]
	v_mfma_f32_16x16x32_bf16 v[90:93], v[168:171], v[184:187], v[90:93]
	v_mfma_f32_16x16x32_bf16 v[82:85], v[160:163], v[192:195], v[82:85]
	v_mfma_f32_16x16x32_bf16 v[74:77], v[168:171], v[192:195], v[74:77]
	v_mfma_f32_16x16x32_bf16 v[70:73], v[160:163], v[216:219], v[70:73]
	v_mfma_f32_16x16x32_bf16 v[66:69], v[168:171], v[216:219], v[66:69]
	v_mfma_f32_16x16x32_bf16 v[114:117], v[164:167], v[180:183], v[114:117]
	v_mfma_f32_16x16x32_bf16 v[106:109], v[172:175], v[180:183], v[106:109]
	v_mfma_f32_16x16x32_bf16 v[98:101], v[164:167], v[188:191], v[98:101]
	v_mfma_f32_16x16x32_bf16 v[90:93], v[172:175], v[188:191], v[90:93]
	v_mfma_f32_16x16x32_bf16 v[82:85], v[164:167], v[212:215], v[82:85]
	v_mfma_f32_16x16x32_bf16 v[74:77], v[172:175], v[212:215], v[74:77]
	v_mfma_f32_16x16x32_bf16 v[70:73], v[164:167], v[220:223], v[70:73]
	v_mfma_f32_16x16x32_bf16 v[66:69], v[172:175], v[220:223], v[66:69]
	s_setprio 0
	s_barrier
	s_add_i32 s40, s40, s45
	v_lshl_add_u64 v[200:201], s[26:27], 0, v[0:1]
	s_mov_b32 m0, s40
	ds_read_b128 v[176:179], v146 offset:16384
	ds_read_b128 v[180:183], v146 offset:17408
	ds_read_b128 v[184:187], v146 offset:18432
	ds_read_b128 v[188:191], v146 offset:19456
	ds_read_b128 v[192:195], v146 offset:20480
	ds_read_b128 v[212:215], v146 offset:21504
	ds_read_b128 v[216:219], v146 offset:22528
	ds_read_b128 v[220:223], v146 offset:23552
	global_load_lds_dwordx4 v[200:201], off
	s_add_i32 m0, s40, 0x2000
	s_add_u32 s40, s26, 0x20000
	v_lshl_add_u64 v[202:203], s[26:27], 0, v[130:131]
	s_addc_u32 s41, s27, 0
	s_add_i32 s42, s42, s45
	global_load_lds_dwordx4 v[202:203], off
	v_lshl_add_u64 v[208:209], s[40:41], 0, v[0:1]
	s_mov_b32 m0, s42
	v_lshl_add_u64 v[210:211], s[28:29], 0, v[132:133]
	global_load_lds_dwordx4 v[208:209], off
	v_lshl_add_u64 v[208:209], s[40:41], 0, v[130:131]
	s_add_i32 m0, s42, 0x2000
	s_nop 0
	global_load_lds_dwordx4 v[208:209], off
	v_lshl_add_u64 v[208:209], s[28:29], 0, v[134:135]
	s_mov_b32 m0, s15
	s_nop 0
	global_load_lds_dwordx4 v[208:209], off
	s_mov_b32 m0, s36
	s_nop 0
	global_load_lds_dwordx4 v[210:211], off
	s_waitcnt vmcnt(8)
	s_waitcnt lgkmcnt(0)
	s_setprio 1
	s_barrier
; #define PG8_STAGE(bufoff, gbase, voff) do { _Pragma("unroll") for (int _i = 0; _i < 2; ++_i) \
;         __builtin_amdgcn_global_load_lds((const unsigned*)((const char*)(gbase) + (voff)[_i]), (PG8_LAS unsigned*)(lds + (bufoff) + ldsw + _i * 8192), 16, 0, 0); } while (0)
; #define PG8_LDA(dst, b, h) do { _Pragma("unroll") for (int m = 0; m < 4; ++m) _Pragma("unroll") for (int k = 0; k < 2; ++k) dst[m][k] = *(const PG8_LAS bf16x8*)(lds + PG8_SA(b, h) + aoff + m * 2048 + k * 1024); } while (0)
; #define PG8_LDB(dst, b, h) do { _Pragma("unroll") for (int n = 0; n < 2; ++n) _Pragma("unroll") for (int k = 0; k < 2; ++k) dst[n][k] = *(const PG8_LAS bf16x8*)(lds + PG8_SB(b, h) + boff + n * 2048 + k * 1024); } while (0)
; #define PG8_MMA(ai, bj, At, Bt) do { __builtin_amdgcn_s_setprio(1); _Pragma("unroll") for (int m = 0; m < 4; ++m) _Pragma("unroll") for (int n = 0; n < 2; ++n) _Pragma("unroll") for (int k = 0; k < 2; ++k) \
;         acc[ai][bj][m][n] = __builtin_amdgcn_mfma_f32_16x16x32_bf16(Bt[n][k], At[m][k], acc[ai][bj][m][n], 0, 0, 0); __builtin_amdgcn_s_setprio(0); } while (0)
; #define PG8_WAIT_V(n) asm volatile("s_waitcnt vmcnt(" #n ")" ::: "memory")
; #define PG8_WAIT_L(n) asm volatile("s_waitcnt lgkmcnt(" #n ")" ::: "memory")
; #define PG8_BAR __builtin_amdgcn_s_barrier()
; #define PG8_SCHED __builtin_amdgcn_sched_barrier(0)
; template <class Epi, class Sched, bool ALIGN_EPI = false, bool SP2 = false>
; __device__ __forceinline__ void gemm_phase(PG8_LAS unsigned char* lds, const Gemm g, const Sched& S, const Epi& E, const int wid) {
;     ...
;             PG8_WAIT_V(8); PG8_WAIT_L(0); PG8_BAR; PG8_MMA(1, 0, At, B0); PG8_MMA(1, 1, At, B1); PG8_BAR; PG8_SCHED;
;             PG8_LDB(B0, 1, 0); PG8_LDB(B1, 1, 1); PG8_SCHED; PG8_LDA(At, 1, 0); PG8_STAGE(PG8_SA(0, 1), a2 + hstep, voffA);
;             PG8_WAIT_V(8); PG8_WAIT_L(0); PG8_BAR; PG8_MMA(0, 0, At, B0); PG8_MMA(0, 1, At, B1); PG8_BAR; PG8_SCHED;
	v_mfma_f32_16x16x32_bf16 v[62:65], v[140:143], v[176:179], v[62:65]
	v_mfma_f32_16x16x32_bf16 v[58:61], v[152:155], v[176:179], v[58:61]
	v_mfma_f32_16x16x32_bf16 v[54:57], v[140:143], v[184:187], v[54:57]
	v_mfma_f32_16x16x32_bf16 v[46:49], v[152:155], v[184:187], v[46:49]
	v_mfma_f32_16x16x32_bf16 v[38:41], v[140:143], v[192:195], v[38:41]
	v_mfma_f32_16x16x32_bf16 v[30:33], v[152:155], v[192:195], v[30:33]
	v_mfma_f32_16x16x32_bf16 v[22:25], v[140:143], v[216:219], v[22:25]
	v_mfma_f32_16x16x32_bf16 v[14:17], v[152:155], v[216:219], v[14:17]
	v_mfma_f32_16x16x32_bf16 v[62:65], v[148:151], v[180:183], v[62:65]
	v_mfma_f32_16x16x32_bf16 v[58:61], v[156:159], v[180:183], v[58:61]
	v_mfma_f32_16x16x32_bf16 v[54:57], v[148:151], v[188:191], v[54:57]
	v_mfma_f32_16x16x32_bf16 v[46:49], v[156:159], v[188:191], v[46:49]
	v_mfma_f32_16x16x32_bf16 v[38:41], v[148:151], v[212:215], v[38:41]
	v_mfma_f32_16x16x32_bf16 v[30:33], v[156:159], v[212:215], v[30:33]
	v_mfma_f32_16x16x32_bf16 v[22:25], v[148:151], v[220:223], v[22:25]
	v_mfma_f32_16x16x32_bf16 v[14:17], v[156:159], v[220:223], v[14:17]
	s_setprio 0
	s_setprio 1
	v_mfma_f32_16x16x32_bf16 v[50:53], v[160:163], v[176:179], v[50:53]
	v_mfma_f32_16x16x32_bf16 v[42:45], v[168:171], v[176:179], v[42:45]
	v_mfma_f32_16x16x32_bf16 v[34:37], v[160:163], v[184:187], v[34:37]
	v_mfma_f32_16x16x32_bf16 v[26:29], v[168:171], v[184:187], v[26:29]
	v_mfma_f32_16x16x32_bf16 v[18:21], v[160:163], v[192:195], v[18:21]
	v_mfma_f32_16x16x32_bf16 v[10:13], v[168:171], v[192:195], v[10:13]
	v_mfma_f32_16x16x32_bf16 v[6:9], v[160:163], v[216:219], v[6:9]
	v_mfma_f32_16x16x32_bf16 v[2:5], v[168:171], v[216:219], v[2:5]
	v_mfma_f32_16x16x32_bf16 v[50:53], v[164:167], v[180:183], v[50:53]
	v_mfma_f32_16x16x32_bf16 v[42:45], v[172:175], v[180:183], v[42:45]
	v_mfma_f32_16x16x32_bf16 v[34:37], v[164:167], v[188:191], v[34:37]
	v_mfma_f32_16x16x32_bf16 v[26:29], v[172:175], v[188:191], v[26:29]
	v_mfma_f32_16x16x32_bf16 v[18:21], v[164:167], v[212:215], v[18:21]
	v_mfma_f32_16x16x32_bf16 v[10:13], v[172:175], v[212:215], v[10:13]
	v_mfma_f32_16x16x32_bf16 v[6:9], v[164:167], v[220:223], v[6:9]
	v_mfma_f32_16x16x32_bf16 v[2:5], v[172:175], v[220:223], v[2:5]
	s_setprio 0
	s_barrier
	s_add_i32 s40, 0, 0x18000
	v_add_u32_e32 v147, s40, v145
	s_add_i32 s41, 0, 0x1c000
	ds_read_b128 v[140:143], v147
	ds_read_b128 v[148:151], v147 offset:1024
	ds_read_b128 v[152:155], v147 offset:2048
	ds_read_b128 v[156:159], v147 offset:3072
	v_add_u32_e32 v147, s41, v145
	ds_read_b128 v[160:163], v147
	ds_read_b128 v[164:167], v147 offset:1024
	ds_read_b128 v[168:171], v147 offset:2048
	ds_read_b128 v[172:175], v147 offset:3072
	s_add_u32 s28, s28, 0x20000
	s_addc_u32 s29, s29, 0
	s_mov_b32 m0, s37
	v_lshl_add_u64 v[224:225], s[28:29], 0, v[134:135]
	ds_read_b128 v[176:179], v146 offset:32768
	ds_read_b128 v[180:183], v146 offset:33792
	ds_read_b128 v[184:187], v146 offset:34816
	ds_read_b128 v[188:191], v146 offset:35840
	ds_read_b128 v[192:195], v146 offset:36864
	ds_read_b128 v[212:215], v146 offset:37888
	ds_read_b128 v[216:219], v146 offset:38912
	ds_read_b128 v[220:223], v146 offset:39936
	global_load_lds_dwordx4 v[224:225], off
	v_lshl_add_u64 v[224:225], s[28:29], 0, v[132:133]
	s_mov_b32 m0, s38
	s_nop 0
	global_load_lds_dwordx4 v[224:225], off
	s_waitcnt vmcnt(8)
	s_waitcnt lgkmcnt(0)
	s_setprio 1
	s_barrier
	v_mfma_f32_16x16x32_bf16 v[126:129], v[140:143], v[176:179], v[126:129]
	v_mfma_f32_16x16x32_bf16 v[122:125], v[152:155], v[176:179], v[122:125]
	v_mfma_f32_16x16x32_bf16 v[118:121], v[140:143], v[184:187], v[118:121]
	v_mfma_f32_16x16x32_bf16 v[110:113], v[152:155], v[184:187], v[110:113]
	v_mfma_f32_16x16x32_bf16 v[102:105], v[140:143], v[192:195], v[102:105]
	v_mfma_f32_16x16x32_bf16 v[94:97], v[152:155], v[192:195], v[94:97]
	v_mfma_f32_16x16x32_bf16 v[86:89], v[140:143], v[216:219], v[86:89]
	v_mfma_f32_16x16x32_bf16 v[78:81], v[152:155], v[216:219], v[78:81]
	v_mfma_f32_16x16x32_bf16 v[126:129], v[148:151], v[180:183], v[126:129]
	v_mfma_f32_16x16x32_bf16 v[122:125], v[156:159], v[180:183], v[122:125]
	v_mfma_f32_16x16x32_bf16 v[118:121], v[148:151], v[188:191], v[118:121]
	v_mfma_f32_16x16x32_bf16 v[110:113], v[156:159], v[188:191], v[110:113]
	v_mfma_f32_16x16x32_bf16 v[102:105], v[148:151], v[212:215], v[102:105]
	v_mfma_f32_16x16x32_bf16 v[94:97], v[156:159], v[212:215], v[94:97]
	v_mfma_f32_16x16x32_bf16 v[86:89], v[148:151], v[220:223], v[86:89]
	v_mfma_f32_16x16x32_bf16 v[78:81], v[156:159], v[220:223], v[78:81]
	s_setprio 0
	s_setprio 1
	v_mfma_f32_16x16x32_bf16 v[114:117], v[160:163], v[176:179], v[114:117]
	v_mfma_f32_16x16x32_bf16 v[106:109], v[168:171], v[176:179], v[106:109]
	v_mfma_f32_16x16x32_bf16 v[98:101], v[160:163], v[184:187], v[98:101]
	v_mfma_f32_16x16x32_bf16 v[90:93], v[168:171], v[184:187], v[90:93]
	v_mfma_f32_16x16x32_bf16 v[82:85], v[160:163], v[192:195], v[82:85]
	v_mfma_f32_16x16x32_bf16 v[74:77], v[168:171], v[192:195], v[74:77]
	v_mfma_f32_16x16x32_bf16 v[70:73], v[160:163], v[216:219], v[70:73]
	v_mfma_f32_16x16x32_bf16 v[66:69], v[168:171], v[216:219], v[66:69]
	v_mfma_f32_16x16x32_bf16 v[114:117], v[164:167], v[180:183], v[114:117]
	v_mfma_f32_16x16x32_bf16 v[106:109], v[172:175], v[180:183], v[106:109]
	v_mfma_f32_16x16x32_bf16 v[98:101], v[164:167], v[188:191], v[98:101]
	v_mfma_f32_16x16x32_bf16 v[90:93], v[172:175], v[188:191], v[90:93]
	v_mfma_f32_16x16x32_bf16 v[82:85], v[164:167], v[212:215], v[82:85]
	v_mfma_f32_16x16x32_bf16 v[74:77], v[172:175], v[212:215], v[74:77]
	v_mfma_f32_16x16x32_bf16 v[70:73], v[164:167], v[220:223], v[70:73]
	v_mfma_f32_16x16x32_bf16 v[66:69], v[172:175], v[220:223], v[66:69]
	s_setprio 0
	s_barrier
; #define PG8_STAGE(bufoff, gbase, voff) do { _Pragma("unroll") for (int _i = 0; _i < 2; ++_i) \
;         __builtin_amdgcn_global_load_lds((const unsigned*)((const char*)(gbase) + (voff)[_i]), (PG8_LAS unsigned*)(lds + (bufoff) + ldsw + _i * 8192), 16, 0, 0); } while (0)
; #define PG8_LDA(dst, b, h) do { _Pragma("unroll") for (int m = 0; m < 4; ++m) _Pragma("unroll") for (int k = 0; k < 2; ++k) dst[m][k] = *(const PG8_LAS bf16x8*)(lds + PG8_SA(b, h) + aoff + m * 2048 + k * 1024); } while (0)
; #define PG8_MMA(ai, bj, At, Bt) do { __builtin_amdgcn_s_setprio(1); _Pragma("unroll") for (int m = 0; m < 4; ++m) _Pragma("unroll") for (int n = 0; n < 2; ++n) _Pragma("unroll") for (int k = 0; k < 2; ++k) \
;         acc[ai][bj][m][n] = __builtin_amdgcn_mfma_f32_16x16x32_bf16(Bt[n][k], At[m][k], acc[ai][bj][m][n], 0, 0, 0); __builtin_amdgcn_s_setprio(0); } while (0)
; #define PG8_WAIT_V(n) asm volatile("s_waitcnt vmcnt(" #n ")" ::: "memory")
; #define PG8_WAIT_L(n) asm volatile("s_waitcnt lgkmcnt(" #n ")" ::: "memory")
; #define PG8_BAR __builtin_amdgcn_s_barrier()
; #define PG8_SCHED __builtin_amdgcn_sched_barrier(0)
; template <class Epi, class Sched, bool ALIGN_EPI = false, bool SP2 = false>
; __device__ __forceinline__ void gemm_phase(PG8_LAS unsigned char* lds, const Gemm g, const Sched& S, const Epi& E, const int wid) {
;     ...
;         for (int t = 0; t < nt; t += 2) {
;     ...
;             PG8_LDA(At, 1, 1); PG8_STAGE(PG8_SB(1, 0), b3, voffB); PG8_STAGE(PG8_SB(1, 1), b3 + hstep, voffB); PG8_STAGE(PG8_SA(1, 0), a3, voffA);
;             PG8_WAIT_V(8); PG8_WAIT_L(0); PG8_BAR; PG8_MMA(1, 0, At, B0); PG8_MMA(1, 1, At, B1); PG8_BAR; PG8_SCHED;
	s_add_i32 s28, s40, s45
	v_lshl_add_u64 v[200:201], v[200:201], 0, s[58:59]
	s_mov_b32 m0, s28
	ds_read_b128 v[176:179], v146 offset:49152
	ds_read_b128 v[180:183], v146 offset:50176
	ds_read_b128 v[184:187], v146 offset:51200
	ds_read_b128 v[188:191], v146 offset:52224
	ds_read_b128 v[192:195], v146 offset:53248
	ds_read_b128 v[212:215], v146 offset:54272
	ds_read_b128 v[216:219], v146 offset:55296
	ds_read_b128 v[220:223], v146 offset:56320
	global_load_lds_dwordx4 v[200:201], off
	s_add_i32 m0, s28, 0x2000
	s_add_u32 s26, s26, 0x20080
	v_lshl_add_u64 v[200:201], v[202:203], 0, s[58:59]
	s_addc_u32 s27, s27, 0
	s_add_i32 s28, s41, s45
	global_load_lds_dwordx4 v[200:201], off
	v_lshl_add_u64 v[200:201], s[26:27], 0, v[0:1]
	s_mov_b32 m0, s28
	s_nop 0
	global_load_lds_dwordx4 v[200:201], off
	v_lshl_add_u64 v[200:201], s[26:27], 0, v[130:131]
	s_add_i32 m0, s28, 0x2000
	s_nop 0
	global_load_lds_dwordx4 v[200:201], off
	v_lshl_add_u64 v[200:201], v[208:209], 0, s[58:59]
	s_mov_b32 m0, s39
	s_nop 0
	global_load_lds_dwordx4 v[200:201], off
	v_lshl_add_u64 v[200:201], v[210:211], 0, s[58:59]
	s_mov_b32 m0, s46
	s_nop 0
	global_load_lds_dwordx4 v[200:201], off
	s_waitcnt vmcnt(8)
	s_waitcnt lgkmcnt(0)
	s_setprio 1
	s_barrier
	v_mfma_f32_16x16x32_bf16 v[62:65], v[140:143], v[176:179], v[62:65]
	v_mfma_f32_16x16x32_bf16 v[58:61], v[152:155], v[176:179], v[58:61]
	v_mfma_f32_16x16x32_bf16 v[54:57], v[140:143], v[184:187], v[54:57]
	v_mfma_f32_16x16x32_bf16 v[46:49], v[152:155], v[184:187], v[46:49]
	v_mfma_f32_16x16x32_bf16 v[38:41], v[140:143], v[192:195], v[38:41]
	v_mfma_f32_16x16x32_bf16 v[30:33], v[152:155], v[192:195], v[30:33]
	v_mfma_f32_16x16x32_bf16 v[22:25], v[140:143], v[216:219], v[22:25]
	v_mfma_f32_16x16x32_bf16 v[14:17], v[152:155], v[216:219], v[14:17]
	v_mfma_f32_16x16x32_bf16 v[62:65], v[148:151], v[180:183], v[62:65]
	v_mfma_f32_16x16x32_bf16 v[58:61], v[156:159], v[180:183], v[58:61]
	v_mfma_f32_16x16x32_bf16 v[54:57], v[148:151], v[188:191], v[54:57]
	v_mfma_f32_16x16x32_bf16 v[46:49], v[156:159], v[188:191], v[46:49]
	v_mfma_f32_16x16x32_bf16 v[38:41], v[148:151], v[212:215], v[38:41]
	v_mfma_f32_16x16x32_bf16 v[30:33], v[156:159], v[212:215], v[30:33]
	v_mfma_f32_16x16x32_bf16 v[22:25], v[148:151], v[220:223], v[22:25]
	v_mfma_f32_16x16x32_bf16 v[14:17], v[156:159], v[220:223], v[14:17]
	s_setprio 0
	s_setprio 1
	v_mfma_f32_16x16x32_bf16 v[50:53], v[160:163], v[176:179], v[50:53]
	v_mfma_f32_16x16x32_bf16 v[42:45], v[168:171], v[176:179], v[42:45]
	v_mfma_f32_16x16x32_bf16 v[34:37], v[160:163], v[184:187], v[34:37]
	v_mfma_f32_16x16x32_bf16 v[26:29], v[168:171], v[184:187], v[26:29]
	v_mfma_f32_16x16x32_bf16 v[18:21], v[160:163], v[192:195], v[18:21]
	v_mfma_f32_16x16x32_bf16 v[10:13], v[168:171], v[192:195], v[10:13]
	v_mfma_f32_16x16x32_bf16 v[6:9], v[160:163], v[216:219], v[6:9]
	v_mfma_f32_16x16x32_bf16 v[2:5], v[168:171], v[216:219], v[2:5]
	v_mfma_f32_16x16x32_bf16 v[50:53], v[164:167], v[180:183], v[50:53]
	v_mfma_f32_16x16x32_bf16 v[42:45], v[172:175], v[180:183], v[42:45]
	v_mfma_f32_16x16x32_bf16 v[34:37], v[164:167], v[188:191], v[34:37]
	v_mfma_f32_16x16x32_bf16 v[26:29], v[172:175], v[188:191], v[26:29]
	v_mfma_f32_16x16x32_bf16 v[18:21], v[164:167], v[212:215], v[18:21]
	v_mfma_f32_16x16x32_bf16 v[10:13], v[172:175], v[212:215], v[10:13]
	v_mfma_f32_16x16x32_bf16 v[6:9], v[164:167], v[220:223], v[6:9]
	v_mfma_f32_16x16x32_bf16 v[2:5], v[172:175], v[220:223], v[2:5]
	s_setprio 0
	s_barrier
	s_add_i32 s84, s84, 2
	s_add_u32 s24, s24, 0x100
	s_addc_u32 s25, s25, 0
	s_add_u32 s66, s66, 0x100
	s_addc_u32 s67, s67, 0
	s_cmp_gt_u32 s84, 5
	s_cbranch_scc0 .LBB0_405
	s_and_b64 vcc, exec, s[12:13]
	s_cbranch_vccz .LBB0_408
	s_barrier

; #define PG8_STAGE(bufoff, gbase, voff) do { _Pragma("unroll") for (int _i = 0; _i < 2; ++_i) \
;         __builtin_amdgcn_global_load_lds((const unsigned*)((const char*)(gbase) + (voff)[_i]), (PG8_LAS unsigned*)(lds + (bufoff) + ldsw + _i * 8192), 16, 0, 0); } while (0)
; #define PG8_LDA(dst, b, h) do { _Pragma("unroll") for (int m = 0; m < 4; ++m) _Pragma("unroll") for (int k = 0; k < 2; ++k) dst[m][k] = *(const PG8_LAS bf16x8*)(lds + PG8_SA(b, h) + aoff + m * 2048 + k * 1024); } while (0)
; #define PG8_LDB(dst, b, h) do { _Pragma("unroll") for (int n = 0; n < 2; ++n) _Pragma("unroll") for (int k = 0; k < 2; ++k) dst[n][k] = *(const PG8_LAS bf16x8*)(lds + PG8_SB(b, h) + boff + n * 2048 + k * 1024); } while (0)
; #define PG8_MMA(ai, bj, At, Bt) do { __builtin_amdgcn_s_setprio(1); _Pragma("unroll") for (int m = 0; m < 4; ++m) _Pragma("unroll") for (int n = 0; n < 2; ++n) _Pragma("unroll") for (int k = 0; k < 2; ++k) \
;         acc[ai][bj][m][n] = __builtin_amdgcn_mfma_f32_16x16x32_bf16(Bt[n][k], At[m][k], acc[ai][bj][m][n], 0, 0, 0); __builtin_amdgcn_s_setprio(0); } while (0)
; #define PG8_WAIT_V(n) asm volatile("s_waitcnt vmcnt(" #n ")" ::: "memory")
; #define PG8_BAR __builtin_amdgcn_s_barrier()
; template <class Epi, class Sched, bool ALIGN_EPI = false, bool SP2 = false>
; __device__ __forceinline__ void gemm_phase(PG8_LAS unsigned char* lds, const Gemm g, const Sched& S, const Epi& E, const int wid) {
;     ...
;         for (int t = 0; t < nt; t += 2) {
;             const bool last = (t == nt - 2);
;             const char* a1 = cA + (size_t)(t + 1) * kstep;
;             const char* a2 = last ? nA : cA + (size_t)(t + 2) * kstep; const char* b2 = last ? nB : cB + (size_t)(t + 2) * kstep;
;             const char* a3 = a2 + kstep; const char* b3 = b2 + kstep;
;             if (last && has_next) S.a_ready(nxt);
;             if constexpr (SP2) {
;             PG8_LDB(B0, 0, 0); PG8_LDB(B1, 0, 1); PG8_SCHED; PG8_LDA(At, 0, 0); PG8_STAGE(PG8_SA(1, 1), a1 + hstep, voffA);
;             PG8_WAIT_V(8); PG8_WAIT_L(0); PG8_BAR; PG8_MMA(0, 0, At, B0); PG8_MMA(0, 1, At, B1); PG8_BAR; PG8_SCHED;
;             PG8_LDA(At, 0, 1); PG8_STAGE(PG8_SB(0, 0), b2, voffB); PG8_STAGE(PG8_SB(0, 1), b2 + hstep, voffB); PG8_STAGE(PG8_SA(0, 0), a2, voffA);
;             PG8_WAIT_V(8); PG8_WAIT_L(0); PG8_BAR; PG8_MMA(1, 0, At, B0); PG8_MMA(1, 1, At, B1); PG8_BAR; PG8_SCHED;
.LBB0_429:
	s_add_u32 s37, s24, s36
	s_addc_u32 s40, s25, 0
	s_add_u32 s41, s37, 0x100
	s_addc_u32 s42, s40, 0
	s_and_b64 s[38:39], s[34:35], exec
	s_cselect_b32 s39, s21, s42
	s_cselect_b32 s38, s94, s41
	s_add_u32 s36, s22, s36
	s_addc_u32 s41, s23, 0
	s_add_u32 s36, s36, 0x100
	s_addc_u32 s41, s41, 0
	s_add_i32 s63, 0, 0x10000
	s_and_b64 s[34:35], s[34:35], exec
	s_cselect_b32 s87, s19, s41
	s_cselect_b32 s86, s95, s36
	s_add_i32 s35, 0, 0x14000
	s_add_u32 s90, s37, 0x10080
	s_addc_u32 s91, s40, 0
	s_add_i32 s62, s63, s45
	s_add_i32 m0, s17, 0xc000
	s_add_i32 s97, s17, 0xe000
	s_add_i32 s54, s62, 0x2000
	v_add_u32_e32 v143, s63, v141
	s_add_u32 s88, s86, 0x10000
	ds_read_b128 v[136:139], v143
	ds_read_b128 v[144:147], v143 offset:1024
	ds_read_b128 v[148:151], v143 offset:2048
	ds_read_b128 v[152:155], v143 offset:3072
	v_add_u32_e32 v143, s35, v141
	s_addc_u32 s89, s87, 0
	s_add_i32 s61, s35, s45
	ds_read_b128 v[156:159], v143
	ds_read_b128 v[160:163], v143 offset:1024
	ds_read_b128 v[164:167], v143 offset:2048
	ds_read_b128 v[168:171], v143 offset:3072
	s_add_i32 s60, s61, 0x2000
	s_add_i32 s43, 0, 0x18000
	s_add_i32 s42, 0, 0x1c000
	s_add_u32 s36, s38, 0x10000
	s_addc_u32 s37, s39, 0
	s_add_i32 s41, s43, s45
	s_add_i32 s40, s41, 0x2000
	s_add_u32 s34, s86, 0x10080
	s_addc_u32 s35, s87, 0
	s_add_i32 s96, s42, s45
	s_add_i32 s63, s96, 0x2000
	v_lshl_add_u64 v[200:201], s[90:91], 0, v[130:131]
	ds_read_b128 v[172:175], v142
	ds_read_b128 v[176:179], v142 offset:1024
	ds_read_b128 v[180:183], v142 offset:2048
	ds_read_b128 v[184:187], v142 offset:3072
	ds_read_b128 v[188:191], v142 offset:4096
	ds_read_b128 v[192:195], v142 offset:5120
	ds_read_b128 v[212:215], v142 offset:6144
	ds_read_b128 v[216:219], v142 offset:7168
	global_load_lds_dwordx4 v[200:201], off
	v_lshl_add_u64 v[200:201], s[90:91], 0, v[132:133]
	s_mov_b32 m0, s97
	s_nop 0
	global_load_lds_dwordx4 v[200:201], off
	s_waitcnt vmcnt(8)
	s_waitcnt lgkmcnt(0)
	s_setprio 1
	s_barrier
	v_mfma_f32_16x16x32_bf16 v[126:129], v[136:139], v[172:175], v[126:129]
	v_mfma_f32_16x16x32_bf16 v[122:125], v[148:151], v[172:175], v[122:125]
	v_mfma_f32_16x16x32_bf16 v[118:121], v[136:139], v[180:183], v[118:121]
	v_mfma_f32_16x16x32_bf16 v[110:113], v[148:151], v[180:183], v[110:113]
	v_mfma_f32_16x16x32_bf16 v[102:105], v[136:139], v[188:191], v[102:105]
	v_mfma_f32_16x16x32_bf16 v[94:97], v[148:151], v[188:191], v[94:97]
	v_mfma_f32_16x16x32_bf16 v[86:89], v[136:139], v[212:215], v[86:89]
	v_mfma_f32_16x16x32_bf16 v[78:81], v[148:151], v[212:215], v[78:81]
	v_mfma_f32_16x16x32_bf16 v[126:129], v[144:147], v[176:179], v[126:129]
	v_mfma_f32_16x16x32_bf16 v[122:125], v[152:155], v[176:179], v[122:125]
	v_mfma_f32_16x16x32_bf16 v[118:121], v[144:147], v[184:187], v[118:121]
	v_mfma_f32_16x16x32_bf16 v[110:113], v[152:155], v[184:187], v[110:113]
	v_mfma_f32_16x16x32_bf16 v[102:105], v[144:147], v[192:195], v[102:105]
	v_mfma_f32_16x16x32_bf16 v[94:97], v[152:155], v[192:195], v[94:97]
	v_mfma_f32_16x16x32_bf16 v[86:89], v[144:147], v[216:219], v[86:89]
	v_mfma_f32_16x16x32_bf16 v[78:81], v[152:155], v[216:219], v[78:81]
	s_setprio 0
	s_setprio 1
	v_mfma_f32_16x16x32_bf16 v[114:117], v[156:159], v[172:175], v[114:117]
	v_mfma_f32_16x16x32_bf16 v[106:109], v[164:167], v[172:175], v[106:109]
	v_mfma_f32_16x16x32_bf16 v[98:101], v[156:159], v[180:183], v[98:101]
	v_mfma_f32_16x16x32_bf16 v[90:93], v[164:167], v[180:183], v[90:93]
	v_mfma_f32_16x16x32_bf16 v[82:85], v[156:159], v[188:191], v[82:85]
	v_mfma_f32_16x16x32_bf16 v[74:77], v[164:167], v[188:191], v[74:77]
	v_mfma_f32_16x16x32_bf16 v[70:73], v[156:159], v[212:215], v[70:73]
	v_mfma_f32_16x16x32_bf16 v[66:69], v[164:167], v[212:215], v[66:69]
	v_mfma_f32_16x16x32_bf16 v[114:117], v[160:163], v[176:179], v[114:117]
	v_mfma_f32_16x16x32_bf16 v[106:109], v[168:171], v[176:179], v[106:109]
	v_mfma_f32_16x16x32_bf16 v[98:101], v[160:163], v[184:187], v[98:101]
	v_mfma_f32_16x16x32_bf16 v[90:93], v[168:171], v[184:187], v[90:93]
	v_mfma_f32_16x16x32_bf16 v[82:85], v[160:163], v[192:195], v[82:85]
	v_mfma_f32_16x16x32_bf16 v[74:77], v[168:171], v[192:195], v[74:77]
	v_mfma_f32_16x16x32_bf16 v[70:73], v[160:163], v[216:219], v[70:73]
	v_mfma_f32_16x16x32_bf16 v[66:69], v[168:171], v[216:219], v[66:69]
	s_setprio 0
	s_barrier
	s_mov_b32 m0, s62
	v_lshl_add_u64 v[200:201], s[86:87], 0, v[0:1]
	ds_read_b128 v[172:175], v142 offset:16384
	ds_read_b128 v[176:179], v142 offset:17408
	ds_read_b128 v[180:183], v142 offset:18432
	ds_read_b128 v[184:187], v142 offset:19456
	ds_read_b128 v[188:191], v142 offset:20480
	ds_read_b128 v[192:195], v142 offset:21504
	ds_read_b128 v[212:215], v142 offset:22528
	ds_read_b128 v[216:219], v142 offset:23552
	global_load_lds_dwordx4 v[200:201], off
	v_lshl_add_u64 v[202:203], s[86:87], 0, v[134:135]
	s_mov_b32 m0, s54
	v_lshl_add_u64 v[208:209], s[88:89], 0, v[0:1]
	global_load_lds_dwordx4 v[202:203], off
	s_mov_b32 m0, s61
	v_lshl_add_u64 v[210:211], s[38:39], 0, v[132:133]
	global_load_lds_dwordx4 v[208:209], off
	v_lshl_add_u64 v[208:209], s[88:89], 0, v[134:135]
	s_mov_b32 m0, s60
	s_nop 0
	global_load_lds_dwordx4 v[208:209], off
	v_lshl_add_u64 v[208:209], s[38:39], 0, v[130:131]
	s_mov_b32 m0, s17
	s_nop 0
	global_load_lds_dwordx4 v[208:209], off
	s_mov_b32 m0, s50
	s_nop 0
	global_load_lds_dwordx4 v[210:211], off
	s_waitcnt vmcnt(8)
	s_waitcnt lgkmcnt(0)
	s_setprio 1
	s_barrier
; #define PG8_STAGE(bufoff, gbase, voff) do { _Pragma("unroll") for (int _i = 0; _i < 2; ++_i) \
;         __builtin_amdgcn_global_load_lds((const unsigned*)((const char*)(gbase) + (voff)[_i]), (PG8_LAS unsigned*)(lds + (bufoff) + ldsw + _i * 8192), 16, 0, 0); } while (0)
; #define PG8_LDA(dst, b, h) do { _Pragma("unroll") for (int m = 0; m < 4; ++m) _Pragma("unroll") for (int k = 0; k < 2; ++k) dst[m][k] = *(const PG8_LAS bf16x8*)(lds + PG8_SA(b, h) + aoff + m * 2048 + k * 1024); } while (0)
; #define PG8_LDB(dst, b, h) do { _Pragma("unroll") for (int n = 0; n < 2; ++n) _Pragma("unroll") for (int k = 0; k < 2; ++k) dst[n][k] = *(const PG8_LAS bf16x8*)(lds + PG8_SB(b, h) + boff + n * 2048 + k * 1024); } while (0)
; #define PG8_MMA(ai, bj, At, Bt) do { __builtin_amdgcn_s_setprio(1); _Pragma("unroll") for (int m = 0; m < 4; ++m) _Pragma("unroll") for (int n = 0; n < 2; ++n) _Pragma("unroll") for (int k = 0; k < 2; ++k) \
;         acc[ai][bj][m][n] = __builtin_amdgcn_mfma_f32_16x16x32_bf16(Bt[n][k], At[m][k], acc[ai][bj][m][n], 0, 0, 0); __builtin_amdgcn_s_setprio(0); } while (0)
; #define PG8_WAIT_V(n) asm volatile("s_waitcnt vmcnt(" #n ")" ::: "memory")
; #define PG8_WAIT_L(n) asm volatile("s_waitcnt lgkmcnt(" #n ")" ::: "memory")
; #define PG8_BAR __builtin_amdgcn_s_barrier()
; #define PG8_SCHED __builtin_amdgcn_sched_barrier(0)
; template <class Epi, class Sched, bool ALIGN_EPI = false, bool SP2 = false>
; __device__ __forceinline__ void gemm_phase(PG8_LAS unsigned char* lds, const Gemm g, const Sched& S, const Epi& E, const int wid) {
;     ...
;             PG8_WAIT_V(8); PG8_WAIT_L(0); PG8_BAR; PG8_MMA(1, 0, At, B0); PG8_MMA(1, 1, At, B1); PG8_BAR; PG8_SCHED;
;             PG8_LDB(B0, 1, 0); PG8_LDB(B1, 1, 1); PG8_SCHED; PG8_LDA(At, 1, 0); PG8_STAGE(PG8_SA(0, 1), a2 + hstep, voffA);
;             PG8_WAIT_V(8); PG8_WAIT_L(0); PG8_BAR; PG8_MMA(0, 0, At, B0); PG8_MMA(0, 1, At, B1); PG8_BAR; PG8_SCHED;
	v_mfma_f32_16x16x32_bf16 v[62:65], v[136:139], v[172:175], v[62:65]
	v_mfma_f32_16x16x32_bf16 v[58:61], v[148:151], v[172:175], v[58:61]
	v_mfma_f32_16x16x32_bf16 v[54:57], v[136:139], v[180:183], v[54:57]
	v_mfma_f32_16x16x32_bf16 v[46:49], v[148:151], v[180:183], v[46:49]
	v_mfma_f32_16x16x32_bf16 v[38:41], v[136:139], v[188:191], v[38:41]
	v_mfma_f32_16x16x32_bf16 v[30:33], v[148:151], v[188:191], v[30:33]
	v_mfma_f32_16x16x32_bf16 v[22:25], v[136:139], v[212:215], v[22:25]
	v_mfma_f32_16x16x32_bf16 v[14:17], v[148:151], v[212:215], v[14:17]
	v_mfma_f32_16x16x32_bf16 v[62:65], v[144:147], v[176:179], v[62:65]
	v_mfma_f32_16x16x32_bf16 v[58:61], v[152:155], v[176:179], v[58:61]
	v_mfma_f32_16x16x32_bf16 v[54:57], v[144:147], v[184:187], v[54:57]
	v_mfma_f32_16x16x32_bf16 v[46:49], v[152:155], v[184:187], v[46:49]
	v_mfma_f32_16x16x32_bf16 v[38:41], v[144:147], v[192:195], v[38:41]
	v_mfma_f32_16x16x32_bf16 v[30:33], v[152:155], v[192:195], v[30:33]
	v_mfma_f32_16x16x32_bf16 v[22:25], v[144:147], v[216:219], v[22:25]
	v_mfma_f32_16x16x32_bf16 v[14:17], v[152:155], v[216:219], v[14:17]
	s_setprio 0
	s_setprio 1
	v_mfma_f32_16x16x32_bf16 v[50:53], v[156:159], v[172:175], v[50:53]
	v_mfma_f32_16x16x32_bf16 v[42:45], v[164:167], v[172:175], v[42:45]
	v_mfma_f32_16x16x32_bf16 v[34:37], v[156:159], v[180:183], v[34:37]
	v_mfma_f32_16x16x32_bf16 v[26:29], v[164:167], v[180:183], v[26:29]
	v_mfma_f32_16x16x32_bf16 v[18:21], v[156:159], v[188:191], v[18:21]
	v_mfma_f32_16x16x32_bf16 v[10:13], v[164:167], v[188:191], v[10:13]
	v_mfma_f32_16x16x32_bf16 v[6:9], v[156:159], v[212:215], v[6:9]
	v_mfma_f32_16x16x32_bf16 v[2:5], v[164:167], v[212:215], v[2:5]
	v_mfma_f32_16x16x32_bf16 v[50:53], v[160:163], v[176:179], v[50:53]
	v_mfma_f32_16x16x32_bf16 v[42:45], v[168:171], v[176:179], v[42:45]
	v_mfma_f32_16x16x32_bf16 v[34:37], v[160:163], v[184:187], v[34:37]
	v_mfma_f32_16x16x32_bf16 v[26:29], v[168:171], v[184:187], v[26:29]
	v_mfma_f32_16x16x32_bf16 v[18:21], v[160:163], v[192:195], v[18:21]
	v_mfma_f32_16x16x32_bf16 v[10:13], v[168:171], v[192:195], v[10:13]
	v_mfma_f32_16x16x32_bf16 v[6:9], v[160:163], v[216:219], v[6:9]
	v_mfma_f32_16x16x32_bf16 v[2:5], v[168:171], v[216:219], v[2:5]
	s_setprio 0
	s_barrier
	v_add_u32_e32 v143, s43, v141
	ds_read_b128 v[136:139], v143
	ds_read_b128 v[144:147], v143 offset:1024
	ds_read_b128 v[148:151], v143 offset:2048
	ds_read_b128 v[152:155], v143 offset:3072
	v_add_u32_e32 v143, s42, v141
	ds_read_b128 v[156:159], v143
	ds_read_b128 v[160:163], v143 offset:1024
	ds_read_b128 v[164:167], v143 offset:2048
	ds_read_b128 v[168:171], v143 offset:3072
	s_mov_b32 m0, s55
	v_lshl_add_u64 v[220:221], s[36:37], 0, v[130:131]
	ds_read_b128 v[172:175], v142 offset:32768
	ds_read_b128 v[176:179], v142 offset:33792
	ds_read_b128 v[180:183], v142 offset:34816
	ds_read_b128 v[184:187], v142 offset:35840
	ds_read_b128 v[188:191], v142 offset:36864
	ds_read_b128 v[192:195], v142 offset:37888
	ds_read_b128 v[212:215], v142 offset:38912
	ds_read_b128 v[216:219], v142 offset:39936
	global_load_lds_dwordx4 v[220:221], off
	v_lshl_add_u64 v[220:221], s[36:37], 0, v[132:133]
	s_mov_b32 m0, s64
	s_nop 0
	global_load_lds_dwordx4 v[220:221], off
	s_waitcnt vmcnt(8)
	s_waitcnt lgkmcnt(0)
	s_setprio 1
	s_barrier
	v_mfma_f32_16x16x32_bf16 v[126:129], v[136:139], v[172:175], v[126:129]
	v_mfma_f32_16x16x32_bf16 v[122:125], v[148:151], v[172:175], v[122:125]
	v_mfma_f32_16x16x32_bf16 v[118:121], v[136:139], v[180:183], v[118:121]
	v_mfma_f32_16x16x32_bf16 v[110:113], v[148:151], v[180:183], v[110:113]
	v_mfma_f32_16x16x32_bf16 v[102:105], v[136:139], v[188:191], v[102:105]
	v_mfma_f32_16x16x32_bf16 v[94:97], v[148:151], v[188:191], v[94:97]
	v_mfma_f32_16x16x32_bf16 v[86:89], v[136:139], v[212:215], v[86:89]
	v_mfma_f32_16x16x32_bf16 v[78:81], v[148:151], v[212:215], v[78:81]
	v_mfma_f32_16x16x32_bf16 v[126:129], v[144:147], v[176:179], v[126:129]
	v_mfma_f32_16x16x32_bf16 v[122:125], v[152:155], v[176:179], v[122:125]
	v_mfma_f32_16x16x32_bf16 v[118:121], v[144:147], v[184:187], v[118:121]
	v_mfma_f32_16x16x32_bf16 v[110:113], v[152:155], v[184:187], v[110:113]
	v_mfma_f32_16x16x32_bf16 v[102:105], v[144:147], v[192:195], v[102:105]
	v_mfma_f32_16x16x32_bf16 v[94:97], v[152:155], v[192:195], v[94:97]
	v_mfma_f32_16x16x32_bf16 v[86:89], v[144:147], v[216:219], v[86:89]
	v_mfma_f32_16x16x32_bf16 v[78:81], v[152:155], v[216:219], v[78:81]
	s_setprio 0
	s_setprio 1
	v_mfma_f32_16x16x32_bf16 v[114:117], v[156:159], v[172:175], v[114:117]
	v_mfma_f32_16x16x32_bf16 v[106:109], v[164:167], v[172:175], v[106:109]
	v_mfma_f32_16x16x32_bf16 v[98:101], v[156:159], v[180:183], v[98:101]
	v_mfma_f32_16x16x32_bf16 v[90:93], v[164:167], v[180:183], v[90:93]
	v_mfma_f32_16x16x32_bf16 v[82:85], v[156:159], v[188:191], v[82:85]
	v_mfma_f32_16x16x32_bf16 v[74:77], v[164:167], v[188:191], v[74:77]
	v_mfma_f32_16x16x32_bf16 v[70:73], v[156:159], v[212:215], v[70:73]
	v_mfma_f32_16x16x32_bf16 v[66:69], v[164:167], v[212:215], v[66:69]
	v_mfma_f32_16x16x32_bf16 v[114:117], v[160:163], v[176:179], v[114:117]
	v_mfma_f32_16x16x32_bf16 v[106:109], v[168:171], v[176:179], v[106:109]
	v_mfma_f32_16x16x32_bf16 v[98:101], v[160:163], v[184:187], v[98:101]
	v_mfma_f32_16x16x32_bf16 v[90:93], v[168:171], v[184:187], v[90:93]
	v_mfma_f32_16x16x32_bf16 v[82:85], v[160:163], v[192:195], v[82:85]
	v_mfma_f32_16x16x32_bf16 v[74:77], v[168:171], v[192:195], v[74:77]
	v_mfma_f32_16x16x32_bf16 v[70:73], v[160:163], v[216:219], v[70:73]
	v_mfma_f32_16x16x32_bf16 v[66:69], v[168:171], v[216:219], v[66:69]
	s_setprio 0
	s_barrier
; #define PG8_STAGE(bufoff, gbase, voff) do { _Pragma("unroll") for (int _i = 0; _i < 2; ++_i) \
;         __builtin_amdgcn_global_load_lds((const unsigned*)((const char*)(gbase) + (voff)[_i]), (PG8_LAS unsigned*)(lds + (bufoff) + ldsw + _i * 8192), 16, 0, 0); } while (0)
; #define PG8_LDA(dst, b, h) do { _Pragma("unroll") for (int m = 0; m < 4; ++m) _Pragma("unroll") for (int k = 0; k < 2; ++k) dst[m][k] = *(const PG8_LAS bf16x8*)(lds + PG8_SA(b, h) + aoff + m * 2048 + k * 1024); } while (0)
; #define PG8_MMA(ai, bj, At, Bt) do { __builtin_amdgcn_s_setprio(1); _Pragma("unroll") for (int m = 0; m < 4; ++m) _Pragma("unroll") for (int n = 0; n < 2; ++n) _Pragma("unroll") for (int k = 0; k < 2; ++k) \
;         acc[ai][bj][m][n] = __builtin_amdgcn_mfma_f32_16x16x32_bf16(Bt[n][k], At[m][k], acc[ai][bj][m][n], 0, 0, 0); __builtin_amdgcn_s_setprio(0); } while (0)
; #define PG8_WAIT_V(n) asm volatile("s_waitcnt vmcnt(" #n ")" ::: "memory")
; #define PG8_WAIT_L(n) asm volatile("s_waitcnt lgkmcnt(" #n ")" ::: "memory")
; #define PG8_BAR __builtin_amdgcn_s_barrier()
; #define PG8_SCHED __builtin_amdgcn_sched_barrier(0)
; template <class Epi, class Sched, bool ALIGN_EPI = false, bool SP2 = false>
; __device__ __forceinline__ void gemm_phase(PG8_LAS unsigned char* lds, const Gemm g, const Sched& S, const Epi& E, const int wid) {
;     ...
;             PG8_LDA(At, 1, 1); PG8_STAGE(PG8_SB(1, 0), b3, voffB); PG8_STAGE(PG8_SB(1, 1), b3 + hstep, voffB); PG8_STAGE(PG8_SA(1, 0), a3, voffA);
;             PG8_WAIT_V(8); PG8_WAIT_L(0); PG8_BAR; PG8_MMA(1, 0, At, B0); PG8_MMA(1, 1, At, B1); PG8_BAR; PG8_SCHED;
	s_mov_b32 m0, s41
	v_lshl_add_u64 v[200:201], v[200:201], 0, s[58:59]
	ds_read_b128 v[172:175], v142 offset:49152
	ds_read_b128 v[176:179], v142 offset:50176
	ds_read_b128 v[180:183], v142 offset:51200
	ds_read_b128 v[184:187], v142 offset:52224
	ds_read_b128 v[188:191], v142 offset:53248
	ds_read_b128 v[192:195], v142 offset:54272
	ds_read_b128 v[212:215], v142 offset:55296
	ds_read_b128 v[216:219], v142 offset:56320
	global_load_lds_dwordx4 v[200:201], off
	v_lshl_add_u64 v[200:201], v[202:203], 0, s[58:59]
	s_mov_b32 m0, s40
	s_nop 0
	global_load_lds_dwordx4 v[200:201], off
	v_lshl_add_u64 v[200:201], s[34:35], 0, v[0:1]
	s_mov_b32 m0, s96
	s_nop 0
	global_load_lds_dwordx4 v[200:201], off
	v_lshl_add_u64 v[200:201], s[34:35], 0, v[134:135]
	s_mov_b32 m0, s63
	s_nop 0
	global_load_lds_dwordx4 v[200:201], off
	v_lshl_add_u64 v[200:201], v[208:209], 0, s[58:59]
	s_mov_b32 m0, s65
	s_nop 0
	global_load_lds_dwordx4 v[200:201], off
	v_lshl_add_u64 v[200:201], v[210:211], 0, s[58:59]
	s_mov_b32 m0, s66
	s_nop 0
	global_load_lds_dwordx4 v[200:201], off
	s_waitcnt vmcnt(8)
	s_waitcnt lgkmcnt(0)
	s_setprio 1
	s_barrier
	v_mfma_f32_16x16x32_bf16 v[62:65], v[136:139], v[172:175], v[62:65]
	v_mfma_f32_16x16x32_bf16 v[58:61], v[148:151], v[172:175], v[58:61]
	v_mfma_f32_16x16x32_bf16 v[54:57], v[136:139], v[180:183], v[54:57]
	v_mfma_f32_16x16x32_bf16 v[46:49], v[148:151], v[180:183], v[46:49]
	v_mfma_f32_16x16x32_bf16 v[38:41], v[136:139], v[188:191], v[38:41]
	v_mfma_f32_16x16x32_bf16 v[30:33], v[148:151], v[188:191], v[30:33]
	v_mfma_f32_16x16x32_bf16 v[22:25], v[136:139], v[212:215], v[22:25]
	v_mfma_f32_16x16x32_bf16 v[14:17], v[148:151], v[212:215], v[14:17]
	v_mfma_f32_16x16x32_bf16 v[62:65], v[144:147], v[176:179], v[62:65]
	v_mfma_f32_16x16x32_bf16 v[58:61], v[152:155], v[176:179], v[58:61]
	v_mfma_f32_16x16x32_bf16 v[54:57], v[144:147], v[184:187], v[54:57]
	v_mfma_f32_16x16x32_bf16 v[46:49], v[152:155], v[184:187], v[46:49]
	v_mfma_f32_16x16x32_bf16 v[38:41], v[144:147], v[192:195], v[38:41]
	v_mfma_f32_16x16x32_bf16 v[30:33], v[152:155], v[192:195], v[30:33]
	v_mfma_f32_16x16x32_bf16 v[22:25], v[144:147], v[216:219], v[22:25]
	v_mfma_f32_16x16x32_bf16 v[14:17], v[152:155], v[216:219], v[14:17]
	s_setprio 0
	s_setprio 1
	v_mfma_f32_16x16x32_bf16 v[50:53], v[156:159], v[172:175], v[50:53]
	v_mfma_f32_16x16x32_bf16 v[42:45], v[164:167], v[172:175], v[42:45]
	v_mfma_f32_16x16x32_bf16 v[34:37], v[156:159], v[180:183], v[34:37]
	v_mfma_f32_16x16x32_bf16 v[26:29], v[164:167], v[180:183], v[26:29]
	v_mfma_f32_16x16x32_bf16 v[18:21], v[156:159], v[188:191], v[18:21]
	v_mfma_f32_16x16x32_bf16 v[10:13], v[164:167], v[188:191], v[10:13]
	v_mfma_f32_16x16x32_bf16 v[6:9], v[156:159], v[212:215], v[6:9]
	v_mfma_f32_16x16x32_bf16 v[2:5], v[164:167], v[212:215], v[2:5]
	v_mfma_f32_16x16x32_bf16 v[50:53], v[160:163], v[176:179], v[50:53]
	v_mfma_f32_16x16x32_bf16 v[42:45], v[168:171], v[176:179], v[42:45]
	v_mfma_f32_16x16x32_bf16 v[34:37], v[160:163], v[184:187], v[34:37]
	v_mfma_f32_16x16x32_bf16 v[26:29], v[168:171], v[184:187], v[26:29]
	v_mfma_f32_16x16x32_bf16 v[18:21], v[160:163], v[192:195], v[18:21]
	v_mfma_f32_16x16x32_bf16 v[10:13], v[168:171], v[192:195], v[10:13]
	v_mfma_f32_16x16x32_bf16 v[6:9], v[160:163], v[216:219], v[6:9]
	v_mfma_f32_16x16x32_bf16 v[2:5], v[168:171], v[216:219], v[2:5]
	s_setprio 0
	s_barrier
	s_movk_i32 s36, 0x100
	s_andn2_b64 vcc, exec, s[30:31]
	s_mov_b64 s[34:35], -1
	s_mov_b64 s[30:31], 0
	s_cbranch_vccz .LBB0_429
	s_and_b64 vcc, exec, s[14:15]
	s_cbranch_vccz .LBB0_432
	s_barrier

; #define PG8_STAGE(bufoff, gbase, voff) do { _Pragma("unroll") for (int _i = 0; _i < 2; ++_i) \
;         __builtin_amdgcn_global_load_lds((const unsigned*)((const char*)(gbase) + (voff)[_i]), (PG8_LAS unsigned*)(lds + (bufoff) + ldsw + _i * 8192), 16, 0, 0); } while (0)
; #define PG8_LDA(dst, b, h) do { _Pragma("unroll") for (int m = 0; m < 4; ++m) _Pragma("unroll") for (int k = 0; k < 2; ++k) dst[m][k] = *(const PG8_LAS bf16x8*)(lds + PG8_SA(b, h) + aoff + m * 2048 + k * 1024); } while (0)
; #define PG8_LDB(dst, b, h) do { _Pragma("unroll") for (int n = 0; n < 2; ++n) _Pragma("unroll") for (int k = 0; k < 2; ++k) dst[n][k] = *(const PG8_LAS bf16x8*)(lds + PG8_SB(b, h) + boff + n * 2048 + k * 1024); } while (0)
; #define PG8_MMA(ai, bj, At, Bt) do { __builtin_amdgcn_s_setprio(1); _Pragma("unroll") for (int m = 0; m < 4; ++m) _Pragma("unroll") for (int n = 0; n < 2; ++n) _Pragma("unroll") for (int k = 0; k < 2; ++k) \
;         acc[ai][bj][m][n] = __builtin_amdgcn_mfma_f32_16x16x32_bf16(Bt[n][k], At[m][k], acc[ai][bj][m][n], 0, 0, 0); __builtin_amdgcn_s_setprio(0); } while (0)
; #define PG8_WAIT_V(n) asm volatile("s_waitcnt vmcnt(" #n ")" ::: "memory")
; #define PG8_BAR __builtin_amdgcn_s_barrier()
; template <class Epi, class Sched, bool ALIGN_EPI = false, bool SP2 = false>
; __device__ __forceinline__ void gemm_phase(PG8_LAS unsigned char* lds, const Gemm g, const Sched& S, const Epi& E, const int wid) {
;     ...
;         for (int t = 0; t < nt; t += 2) {
;             const bool last = (t == nt - 2);
;             const char* a1 = cA + (size_t)(t + 1) * kstep;
;             const char* a2 = last ? nA : cA + (size_t)(t + 2) * kstep; const char* b2 = last ? nB : cB + (size_t)(t + 2) * kstep;
;             const char* a3 = a2 + kstep; const char* b3 = b2 + kstep;
;             if (last && has_next) S.a_ready(nxt);
;             if constexpr (SP2) {
;             PG8_LDB(B0, 0, 0); PG8_LDB(B1, 0, 1); PG8_SCHED; PG8_LDA(At, 0, 0); PG8_STAGE(PG8_SA(1, 1), a1 + hstep, voffA);
;             PG8_WAIT_V(8); PG8_WAIT_L(0); PG8_BAR; PG8_MMA(0, 0, At, B0); PG8_MMA(0, 1, At, B1); PG8_BAR; PG8_SCHED;
;             PG8_LDA(At, 0, 1); PG8_STAGE(PG8_SB(0, 0), b2, voffB); PG8_STAGE(PG8_SB(0, 1), b2 + hstep, voffB); PG8_STAGE(PG8_SA(0, 0), a2, voffA);
;             PG8_WAIT_V(8); PG8_WAIT_L(0); PG8_BAR; PG8_MMA(1, 0, At, B0); PG8_MMA(1, 1, At, B1); PG8_BAR; PG8_SCHED;
.LBB0_453:
	s_add_u32 s35, s22, s34
	s_addc_u32 s40, s23, 0
	s_add_u32 s38, s35, 0x100
	s_addc_u32 s39, s40, 0
	s_and_b64 s[36:37], s[30:31], exec
	s_cselect_b32 s37, s19, s39
	s_cselect_b32 s36, s68, s38
	s_add_u32 s34, s20, s34
	s_addc_u32 s38, s21, 0
	s_add_u32 s34, s34, 0x100
	s_addc_u32 s38, s38, 0
	s_add_i32 s63, 0, 0x10000
	s_and_b64 s[30:31], s[30:31], exec
	s_cselect_b32 s39, s17, s38
	s_cselect_b32 s38, s90, s34
	s_add_i32 s31, 0, 0x14000
	s_add_u32 s88, s35, 0x10080
	s_addc_u32 s89, s40, 0
	s_add_i32 s62, s63, s45
	s_add_i32 m0, s15, 0xc000
	s_add_i32 s92, s15, 0xe000
	s_add_i32 s54, s62, 0x2000
	v_add_u32_e32 v143, s63, v141
	s_add_u32 s86, s38, 0x10000
	ds_read_b128 v[136:139], v143
	ds_read_b128 v[144:147], v143 offset:1024
	ds_read_b128 v[148:151], v143 offset:2048
	ds_read_b128 v[152:155], v143 offset:3072
	v_add_u32_e32 v143, s31, v141
	s_addc_u32 s87, s39, 0
	s_add_i32 s61, s31, s45
	ds_read_b128 v[156:159], v143
	ds_read_b128 v[160:163], v143 offset:1024
	ds_read_b128 v[164:167], v143 offset:2048
	ds_read_b128 v[168:171], v143 offset:3072
	s_add_i32 s60, s61, 0x2000
	s_add_i32 s43, 0, 0x18000
	s_add_i32 s42, 0, 0x1c000
	s_add_u32 s34, s36, 0x10000
	s_addc_u32 s35, s37, 0
	s_add_i32 s41, s43, s45
	s_add_i32 s40, s41, 0x2000
	s_add_u32 s30, s38, 0x10080
	s_addc_u32 s31, s39, 0
	s_add_i32 s91, s42, s45
	s_add_i32 s63, s91, 0x2000
	v_lshl_add_u64 v[200:201], s[88:89], 0, v[130:131]
	ds_read_b128 v[172:175], v142
	ds_read_b128 v[176:179], v142 offset:1024
	ds_read_b128 v[180:183], v142 offset:2048
	ds_read_b128 v[184:187], v142 offset:3072
	ds_read_b128 v[188:191], v142 offset:4096
	ds_read_b128 v[192:195], v142 offset:5120
	ds_read_b128 v[212:215], v142 offset:6144
	ds_read_b128 v[216:219], v142 offset:7168
	global_load_lds_dwordx4 v[200:201], off
	v_lshl_add_u64 v[200:201], s[88:89], 0, v[132:133]
	s_mov_b32 m0, s92
	s_nop 0
	global_load_lds_dwordx4 v[200:201], off
	s_waitcnt vmcnt(8)
	s_waitcnt lgkmcnt(0)
	s_setprio 1
	s_barrier
	v_mfma_f32_16x16x32_bf16 v[126:129], v[136:139], v[172:175], v[126:129]
	v_mfma_f32_16x16x32_bf16 v[122:125], v[148:151], v[172:175], v[122:125]
	v_mfma_f32_16x16x32_bf16 v[118:121], v[136:139], v[180:183], v[118:121]
	v_mfma_f32_16x16x32_bf16 v[110:113], v[148:151], v[180:183], v[110:113]
	v_mfma_f32_16x16x32_bf16 v[102:105], v[136:139], v[188:191], v[102:105]
	v_mfma_f32_16x16x32_bf16 v[94:97], v[148:151], v[188:191], v[94:97]
	v_mfma_f32_16x16x32_bf16 v[86:89], v[136:139], v[212:215], v[86:89]
	v_mfma_f32_16x16x32_bf16 v[78:81], v[148:151], v[212:215], v[78:81]
	v_mfma_f32_16x16x32_bf16 v[126:129], v[144:147], v[176:179], v[126:129]
	v_mfma_f32_16x16x32_bf16 v[122:125], v[152:155], v[176:179], v[122:125]
	v_mfma_f32_16x16x32_bf16 v[118:121], v[144:147], v[184:187], v[118:121]
	v_mfma_f32_16x16x32_bf16 v[110:113], v[152:155], v[184:187], v[110:113]
	v_mfma_f32_16x16x32_bf16 v[102:105], v[144:147], v[192:195], v[102:105]
	v_mfma_f32_16x16x32_bf16 v[94:97], v[152:155], v[192:195], v[94:97]
	v_mfma_f32_16x16x32_bf16 v[86:89], v[144:147], v[216:219], v[86:89]
	v_mfma_f32_16x16x32_bf16 v[78:81], v[152:155], v[216:219], v[78:81]
	s_setprio 0
	s_setprio 1
	v_mfma_f32_16x16x32_bf16 v[114:117], v[156:159], v[172:175], v[114:117]
	v_mfma_f32_16x16x32_bf16 v[106:109], v[164:167], v[172:175], v[106:109]
	v_mfma_f32_16x16x32_bf16 v[98:101], v[156:159], v[180:183], v[98:101]
	v_mfma_f32_16x16x32_bf16 v[90:93], v[164:167], v[180:183], v[90:93]
	v_mfma_f32_16x16x32_bf16 v[82:85], v[156:159], v[188:191], v[82:85]
	v_mfma_f32_16x16x32_bf16 v[74:77], v[164:167], v[188:191], v[74:77]
	v_mfma_f32_16x16x32_bf16 v[70:73], v[156:159], v[212:215], v[70:73]
	v_mfma_f32_16x16x32_bf16 v[66:69], v[164:167], v[212:215], v[66:69]
	v_mfma_f32_16x16x32_bf16 v[114:117], v[160:163], v[176:179], v[114:117]
	v_mfma_f32_16x16x32_bf16 v[106:109], v[168:171], v[176:179], v[106:109]
	v_mfma_f32_16x16x32_bf16 v[98:101], v[160:163], v[184:187], v[98:101]
	v_mfma_f32_16x16x32_bf16 v[90:93], v[168:171], v[184:187], v[90:93]
	v_mfma_f32_16x16x32_bf16 v[82:85], v[160:163], v[192:195], v[82:85]
	v_mfma_f32_16x16x32_bf16 v[74:77], v[168:171], v[192:195], v[74:77]
	v_mfma_f32_16x16x32_bf16 v[70:73], v[160:163], v[216:219], v[70:73]
	v_mfma_f32_16x16x32_bf16 v[66:69], v[168:171], v[216:219], v[66:69]
	s_setprio 0
	s_barrier
	s_mov_b32 m0, s62
	v_lshl_add_u64 v[200:201], s[38:39], 0, v[0:1]
	ds_read_b128 v[172:175], v142 offset:16384
	ds_read_b128 v[176:179], v142 offset:17408
	ds_read_b128 v[180:183], v142 offset:18432
	ds_read_b128 v[184:187], v142 offset:19456
	ds_read_b128 v[188:191], v142 offset:20480
	ds_read_b128 v[192:195], v142 offset:21504
	ds_read_b128 v[212:215], v142 offset:22528
	ds_read_b128 v[216:219], v142 offset:23552
	global_load_lds_dwordx4 v[200:201], off
	v_lshl_add_u64 v[202:203], s[38:39], 0, v[134:135]
	s_mov_b32 m0, s54
	v_lshl_add_u64 v[208:209], s[86:87], 0, v[0:1]
	global_load_lds_dwordx4 v[202:203], off
	s_mov_b32 m0, s61
	v_lshl_add_u64 v[210:211], s[36:37], 0, v[132:133]
	global_load_lds_dwordx4 v[208:209], off
	v_lshl_add_u64 v[208:209], s[86:87], 0, v[134:135]
	s_mov_b32 m0, s60
	s_nop 0
	global_load_lds_dwordx4 v[208:209], off
	v_lshl_add_u64 v[208:209], s[36:37], 0, v[130:131]
	s_mov_b32 m0, s15
	s_nop 0
	global_load_lds_dwordx4 v[208:209], off
	s_mov_b32 m0, s50
	s_nop 0
	global_load_lds_dwordx4 v[210:211], off
	s_waitcnt vmcnt(8)
	s_waitcnt lgkmcnt(0)
	s_setprio 1
	s_barrier
; #define PG8_STAGE(bufoff, gbase, voff) do { _Pragma("unroll") for (int _i = 0; _i < 2; ++_i) \
;         __builtin_amdgcn_global_load_lds((const unsigned*)((const char*)(gbase) + (voff)[_i]), (PG8_LAS unsigned*)(lds + (bufoff) + ldsw + _i * 8192), 16, 0, 0); } while (0)
; #define PG8_LDA(dst, b, h) do { _Pragma("unroll") for (int m = 0; m < 4; ++m) _Pragma("unroll") for (int k = 0; k < 2; ++k) dst[m][k] = *(const PG8_LAS bf16x8*)(lds + PG8_SA(b, h) + aoff + m * 2048 + k * 1024); } while (0)
; #define PG8_LDB(dst, b, h) do { _Pragma("unroll") for (int n = 0; n < 2; ++n) _Pragma("unroll") for (int k = 0; k < 2; ++k) dst[n][k] = *(const PG8_LAS bf16x8*)(lds + PG8_SB(b, h) + boff + n * 2048 + k * 1024); } while (0)
; #define PG8_MMA(ai, bj, At, Bt) do { __builtin_amdgcn_s_setprio(1); _Pragma("unroll") for (int m = 0; m < 4; ++m) _Pragma("unroll") for (int n = 0; n < 2; ++n) _Pragma("unroll") for (int k = 0; k < 2; ++k) \
;         acc[ai][bj][m][n] = __builtin_amdgcn_mfma_f32_16x16x32_bf16(Bt[n][k], At[m][k], acc[ai][bj][m][n], 0, 0, 0); __builtin_amdgcn_s_setprio(0); } while (0)
; #define PG8_WAIT_V(n) asm volatile("s_waitcnt vmcnt(" #n ")" ::: "memory")
; #define PG8_WAIT_L(n) asm volatile("s_waitcnt lgkmcnt(" #n ")" ::: "memory")
; #define PG8_BAR __builtin_amdgcn_s_barrier()
; #define PG8_SCHED __builtin_amdgcn_sched_barrier(0)
; template <class Epi, class Sched, bool ALIGN_EPI = false, bool SP2 = false>
; __device__ __forceinline__ void gemm_phase(PG8_LAS unsigned char* lds, const Gemm g, const Sched& S, const Epi& E, const int wid) {
;     ...
;             PG8_WAIT_V(8); PG8_WAIT_L(0); PG8_BAR; PG8_MMA(1, 0, At, B0); PG8_MMA(1, 1, At, B1); PG8_BAR; PG8_SCHED;
;             PG8_LDB(B0, 1, 0); PG8_LDB(B1, 1, 1); PG8_SCHED; PG8_LDA(At, 1, 0); PG8_STAGE(PG8_SA(0, 1), a2 + hstep, voffA);
;             PG8_WAIT_V(8); PG8_WAIT_L(0); PG8_BAR; PG8_MMA(0, 0, At, B0); PG8_MMA(0, 1, At, B1); PG8_BAR; PG8_SCHED;
	v_mfma_f32_16x16x32_bf16 v[62:65], v[136:139], v[172:175], v[62:65]
	v_mfma_f32_16x16x32_bf16 v[58:61], v[148:151], v[172:175], v[58:61]
	v_mfma_f32_16x16x32_bf16 v[54:57], v[136:139], v[180:183], v[54:57]
	v_mfma_f32_16x16x32_bf16 v[46:49], v[148:151], v[180:183], v[46:49]
	v_mfma_f32_16x16x32_bf16 v[38:41], v[136:139], v[188:191], v[38:41]
	v_mfma_f32_16x16x32_bf16 v[30:33], v[148:151], v[188:191], v[30:33]
	v_mfma_f32_16x16x32_bf16 v[22:25], v[136:139], v[212:215], v[22:25]
	v_mfma_f32_16x16x32_bf16 v[14:17], v[148:151], v[212:215], v[14:17]
	v_mfma_f32_16x16x32_bf16 v[62:65], v[144:147], v[176:179], v[62:65]
	v_mfma_f32_16x16x32_bf16 v[58:61], v[152:155], v[176:179], v[58:61]
	v_mfma_f32_16x16x32_bf16 v[54:57], v[144:147], v[184:187], v[54:57]
	v_mfma_f32_16x16x32_bf16 v[46:49], v[152:155], v[184:187], v[46:49]
	v_mfma_f32_16x16x32_bf16 v[38:41], v[144:147], v[192:195], v[38:41]
	v_mfma_f32_16x16x32_bf16 v[30:33], v[152:155], v[192:195], v[30:33]
	v_mfma_f32_16x16x32_bf16 v[22:25], v[144:147], v[216:219], v[22:25]
	v_mfma_f32_16x16x32_bf16 v[14:17], v[152:155], v[216:219], v[14:17]
	s_setprio 0
	s_setprio 1
	v_mfma_f32_16x16x32_bf16 v[50:53], v[156:159], v[172:175], v[50:53]
	v_mfma_f32_16x16x32_bf16 v[42:45], v[164:167], v[172:175], v[42:45]
	v_mfma_f32_16x16x32_bf16 v[34:37], v[156:159], v[180:183], v[34:37]
	v_mfma_f32_16x16x32_bf16 v[26:29], v[164:167], v[180:183], v[26:29]
	v_mfma_f32_16x16x32_bf16 v[18:21], v[156:159], v[188:191], v[18:21]
	v_mfma_f32_16x16x32_bf16 v[10:13], v[164:167], v[188:191], v[10:13]
	v_mfma_f32_16x16x32_bf16 v[6:9], v[156:159], v[212:215], v[6:9]
	v_mfma_f32_16x16x32_bf16 v[2:5], v[164:167], v[212:215], v[2:5]
	v_mfma_f32_16x16x32_bf16 v[50:53], v[160:163], v[176:179], v[50:53]
	v_mfma_f32_16x16x32_bf16 v[42:45], v[168:171], v[176:179], v[42:45]
	v_mfma_f32_16x16x32_bf16 v[34:37], v[160:163], v[184:187], v[34:37]
	v_mfma_f32_16x16x32_bf16 v[26:29], v[168:171], v[184:187], v[26:29]
	v_mfma_f32_16x16x32_bf16 v[18:21], v[160:163], v[192:195], v[18:21]
	v_mfma_f32_16x16x32_bf16 v[10:13], v[168:171], v[192:195], v[10:13]
	v_mfma_f32_16x16x32_bf16 v[6:9], v[160:163], v[216:219], v[6:9]
	v_mfma_f32_16x16x32_bf16 v[2:5], v[168:171], v[216:219], v[2:5]
	s_setprio 0
	s_barrier
	v_add_u32_e32 v143, s43, v141
	ds_read_b128 v[136:139], v143
	ds_read_b128 v[144:147], v143 offset:1024
	ds_read_b128 v[148:151], v143 offset:2048
	ds_read_b128 v[152:155], v143 offset:3072
	v_add_u32_e32 v143, s42, v141
	ds_read_b128 v[156:159], v143
	ds_read_b128 v[160:163], v143 offset:1024
	ds_read_b128 v[164:167], v143 offset:2048
	ds_read_b128 v[168:171], v143 offset:3072
	s_mov_b32 m0, s55
	v_lshl_add_u64 v[220:221], s[34:35], 0, v[130:131]
	ds_read_b128 v[172:175], v142 offset:32768
	ds_read_b128 v[176:179], v142 offset:33792
	ds_read_b128 v[180:183], v142 offset:34816
	ds_read_b128 v[184:187], v142 offset:35840
	ds_read_b128 v[188:191], v142 offset:36864
	ds_read_b128 v[192:195], v142 offset:37888
	ds_read_b128 v[212:215], v142 offset:38912
	ds_read_b128 v[216:219], v142 offset:39936
	global_load_lds_dwordx4 v[220:221], off
	v_lshl_add_u64 v[220:221], s[34:35], 0, v[132:133]
	s_mov_b32 m0, s64
	s_nop 0
	global_load_lds_dwordx4 v[220:221], off
	s_waitcnt vmcnt(8)
	s_waitcnt lgkmcnt(0)
	s_setprio 1
	s_barrier
	v_mfma_f32_16x16x32_bf16 v[126:129], v[136:139], v[172:175], v[126:129]
	v_mfma_f32_16x16x32_bf16 v[122:125], v[148:151], v[172:175], v[122:125]
	v_mfma_f32_16x16x32_bf16 v[118:121], v[136:139], v[180:183], v[118:121]
	v_mfma_f32_16x16x32_bf16 v[110:113], v[148:151], v[180:183], v[110:113]
	v_mfma_f32_16x16x32_bf16 v[102:105], v[136:139], v[188:191], v[102:105]
	v_mfma_f32_16x16x32_bf16 v[94:97], v[148:151], v[188:191], v[94:97]
	v_mfma_f32_16x16x32_bf16 v[86:89], v[136:139], v[212:215], v[86:89]
	v_mfma_f32_16x16x32_bf16 v[78:81], v[148:151], v[212:215], v[78:81]
	v_mfma_f32_16x16x32_bf16 v[126:129], v[144:147], v[176:179], v[126:129]
	v_mfma_f32_16x16x32_bf16 v[122:125], v[152:155], v[176:179], v[122:125]
	v_mfma_f32_16x16x32_bf16 v[118:121], v[144:147], v[184:187], v[118:121]
	v_mfma_f32_16x16x32_bf16 v[110:113], v[152:155], v[184:187], v[110:113]
	v_mfma_f32_16x16x32_bf16 v[102:105], v[144:147], v[192:195], v[102:105]
	v_mfma_f32_16x16x32_bf16 v[94:97], v[152:155], v[192:195], v[94:97]
	v_mfma_f32_16x16x32_bf16 v[86:89], v[144:147], v[216:219], v[86:89]
	v_mfma_f32_16x16x32_bf16 v[78:81], v[152:155], v[216:219], v[78:81]
	s_setprio 0
	s_setprio 1
	v_mfma_f32_16x16x32_bf16 v[114:117], v[156:159], v[172:175], v[114:117]
	v_mfma_f32_16x16x32_bf16 v[106:109], v[164:167], v[172:175], v[106:109]
	v_mfma_f32_16x16x32_bf16 v[98:101], v[156:159], v[180:183], v[98:101]
	v_mfma_f32_16x16x32_bf16 v[90:93], v[164:167], v[180:183], v[90:93]
	v_mfma_f32_16x16x32_bf16 v[82:85], v[156:159], v[188:191], v[82:85]
	v_mfma_f32_16x16x32_bf16 v[74:77], v[164:167], v[188:191], v[74:77]
	v_mfma_f32_16x16x32_bf16 v[70:73], v[156:159], v[212:215], v[70:73]
	v_mfma_f32_16x16x32_bf16 v[66:69], v[164:167], v[212:215], v[66:69]
	v_mfma_f32_16x16x32_bf16 v[114:117], v[160:163], v[176:179], v[114:117]
	v_mfma_f32_16x16x32_bf16 v[106:109], v[168:171], v[176:179], v[106:109]
	v_mfma_f32_16x16x32_bf16 v[98:101], v[160:163], v[184:187], v[98:101]
	v_mfma_f32_16x16x32_bf16 v[90:93], v[168:171], v[184:187], v[90:93]
	v_mfma_f32_16x16x32_bf16 v[82:85], v[160:163], v[192:195], v[82:85]
	v_mfma_f32_16x16x32_bf16 v[74:77], v[168:171], v[192:195], v[74:77]
	v_mfma_f32_16x16x32_bf16 v[70:73], v[160:163], v[216:219], v[70:73]
	v_mfma_f32_16x16x32_bf16 v[66:69], v[168:171], v[216:219], v[66:69]
	s_setprio 0
	s_barrier
; #define PG8_STAGE(bufoff, gbase, voff) do { _Pragma("unroll") for (int _i = 0; _i < 2; ++_i) \
;         __builtin_amdgcn_global_load_lds((const unsigned*)((const char*)(gbase) + (voff)[_i]), (PG8_LAS unsigned*)(lds + (bufoff) + ldsw + _i * 8192), 16, 0, 0); } while (0)
; #define PG8_LDA(dst, b, h) do { _Pragma("unroll") for (int m = 0; m < 4; ++m) _Pragma("unroll") for (int k = 0; k < 2; ++k) dst[m][k] = *(const PG8_LAS bf16x8*)(lds + PG8_SA(b, h) + aoff + m * 2048 + k * 1024); } while (0)
; #define PG8_MMA(ai, bj, At, Bt) do { __builtin_amdgcn_s_setprio(1); _Pragma("unroll") for (int m = 0; m < 4; ++m) _Pragma("unroll") for (int n = 0; n < 2; ++n) _Pragma("unroll") for (int k = 0; k < 2; ++k) \
;         acc[ai][bj][m][n] = __builtin_amdgcn_mfma_f32_16x16x32_bf16(Bt[n][k], At[m][k], acc[ai][bj][m][n], 0, 0, 0); __builtin_amdgcn_s_setprio(0); } while (0)
; #define PG8_WAIT_V(n) asm volatile("s_waitcnt vmcnt(" #n ")" ::: "memory")
; #define PG8_WAIT_L(n) asm volatile("s_waitcnt lgkmcnt(" #n ")" ::: "memory")
; #define PG8_BAR __builtin_amdgcn_s_barrier()
; #define PG8_SCHED __builtin_amdgcn_sched_barrier(0)
; template <class Epi, class Sched, bool ALIGN_EPI = false, bool SP2 = false>
; __device__ __forceinline__ void gemm_phase(PG8_LAS unsigned char* lds, const Gemm g, const Sched& S, const Epi& E, const int wid) {
;     ...
;             PG8_LDA(At, 1, 1); PG8_STAGE(PG8_SB(1, 0), b3, voffB); PG8_STAGE(PG8_SB(1, 1), b3 + hstep, voffB); PG8_STAGE(PG8_SA(1, 0), a3, voffA);
;             PG8_WAIT_V(8); PG8_WAIT_L(0); PG8_BAR; PG8_MMA(1, 0, At, B0); PG8_MMA(1, 1, At, B1); PG8_BAR; PG8_SCHED;
	s_mov_b32 m0, s41
	v_lshl_add_u64 v[200:201], v[200:201], 0, s[58:59]
	ds_read_b128 v[172:175], v142 offset:49152
	ds_read_b128 v[176:179], v142 offset:50176
	ds_read_b128 v[180:183], v142 offset:51200
	ds_read_b128 v[184:187], v142 offset:52224
	ds_read_b128 v[188:191], v142 offset:53248
	ds_read_b128 v[192:195], v142 offset:54272
	ds_read_b128 v[212:215], v142 offset:55296
	ds_read_b128 v[216:219], v142 offset:56320
	global_load_lds_dwordx4 v[200:201], off
	v_lshl_add_u64 v[200:201], v[202:203], 0, s[58:59]
	s_mov_b32 m0, s40
	s_nop 0
	global_load_lds_dwordx4 v[200:201], off
	v_lshl_add_u64 v[200:201], s[30:31], 0, v[0:1]
	s_mov_b32 m0, s91
	s_nop 0
	global_load_lds_dwordx4 v[200:201], off
	v_lshl_add_u64 v[200:201], s[30:31], 0, v[134:135]
	s_mov_b32 m0, s63
	s_nop 0
	global_load_lds_dwordx4 v[200:201], off
	v_lshl_add_u64 v[200:201], v[208:209], 0, s[58:59]
	s_mov_b32 m0, s44
	s_nop 0
	global_load_lds_dwordx4 v[200:201], off
	v_lshl_add_u64 v[200:201], v[210:211], 0, s[58:59]
	s_mov_b32 m0, s65
	s_nop 0
	global_load_lds_dwordx4 v[200:201], off
	s_waitcnt vmcnt(8)
	s_waitcnt lgkmcnt(0)
	s_setprio 1
	s_barrier
	v_mfma_f32_16x16x32_bf16 v[62:65], v[136:139], v[172:175], v[62:65]
	v_mfma_f32_16x16x32_bf16 v[58:61], v[148:151], v[172:175], v[58:61]
	v_mfma_f32_16x16x32_bf16 v[54:57], v[136:139], v[180:183], v[54:57]
	v_mfma_f32_16x16x32_bf16 v[46:49], v[148:151], v[180:183], v[46:49]
	v_mfma_f32_16x16x32_bf16 v[38:41], v[136:139], v[188:191], v[38:41]
	v_mfma_f32_16x16x32_bf16 v[30:33], v[148:151], v[188:191], v[30:33]
	v_mfma_f32_16x16x32_bf16 v[22:25], v[136:139], v[212:215], v[22:25]
	v_mfma_f32_16x16x32_bf16 v[14:17], v[148:151], v[212:215], v[14:17]
	v_mfma_f32_16x16x32_bf16 v[62:65], v[144:147], v[176:179], v[62:65]
	v_mfma_f32_16x16x32_bf16 v[58:61], v[152:155], v[176:179], v[58:61]
	v_mfma_f32_16x16x32_bf16 v[54:57], v[144:147], v[184:187], v[54:57]
	v_mfma_f32_16x16x32_bf16 v[46:49], v[152:155], v[184:187], v[46:49]
	v_mfma_f32_16x16x32_bf16 v[38:41], v[144:147], v[192:195], v[38:41]
	v_mfma_f32_16x16x32_bf16 v[30:33], v[152:155], v[192:195], v[30:33]
	v_mfma_f32_16x16x32_bf16 v[22:25], v[144:147], v[216:219], v[22:25]
	v_mfma_f32_16x16x32_bf16 v[14:17], v[152:155], v[216:219], v[14:17]
	s_setprio 0
	s_setprio 1
	v_mfma_f32_16x16x32_bf16 v[50:53], v[156:159], v[172:175], v[50:53]
	v_mfma_f32_16x16x32_bf16 v[42:45], v[164:167], v[172:175], v[42:45]
	v_mfma_f32_16x16x32_bf16 v[34:37], v[156:159], v[180:183], v[34:37]
	v_mfma_f32_16x16x32_bf16 v[26:29], v[164:167], v[180:183], v[26:29]
	v_mfma_f32_16x16x32_bf16 v[18:21], v[156:159], v[188:191], v[18:21]
	v_mfma_f32_16x16x32_bf16 v[10:13], v[164:167], v[188:191], v[10:13]
	v_mfma_f32_16x16x32_bf16 v[6:9], v[156:159], v[212:215], v[6:9]
	v_mfma_f32_16x16x32_bf16 v[2:5], v[164:167], v[212:215], v[2:5]
	v_mfma_f32_16x16x32_bf16 v[50:53], v[160:163], v[176:179], v[50:53]
	v_mfma_f32_16x16x32_bf16 v[42:45], v[168:171], v[176:179], v[42:45]
	v_mfma_f32_16x16x32_bf16 v[34:37], v[160:163], v[184:187], v[34:37]
	v_mfma_f32_16x16x32_bf16 v[26:29], v[168:171], v[184:187], v[26:29]
	v_mfma_f32_16x16x32_bf16 v[18:21], v[160:163], v[192:195], v[18:21]
	v_mfma_f32_16x16x32_bf16 v[10:13], v[168:171], v[192:195], v[10:13]
	v_mfma_f32_16x16x32_bf16 v[6:9], v[160:163], v[216:219], v[6:9]
	v_mfma_f32_16x16x32_bf16 v[2:5], v[168:171], v[216:219], v[2:5]
	s_setprio 0
	s_barrier
	s_movk_i32 s34, 0x100
	s_andn2_b64 vcc, exec, s[28:29]
	s_mov_b64 s[30:31], -1
	s_mov_b64 s[28:29], 0
	s_cbranch_vccz .LBB0_453
	s_and_b64 vcc, exec, s[12:13]
	s_cbranch_vccz .LBB0_456
	s_barrier

; #define PG8_STAGE(bufoff, gbase, voff) do { _Pragma("unroll") for (int _i = 0; _i < 2; ++_i) \
;         __builtin_amdgcn_global_load_lds((const unsigned*)((const char*)(gbase) + (voff)[_i]), (PG8_LAS unsigned*)(lds + (bufoff) + ldsw + _i * 8192), 16, 0, 0); } while (0)
; #define PG8_LDA(dst, b, h) do { _Pragma("unroll") for (int m = 0; m < 4; ++m) _Pragma("unroll") for (int k = 0; k < 2; ++k) dst[m][k] = *(const PG8_LAS bf16x8*)(lds + PG8_SA(b, h) + aoff + m * 2048 + k * 1024); } while (0)
; #define PG8_LDB(dst, b, h) do { _Pragma("unroll") for (int n = 0; n < 2; ++n) _Pragma("unroll") for (int k = 0; k < 2; ++k) dst[n][k] = *(const PG8_LAS bf16x8*)(lds + PG8_SB(b, h) + boff + n * 2048 + k * 1024); } while (0)
; #define PG8_MMA(ai, bj, At, Bt) do { __builtin_amdgcn_s_setprio(1); _Pragma("unroll") for (int m = 0; m < 4; ++m) _Pragma("unroll") for (int n = 0; n < 2; ++n) _Pragma("unroll") for (int k = 0; k < 2; ++k) \
;         acc[ai][bj][m][n] = __builtin_amdgcn_mfma_f32_16x16x32_bf16(Bt[n][k], At[m][k], acc[ai][bj][m][n], 0, 0, 0); __builtin_amdgcn_s_setprio(0); } while (0)
; #define PG8_WAIT_V(n) asm volatile("s_waitcnt vmcnt(" #n ")" ::: "memory")
; #define PG8_BAR __builtin_amdgcn_s_barrier()
; template <class Epi, class Sched, bool ALIGN_EPI = false, bool SP2 = false>
; __device__ __forceinline__ void gemm_phase(PG8_LAS unsigned char* lds, const Gemm g, const Sched& S, const Epi& E, const int wid) {
;     ...
;         for (int t = 0; t < nt; t += 2) {
;             const bool last = (t == nt - 2);
;             const char* a1 = cA + (size_t)(t + 1) * kstep;
;             const char* a2 = last ? nA : cA + (size_t)(t + 2) * kstep; const char* b2 = last ? nB : cB + (size_t)(t + 2) * kstep;
;             const char* a3 = a2 + kstep; const char* b3 = b2 + kstep;
;             if (last && has_next) S.a_ready(nxt);
;             if constexpr (SP2) {
;             PG8_LDB(B0, 0, 0); PG8_LDB(B1, 0, 1); PG8_SCHED; PG8_LDA(At, 0, 0); PG8_STAGE(PG8_SA(1, 1), a1 + hstep, voffA);
;             PG8_WAIT_V(8); PG8_WAIT_L(0); PG8_BAR; PG8_MMA(0, 0, At, B0); PG8_MMA(0, 1, At, B1); PG8_BAR; PG8_SCHED;
;             PG8_LDA(At, 0, 1); PG8_STAGE(PG8_SB(0, 0), b2, voffB); PG8_STAGE(PG8_SB(0, 1), b2 + hstep, voffB); PG8_STAGE(PG8_SA(0, 0), a2, voffA);
;             PG8_WAIT_V(8); PG8_WAIT_L(0); PG8_BAR; PG8_MMA(1, 0, At, B0); PG8_MMA(1, 1, At, B1); PG8_BAR; PG8_SCHED;
.LBB0_478:
	s_add_u32 s36, s34, 0xfff80080
	s_addc_u32 s37, s35, -1
	s_add_i32 s40, 0, 0x10000
	s_cmp_eq_u32 s55, 28
	s_cselect_b32 s39, s25, s37
	s_cselect_b32 s38, s31, s36
	v_add_u32_e32 v0, s40, v149
	s_cselect_b32 s37, s23, s50
	s_cselect_b32 s36, s46, s47
	s_add_i32 s42, 0, 0x14000
	ds_read_b128 v[142:145], v0
	ds_read_b128 v[152:155], v0 offset:1024
	ds_read_b128 v[156:159], v0 offset:2048
	ds_read_b128 v[160:163], v0 offset:3072
	v_add_u32_e32 v0, s42, v149
	ds_read_b128 v[164:167], v0
	ds_read_b128 v[168:171], v0 offset:1024
	ds_read_b128 v[172:175], v0 offset:2048
	ds_read_b128 v[176:179], v0 offset:3072
	v_lshl_add_u64 v[146:147], s[34:35], 0, v[138:139]
	s_add_i32 m0, s92, 0xc000
	ds_read_b128 v[180:183], v150
	ds_read_b128 v[184:187], v150 offset:1024
	ds_read_b128 v[188:191], v150 offset:2048
	ds_read_b128 v[192:195], v150 offset:3072
	ds_read_b128 v[212:215], v150 offset:4096
	ds_read_b128 v[216:219], v150 offset:5120
	ds_read_b128 v[220:223], v150 offset:6144
	ds_read_b128 v[224:227], v150 offset:7168
	global_load_lds_dwordx4 v[146:147], off
	v_lshl_add_u64 v[146:147], s[34:35], 0, v[140:141]
	s_add_i32 m0, s92, 0xe000
	s_nop 0
	global_load_lds_dwordx4 v[146:147], off
	s_waitcnt vmcnt(8)
	s_waitcnt lgkmcnt(0)
	s_setprio 1
	s_barrier
	v_mfma_f32_16x16x32_bf16 v[126:129], v[142:145], v[180:183], v[126:129]
	v_mfma_f32_16x16x32_bf16 v[122:125], v[156:159], v[180:183], v[122:125]
	v_mfma_f32_16x16x32_bf16 v[110:113], v[142:145], v[188:191], v[110:113]
	v_mfma_f32_16x16x32_bf16 v[106:109], v[156:159], v[188:191], v[106:109]
	v_mfma_f32_16x16x32_bf16 v[94:97], v[142:145], v[212:215], v[94:97]
	v_mfma_f32_16x16x32_bf16 v[90:93], v[156:159], v[212:215], v[90:93]
	v_mfma_f32_16x16x32_bf16 v[78:81], v[142:145], v[220:223], v[78:81]
	v_mfma_f32_16x16x32_bf16 v[74:77], v[156:159], v[220:223], v[74:77]
	v_mfma_f32_16x16x32_bf16 v[126:129], v[152:155], v[184:187], v[126:129]
	v_mfma_f32_16x16x32_bf16 v[122:125], v[160:163], v[184:187], v[122:125]
	v_mfma_f32_16x16x32_bf16 v[110:113], v[152:155], v[192:195], v[110:113]
	v_mfma_f32_16x16x32_bf16 v[106:109], v[160:163], v[192:195], v[106:109]
	v_mfma_f32_16x16x32_bf16 v[94:97], v[152:155], v[216:219], v[94:97]
	v_mfma_f32_16x16x32_bf16 v[90:93], v[160:163], v[216:219], v[90:93]
	v_mfma_f32_16x16x32_bf16 v[78:81], v[152:155], v[224:227], v[78:81]
	v_mfma_f32_16x16x32_bf16 v[74:77], v[160:163], v[224:227], v[74:77]
	s_setprio 0
	s_setprio 1
	v_mfma_f32_16x16x32_bf16 v[118:121], v[164:167], v[180:183], v[118:121]
	v_mfma_f32_16x16x32_bf16 v[114:117], v[172:175], v[180:183], v[114:117]
	v_mfma_f32_16x16x32_bf16 v[102:105], v[164:167], v[188:191], v[102:105]
	v_mfma_f32_16x16x32_bf16 v[98:101], v[172:175], v[188:191], v[98:101]
	v_mfma_f32_16x16x32_bf16 v[86:89], v[164:167], v[212:215], v[86:89]
	v_mfma_f32_16x16x32_bf16 v[82:85], v[172:175], v[212:215], v[82:85]
	v_mfma_f32_16x16x32_bf16 v[70:73], v[164:167], v[220:223], v[70:73]
	v_mfma_f32_16x16x32_bf16 v[66:69], v[172:175], v[220:223], v[66:69]
	v_mfma_f32_16x16x32_bf16 v[118:121], v[168:171], v[184:187], v[118:121]
	v_mfma_f32_16x16x32_bf16 v[114:117], v[176:179], v[184:187], v[114:117]
	v_mfma_f32_16x16x32_bf16 v[102:105], v[168:171], v[192:195], v[102:105]
	v_mfma_f32_16x16x32_bf16 v[98:101], v[176:179], v[192:195], v[98:101]
	v_mfma_f32_16x16x32_bf16 v[86:89], v[168:171], v[216:219], v[86:89]
	v_mfma_f32_16x16x32_bf16 v[82:85], v[176:179], v[216:219], v[82:85]
	v_mfma_f32_16x16x32_bf16 v[70:73], v[168:171], v[224:227], v[70:73]
	v_mfma_f32_16x16x32_bf16 v[66:69], v[176:179], v[224:227], v[66:69]
	s_setprio 0
	s_barrier
	s_add_i32 s40, s40, s79
	v_lshl_add_u64 v[146:147], s[36:37], 0, v[132:133]
	s_mov_b32 m0, s40
	ds_read_b128 v[180:183], v150 offset:16384
	ds_read_b128 v[184:187], v150 offset:17408
	ds_read_b128 v[188:191], v150 offset:18432
	ds_read_b128 v[192:195], v150 offset:19456
	ds_read_b128 v[212:215], v150 offset:20480
	ds_read_b128 v[216:219], v150 offset:21504
	ds_read_b128 v[220:223], v150 offset:22528
	ds_read_b128 v[224:227], v150 offset:23552
	global_load_lds_dwordx4 v[146:147], off
	s_add_i32 m0, s40, 0x2000
	s_add_u32 s40, s36, 0x80000
	v_lshl_add_u64 v[200:201], s[36:37], 0, v[136:137]
	s_addc_u32 s41, s37, 0
	s_add_i32 s42, s42, s79
	global_load_lds_dwordx4 v[200:201], off
	v_lshl_add_u64 v[202:203], s[40:41], 0, v[132:133]
	s_mov_b32 m0, s42
	v_lshl_add_u64 v[208:209], s[38:39], 0, v[134:135]
	global_load_lds_dwordx4 v[202:203], off
	v_lshl_add_u64 v[202:203], s[40:41], 0, v[136:137]
	s_add_i32 m0, s42, 0x2000
	s_nop 0
	global_load_lds_dwordx4 v[202:203], off
	v_lshl_add_u64 v[202:203], s[38:39], 0, v[130:131]
	s_mov_b32 m0, s92
	s_nop 0
	global_load_lds_dwordx4 v[202:203], off
	s_mov_b32 m0, s93
	s_nop 0
	global_load_lds_dwordx4 v[208:209], off
	s_waitcnt vmcnt(8)
	s_waitcnt lgkmcnt(0)
	s_setprio 1
	s_barrier
; #define PG8_STAGE(bufoff, gbase, voff) do { _Pragma("unroll") for (int _i = 0; _i < 2; ++_i) \
;         __builtin_amdgcn_global_load_lds((const unsigned*)((const char*)(gbase) + (voff)[_i]), (PG8_LAS unsigned*)(lds + (bufoff) + ldsw + _i * 8192), 16, 0, 0); } while (0)
; #define PG8_LDA(dst, b, h) do { _Pragma("unroll") for (int m = 0; m < 4; ++m) _Pragma("unroll") for (int k = 0; k < 2; ++k) dst[m][k] = *(const PG8_LAS bf16x8*)(lds + PG8_SA(b, h) + aoff + m * 2048 + k * 1024); } while (0)
; #define PG8_LDB(dst, b, h) do { _Pragma("unroll") for (int n = 0; n < 2; ++n) _Pragma("unroll") for (int k = 0; k < 2; ++k) dst[n][k] = *(const PG8_LAS bf16x8*)(lds + PG8_SB(b, h) + boff + n * 2048 + k * 1024); } while (0)
; #define PG8_MMA(ai, bj, At, Bt) do { __builtin_amdgcn_s_setprio(1); _Pragma("unroll") for (int m = 0; m < 4; ++m) _Pragma("unroll") for (int n = 0; n < 2; ++n) _Pragma("unroll") for (int k = 0; k < 2; ++k) \
;         acc[ai][bj][m][n] = __builtin_amdgcn_mfma_f32_16x16x32_bf16(Bt[n][k], At[m][k], acc[ai][bj][m][n], 0, 0, 0); __builtin_amdgcn_s_setprio(0); } while (0)
; #define PG8_WAIT_V(n) asm volatile("s_waitcnt vmcnt(" #n ")" ::: "memory")
; #define PG8_WAIT_L(n) asm volatile("s_waitcnt lgkmcnt(" #n ")" ::: "memory")
; #define PG8_BAR __builtin_amdgcn_s_barrier()
; #define PG8_SCHED __builtin_amdgcn_sched_barrier(0)
; template <class Epi, class Sched, bool ALIGN_EPI = false, bool SP2 = false>
; __device__ __forceinline__ void gemm_phase(PG8_LAS unsigned char* lds, const Gemm g, const Sched& S, const Epi& E, const int wid) {
;     ...
;             PG8_WAIT_V(8); PG8_WAIT_L(0); PG8_BAR; PG8_MMA(1, 0, At, B0); PG8_MMA(1, 1, At, B1); PG8_BAR; PG8_SCHED;
;             PG8_LDB(B0, 1, 0); PG8_LDB(B1, 1, 1); PG8_SCHED; PG8_LDA(At, 1, 0); PG8_STAGE(PG8_SA(0, 1), a2 + hstep, voffA);
;             PG8_WAIT_V(8); PG8_WAIT_L(0); PG8_BAR; PG8_MMA(0, 0, At, B0); PG8_MMA(0, 1, At, B1); PG8_BAR; PG8_SCHED;
	v_mfma_f32_16x16x32_bf16 v[62:65], v[142:145], v[180:183], v[62:65]
	v_mfma_f32_16x16x32_bf16 v[58:61], v[156:159], v[180:183], v[58:61]
	v_mfma_f32_16x16x32_bf16 v[46:49], v[142:145], v[188:191], v[46:49]
	v_mfma_f32_16x16x32_bf16 v[42:45], v[156:159], v[188:191], v[42:45]
	v_mfma_f32_16x16x32_bf16 v[30:33], v[142:145], v[212:215], v[30:33]
	v_mfma_f32_16x16x32_bf16 v[26:29], v[156:159], v[212:215], v[26:29]
	v_mfma_f32_16x16x32_bf16 v[14:17], v[142:145], v[220:223], v[14:17]
	v_mfma_f32_16x16x32_bf16 v[10:13], v[156:159], v[220:223], v[10:13]
	v_mfma_f32_16x16x32_bf16 v[62:65], v[152:155], v[184:187], v[62:65]
	v_mfma_f32_16x16x32_bf16 v[58:61], v[160:163], v[184:187], v[58:61]
	v_mfma_f32_16x16x32_bf16 v[46:49], v[152:155], v[192:195], v[46:49]
	v_mfma_f32_16x16x32_bf16 v[42:45], v[160:163], v[192:195], v[42:45]
	v_mfma_f32_16x16x32_bf16 v[30:33], v[152:155], v[216:219], v[30:33]
	v_mfma_f32_16x16x32_bf16 v[26:29], v[160:163], v[216:219], v[26:29]
	v_mfma_f32_16x16x32_bf16 v[14:17], v[152:155], v[224:227], v[14:17]
	v_mfma_f32_16x16x32_bf16 v[10:13], v[160:163], v[224:227], v[10:13]
	s_setprio 0
	s_setprio 1
	v_mfma_f32_16x16x32_bf16 v[54:57], v[164:167], v[180:183], v[54:57]
	v_mfma_f32_16x16x32_bf16 v[50:53], v[172:175], v[180:183], v[50:53]
	v_mfma_f32_16x16x32_bf16 v[38:41], v[164:167], v[188:191], v[38:41]
	v_mfma_f32_16x16x32_bf16 v[34:37], v[172:175], v[188:191], v[34:37]
	v_mfma_f32_16x16x32_bf16 v[22:25], v[164:167], v[212:215], v[22:25]
	v_mfma_f32_16x16x32_bf16 v[18:21], v[172:175], v[212:215], v[18:21]
	v_mfma_f32_16x16x32_bf16 v[6:9], v[164:167], v[220:223], v[6:9]
	v_mfma_f32_16x16x32_bf16 v[2:5], v[172:175], v[220:223], v[2:5]
	v_mfma_f32_16x16x32_bf16 v[54:57], v[168:171], v[184:187], v[54:57]
	v_mfma_f32_16x16x32_bf16 v[50:53], v[176:179], v[184:187], v[50:53]
	v_mfma_f32_16x16x32_bf16 v[38:41], v[168:171], v[192:195], v[38:41]
	v_mfma_f32_16x16x32_bf16 v[34:37], v[176:179], v[192:195], v[34:37]
	v_mfma_f32_16x16x32_bf16 v[22:25], v[168:171], v[216:219], v[22:25]
	v_mfma_f32_16x16x32_bf16 v[18:21], v[176:179], v[216:219], v[18:21]
	v_mfma_f32_16x16x32_bf16 v[6:9], v[168:171], v[224:227], v[6:9]
	v_mfma_f32_16x16x32_bf16 v[2:5], v[176:179], v[224:227], v[2:5]
	s_setprio 0
	s_barrier
	s_add_i32 s40, 0, 0x18000
	v_add_u32_e32 v0, s40, v149
	s_add_i32 s41, 0, 0x1c000
	ds_read_b128 v[142:145], v0
	ds_read_b128 v[152:155], v0 offset:1024
	ds_read_b128 v[156:159], v0 offset:2048
	ds_read_b128 v[160:163], v0 offset:3072
	v_add_u32_e32 v0, s41, v149
	ds_read_b128 v[164:167], v0
	ds_read_b128 v[168:171], v0 offset:1024
	ds_read_b128 v[172:175], v0 offset:2048
	ds_read_b128 v[176:179], v0 offset:3072
	s_add_u32 s38, s38, 0x80000
	s_addc_u32 s39, s39, 0
	s_mov_b32 m0, s94
	v_lshl_add_u64 v[210:211], s[38:39], 0, v[130:131]
	ds_read_b128 v[180:183], v150 offset:32768
	ds_read_b128 v[184:187], v150 offset:33792
	ds_read_b128 v[188:191], v150 offset:34816
	ds_read_b128 v[192:195], v150 offset:35840
	ds_read_b128 v[212:215], v150 offset:36864
	ds_read_b128 v[216:219], v150 offset:37888
	ds_read_b128 v[220:223], v150 offset:38912
	ds_read_b128 v[224:227], v150 offset:39936
	global_load_lds_dwordx4 v[210:211], off
	v_lshl_add_u64 v[210:211], s[38:39], 0, v[134:135]
	s_mov_b32 m0, s95
	s_nop 0
	global_load_lds_dwordx4 v[210:211], off
	s_waitcnt vmcnt(8)
	s_waitcnt lgkmcnt(0)
	s_setprio 1
	s_barrier
	v_mfma_f32_16x16x32_bf16 v[126:129], v[142:145], v[180:183], v[126:129]
	v_mfma_f32_16x16x32_bf16 v[122:125], v[156:159], v[180:183], v[122:125]
	v_mfma_f32_16x16x32_bf16 v[110:113], v[142:145], v[188:191], v[110:113]
	v_mfma_f32_16x16x32_bf16 v[106:109], v[156:159], v[188:191], v[106:109]
	v_mfma_f32_16x16x32_bf16 v[94:97], v[142:145], v[212:215], v[94:97]
	v_mfma_f32_16x16x32_bf16 v[90:93], v[156:159], v[212:215], v[90:93]
	v_mfma_f32_16x16x32_bf16 v[78:81], v[142:145], v[220:223], v[78:81]
	v_mfma_f32_16x16x32_bf16 v[74:77], v[156:159], v[220:223], v[74:77]
	v_mfma_f32_16x16x32_bf16 v[126:129], v[152:155], v[184:187], v[126:129]
	v_mfma_f32_16x16x32_bf16 v[122:125], v[160:163], v[184:187], v[122:125]
	v_mfma_f32_16x16x32_bf16 v[110:113], v[152:155], v[192:195], v[110:113]
	v_mfma_f32_16x16x32_bf16 v[106:109], v[160:163], v[192:195], v[106:109]
	v_mfma_f32_16x16x32_bf16 v[94:97], v[152:155], v[216:219], v[94:97]
	v_mfma_f32_16x16x32_bf16 v[90:93], v[160:163], v[216:219], v[90:93]
	v_mfma_f32_16x16x32_bf16 v[78:81], v[152:155], v[224:227], v[78:81]
	v_mfma_f32_16x16x32_bf16 v[74:77], v[160:163], v[224:227], v[74:77]
	s_setprio 0
	s_setprio 1
	v_mfma_f32_16x16x32_bf16 v[118:121], v[164:167], v[180:183], v[118:121]
	v_mfma_f32_16x16x32_bf16 v[114:117], v[172:175], v[180:183], v[114:117]
	v_mfma_f32_16x16x32_bf16 v[102:105], v[164:167], v[188:191], v[102:105]
	v_mfma_f32_16x16x32_bf16 v[98:101], v[172:175], v[188:191], v[98:101]
	v_mfma_f32_16x16x32_bf16 v[86:89], v[164:167], v[212:215], v[86:89]
	v_mfma_f32_16x16x32_bf16 v[82:85], v[172:175], v[212:215], v[82:85]
	v_mfma_f32_16x16x32_bf16 v[70:73], v[164:167], v[220:223], v[70:73]
	v_mfma_f32_16x16x32_bf16 v[66:69], v[172:175], v[220:223], v[66:69]
	v_mfma_f32_16x16x32_bf16 v[118:121], v[168:171], v[184:187], v[118:121]
	v_mfma_f32_16x16x32_bf16 v[114:117], v[176:179], v[184:187], v[114:117]
	v_mfma_f32_16x16x32_bf16 v[102:105], v[168:171], v[192:195], v[102:105]
	v_mfma_f32_16x16x32_bf16 v[98:101], v[176:179], v[192:195], v[98:101]
	v_mfma_f32_16x16x32_bf16 v[86:89], v[168:171], v[216:219], v[86:89]
	v_mfma_f32_16x16x32_bf16 v[82:85], v[176:179], v[216:219], v[82:85]
	v_mfma_f32_16x16x32_bf16 v[70:73], v[168:171], v[224:227], v[70:73]
	v_mfma_f32_16x16x32_bf16 v[66:69], v[176:179], v[224:227], v[66:69]
	s_setprio 0
	s_barrier
; #define PG8_STAGE(bufoff, gbase, voff) do { _Pragma("unroll") for (int _i = 0; _i < 2; ++_i) \
;         __builtin_amdgcn_global_load_lds((const unsigned*)((const char*)(gbase) + (voff)[_i]), (PG8_LAS unsigned*)(lds + (bufoff) + ldsw + _i * 8192), 16, 0, 0); } while (0)
; #define PG8_LDA(dst, b, h) do { _Pragma("unroll") for (int m = 0; m < 4; ++m) _Pragma("unroll") for (int k = 0; k < 2; ++k) dst[m][k] = *(const PG8_LAS bf16x8*)(lds + PG8_SA(b, h) + aoff + m * 2048 + k * 1024); } while (0)
; #define PG8_MMA(ai, bj, At, Bt) do { __builtin_amdgcn_s_setprio(1); _Pragma("unroll") for (int m = 0; m < 4; ++m) _Pragma("unroll") for (int n = 0; n < 2; ++n) _Pragma("unroll") for (int k = 0; k < 2; ++k) \
;         acc[ai][bj][m][n] = __builtin_amdgcn_mfma_f32_16x16x32_bf16(Bt[n][k], At[m][k], acc[ai][bj][m][n], 0, 0, 0); __builtin_amdgcn_s_setprio(0); } while (0)
; #define PG8_WAIT_V(n) asm volatile("s_waitcnt vmcnt(" #n ")" ::: "memory")
; #define PG8_WAIT_L(n) asm volatile("s_waitcnt lgkmcnt(" #n ")" ::: "memory")
; #define PG8_BAR __builtin_amdgcn_s_barrier()
; #define PG8_SCHED __builtin_amdgcn_sched_barrier(0)
; template <class Epi, class Sched, bool ALIGN_EPI = false, bool SP2 = false>
; __device__ __forceinline__ void gemm_phase(PG8_LAS unsigned char* lds, const Gemm g, const Sched& S, const Epi& E, const int wid) {
;     ...
;         for (int t = 0; t < nt; t += 2) {
;     ...
;             PG8_LDA(At, 1, 1); PG8_STAGE(PG8_SB(1, 0), b3, voffB); PG8_STAGE(PG8_SB(1, 1), b3 + hstep, voffB); PG8_STAGE(PG8_SA(1, 0), a3, voffA);
;             PG8_WAIT_V(8); PG8_WAIT_L(0); PG8_BAR; PG8_MMA(1, 0, At, B0); PG8_MMA(1, 1, At, B1); PG8_BAR; PG8_SCHED;
;     ...
;         if constexpr (ALIGN_EPI) { if (wr == 0) PG8_BAR; }
	s_add_i32 s38, s40, s79
	v_lshl_add_u64 v[146:147], v[146:147], 0, s[58:59]
	s_mov_b32 m0, s38
	ds_read_b128 v[180:183], v150 offset:49152
	ds_read_b128 v[184:187], v150 offset:50176
	ds_read_b128 v[188:191], v150 offset:51200
	ds_read_b128 v[192:195], v150 offset:52224
	ds_read_b128 v[212:215], v150 offset:53248
	ds_read_b128 v[216:219], v150 offset:54272
	ds_read_b128 v[220:223], v150 offset:55296
	ds_read_b128 v[224:227], v150 offset:56320
	global_load_lds_dwordx4 v[146:147], off
	s_add_i32 m0, s38, 0x2000
	s_add_u32 s36, s36, 0x80080
	v_lshl_add_u64 v[146:147], v[200:201], 0, s[58:59]
	s_addc_u32 s37, s37, 0
	s_add_i32 s38, s41, s79
	global_load_lds_dwordx4 v[146:147], off
	v_lshl_add_u64 v[146:147], s[36:37], 0, v[132:133]
	s_mov_b32 m0, s38
	s_nop 0
	global_load_lds_dwordx4 v[146:147], off
	v_lshl_add_u64 v[146:147], s[36:37], 0, v[136:137]
	s_add_i32 m0, s38, 0x2000
	s_nop 0
	global_load_lds_dwordx4 v[146:147], off
	v_lshl_add_u64 v[146:147], v[202:203], 0, s[58:59]
	s_mov_b32 m0, s96
	s_nop 0
	global_load_lds_dwordx4 v[146:147], off
	v_lshl_add_u64 v[146:147], v[208:209], 0, s[58:59]
	s_mov_b32 m0, s97
	s_nop 0
	global_load_lds_dwordx4 v[146:147], off
	s_waitcnt vmcnt(8)
	s_waitcnt lgkmcnt(0)
	s_setprio 1
	s_barrier
	v_mfma_f32_16x16x32_bf16 v[62:65], v[142:145], v[180:183], v[62:65]
	v_mfma_f32_16x16x32_bf16 v[58:61], v[156:159], v[180:183], v[58:61]
	v_mfma_f32_16x16x32_bf16 v[46:49], v[142:145], v[188:191], v[46:49]
	v_mfma_f32_16x16x32_bf16 v[42:45], v[156:159], v[188:191], v[42:45]
	v_mfma_f32_16x16x32_bf16 v[30:33], v[142:145], v[212:215], v[30:33]
	v_mfma_f32_16x16x32_bf16 v[26:29], v[156:159], v[212:215], v[26:29]
	v_mfma_f32_16x16x32_bf16 v[14:17], v[142:145], v[220:223], v[14:17]
	v_mfma_f32_16x16x32_bf16 v[10:13], v[156:159], v[220:223], v[10:13]
	v_mfma_f32_16x16x32_bf16 v[62:65], v[152:155], v[184:187], v[62:65]
	v_mfma_f32_16x16x32_bf16 v[58:61], v[160:163], v[184:187], v[58:61]
	v_mfma_f32_16x16x32_bf16 v[46:49], v[152:155], v[192:195], v[46:49]
	v_mfma_f32_16x16x32_bf16 v[42:45], v[160:163], v[192:195], v[42:45]
	v_mfma_f32_16x16x32_bf16 v[30:33], v[152:155], v[216:219], v[30:33]
	v_mfma_f32_16x16x32_bf16 v[26:29], v[160:163], v[216:219], v[26:29]
	v_mfma_f32_16x16x32_bf16 v[14:17], v[152:155], v[224:227], v[14:17]
	v_mfma_f32_16x16x32_bf16 v[10:13], v[160:163], v[224:227], v[10:13]
	s_setprio 0
	s_setprio 1
	v_mfma_f32_16x16x32_bf16 v[54:57], v[164:167], v[180:183], v[54:57]
	v_mfma_f32_16x16x32_bf16 v[50:53], v[172:175], v[180:183], v[50:53]
	v_mfma_f32_16x16x32_bf16 v[38:41], v[164:167], v[188:191], v[38:41]
	v_mfma_f32_16x16x32_bf16 v[34:37], v[172:175], v[188:191], v[34:37]
	v_mfma_f32_16x16x32_bf16 v[22:25], v[164:167], v[212:215], v[22:25]
	v_mfma_f32_16x16x32_bf16 v[18:21], v[172:175], v[212:215], v[18:21]
	v_mfma_f32_16x16x32_bf16 v[6:9], v[164:167], v[220:223], v[6:9]
	v_mfma_f32_16x16x32_bf16 v[2:5], v[172:175], v[220:223], v[2:5]
	v_mfma_f32_16x16x32_bf16 v[54:57], v[168:171], v[184:187], v[54:57]
	v_mfma_f32_16x16x32_bf16 v[50:53], v[176:179], v[184:187], v[50:53]
	v_mfma_f32_16x16x32_bf16 v[38:41], v[168:171], v[192:195], v[38:41]
	v_mfma_f32_16x16x32_bf16 v[34:37], v[176:179], v[192:195], v[34:37]
	v_mfma_f32_16x16x32_bf16 v[22:25], v[168:171], v[216:219], v[22:25]
	v_mfma_f32_16x16x32_bf16 v[18:21], v[176:179], v[216:219], v[18:21]
	v_mfma_f32_16x16x32_bf16 v[6:9], v[168:171], v[224:227], v[6:9]
	v_mfma_f32_16x16x32_bf16 v[2:5], v[176:179], v[224:227], v[2:5]
	s_setprio 0
	s_barrier
	s_add_i32 s55, s55, 2
	s_add_u32 s34, s34, 0x100
	s_addc_u32 s35, s35, 0
	s_add_u32 s47, s47, 0x100
	s_addc_u32 s50, s50, 0
	s_cmp_gt_u32 s55, 29
	s_cbranch_scc0 .LBB0_478
	s_and_b64 vcc, exec, s[18:19]
	s_cbranch_vccz .LBB0_481
	s_barrier

; #define PG8_STAGE(bufoff, gbase, voff) do { _Pragma("unroll") for (int _i = 0; _i < 2; ++_i) \
;         __builtin_amdgcn_global_load_lds((const unsigned*)((const char*)(gbase) + (voff)[_i]), (PG8_LAS unsigned*)(lds + (bufoff) + ldsw + _i * 8192), 16, 0, 0); } while (0)
; #define PG8_LDA(dst, b, h) do { _Pragma("unroll") for (int m = 0; m < 4; ++m) _Pragma("unroll") for (int k = 0; k < 2; ++k) dst[m][k] = *(const PG8_LAS bf16x8*)(lds + PG8_SA(b, h) + aoff + m * 2048 + k * 1024); } while (0)
; #define PG8_LDB(dst, b, h) do { _Pragma("unroll") for (int n = 0; n < 2; ++n) _Pragma("unroll") for (int k = 0; k < 2; ++k) dst[n][k] = *(const PG8_LAS bf16x8*)(lds + PG8_SB(b, h) + boff + n * 2048 + k * 1024); } while (0)
; #define PG8_MMA(ai, bj, At, Bt) do { __builtin_amdgcn_s_setprio(1); _Pragma("unroll") for (int m = 0; m < 4; ++m) _Pragma("unroll") for (int n = 0; n < 2; ++n) _Pragma("unroll") for (int k = 0; k < 2; ++k) \
;         acc[ai][bj][m][n] = __builtin_amdgcn_mfma_f32_16x16x32_bf16(Bt[n][k], At[m][k], acc[ai][bj][m][n], 0, 0, 0); __builtin_amdgcn_s_setprio(0); } while (0)
; #define PG8_WAIT_V(n) asm volatile("s_waitcnt vmcnt(" #n ")" ::: "memory")
; #define PG8_WAIT_L(n) asm volatile("s_waitcnt lgkmcnt(" #n ")" ::: "memory")
; template <class Epi, class Sched, bool ALIGN_EPI = false, bool SP2 = false>
; __device__ __forceinline__ void gemm_phase(PG8_LAS unsigned char* lds, const Gemm g, const Sched& S, const Epi& E, const int wid) {
;     ...
;             const bool last = (t == nt - 2);
;             const char* a1 = cA + (size_t)(t + 1) * kstep;
;             const char* a2 = last ? nA : cA + (size_t)(t + 2) * kstep; const char* b2 = last ? nB : cB + (size_t)(t + 2) * kstep;
;             const char* a3 = a2 + kstep; const char* b3 = b2 + kstep;
;             if (last && has_next) S.a_ready(nxt);
;             if constexpr (SP2) {
;             PG8_LDB(B0, 0, 0); PG8_LDB(B1, 0, 1); PG8_SCHED; PG8_LDA(At, 0, 0); PG8_STAGE(PG8_SA(1, 1), a1 + hstep, voffA);
;             PG8_WAIT_V(8); PG8_WAIT_L(0); PG8_BAR; PG8_MMA(0, 0, At, B0); PG8_MMA(0, 1, At, B1); PG8_BAR; PG8_SCHED;
;             PG8_LDA(At, 0, 1); PG8_STAGE(PG8_SB(0, 0), b2, voffB); PG8_STAGE(PG8_SB(0, 1), b2 + hstep, voffB); PG8_STAGE(PG8_SA(0, 0), a2, voffA);
;             PG8_WAIT_V(8); PG8_WAIT_L(0); PG8_BAR; PG8_MMA(1, 0, At, B0); PG8_MMA(1, 1, At, B1); PG8_BAR; PG8_SCHED;
.LBB0_500:
	s_add_u32 s36, s34, 0xfff80080
	s_addc_u32 s37, s35, -1
	s_add_i32 s40, 0, 0x10000
	s_cmp_eq_u32 s55, 28
	s_cselect_b32 s39, s25, s37
	s_cselect_b32 s38, s31, s36
	v_add_u32_e32 v0, s40, v149
	s_cselect_b32 s37, s23, s50
	s_cselect_b32 s36, s46, s47
	s_add_i32 s42, 0, 0x14000
	ds_read_b128 v[142:145], v0
	ds_read_b128 v[152:155], v0 offset:1024
	ds_read_b128 v[156:159], v0 offset:2048
	ds_read_b128 v[160:163], v0 offset:3072
	v_add_u32_e32 v0, s42, v149
	ds_read_b128 v[164:167], v0
	ds_read_b128 v[168:171], v0 offset:1024
	ds_read_b128 v[172:175], v0 offset:2048
	ds_read_b128 v[176:179], v0 offset:3072
	v_lshl_add_u64 v[146:147], s[34:35], 0, v[138:139]
	s_add_i32 m0, s92, 0xc000
	ds_read_b128 v[180:183], v150
	ds_read_b128 v[184:187], v150 offset:1024
	ds_read_b128 v[188:191], v150 offset:2048
	ds_read_b128 v[192:195], v150 offset:3072
	ds_read_b128 v[212:215], v150 offset:4096
	ds_read_b128 v[216:219], v150 offset:5120
	ds_read_b128 v[220:223], v150 offset:6144
	ds_read_b128 v[224:227], v150 offset:7168
	global_load_lds_dwordx4 v[146:147], off
	v_lshl_add_u64 v[146:147], s[34:35], 0, v[140:141]
	s_add_i32 m0, s92, 0xe000
	s_nop 0
	global_load_lds_dwordx4 v[146:147], off
	s_waitcnt vmcnt(8)
	s_waitcnt lgkmcnt(0)
	s_setprio 1
	s_barrier
	v_mfma_f32_16x16x32_bf16 v[126:129], v[142:145], v[180:183], v[126:129]
	v_mfma_f32_16x16x32_bf16 v[122:125], v[156:159], v[180:183], v[122:125]
	v_mfma_f32_16x16x32_bf16 v[110:113], v[142:145], v[188:191], v[110:113]
	v_mfma_f32_16x16x32_bf16 v[106:109], v[156:159], v[188:191], v[106:109]
	v_mfma_f32_16x16x32_bf16 v[94:97], v[142:145], v[212:215], v[94:97]
	v_mfma_f32_16x16x32_bf16 v[90:93], v[156:159], v[212:215], v[90:93]
	v_mfma_f32_16x16x32_bf16 v[78:81], v[142:145], v[220:223], v[78:81]
	v_mfma_f32_16x16x32_bf16 v[74:77], v[156:159], v[220:223], v[74:77]
	v_mfma_f32_16x16x32_bf16 v[126:129], v[152:155], v[184:187], v[126:129]
	v_mfma_f32_16x16x32_bf16 v[122:125], v[160:163], v[184:187], v[122:125]
	v_mfma_f32_16x16x32_bf16 v[110:113], v[152:155], v[192:195], v[110:113]
	v_mfma_f32_16x16x32_bf16 v[106:109], v[160:163], v[192:195], v[106:109]
	v_mfma_f32_16x16x32_bf16 v[94:97], v[152:155], v[216:219], v[94:97]
	v_mfma_f32_16x16x32_bf16 v[90:93], v[160:163], v[216:219], v[90:93]
	v_mfma_f32_16x16x32_bf16 v[78:81], v[152:155], v[224:227], v[78:81]
	v_mfma_f32_16x16x32_bf16 v[74:77], v[160:163], v[224:227], v[74:77]
	s_setprio 0
	s_setprio 1
	v_mfma_f32_16x16x32_bf16 v[118:121], v[164:167], v[180:183], v[118:121]
	v_mfma_f32_16x16x32_bf16 v[114:117], v[172:175], v[180:183], v[114:117]
	v_mfma_f32_16x16x32_bf16 v[102:105], v[164:167], v[188:191], v[102:105]
	v_mfma_f32_16x16x32_bf16 v[98:101], v[172:175], v[188:191], v[98:101]
	v_mfma_f32_16x16x32_bf16 v[86:89], v[164:167], v[212:215], v[86:89]
	v_mfma_f32_16x16x32_bf16 v[82:85], v[172:175], v[212:215], v[82:85]
	v_mfma_f32_16x16x32_bf16 v[70:73], v[164:167], v[220:223], v[70:73]
	v_mfma_f32_16x16x32_bf16 v[66:69], v[172:175], v[220:223], v[66:69]
	v_mfma_f32_16x16x32_bf16 v[118:121], v[168:171], v[184:187], v[118:121]
	v_mfma_f32_16x16x32_bf16 v[114:117], v[176:179], v[184:187], v[114:117]
	v_mfma_f32_16x16x32_bf16 v[102:105], v[168:171], v[192:195], v[102:105]
	v_mfma_f32_16x16x32_bf16 v[98:101], v[176:179], v[192:195], v[98:101]
	v_mfma_f32_16x16x32_bf16 v[86:89], v[168:171], v[216:219], v[86:89]
	v_mfma_f32_16x16x32_bf16 v[82:85], v[176:179], v[216:219], v[82:85]
	v_mfma_f32_16x16x32_bf16 v[70:73], v[168:171], v[224:227], v[70:73]
	v_mfma_f32_16x16x32_bf16 v[66:69], v[176:179], v[224:227], v[66:69]
	s_setprio 0
	s_barrier
	s_add_i32 s40, s40, s79
	v_lshl_add_u64 v[146:147], s[36:37], 0, v[134:135]
	s_mov_b32 m0, s40
	ds_read_b128 v[180:183], v150 offset:16384
	ds_read_b128 v[184:187], v150 offset:17408
	ds_read_b128 v[188:191], v150 offset:18432
	ds_read_b128 v[192:195], v150 offset:19456
	ds_read_b128 v[212:215], v150 offset:20480
	ds_read_b128 v[216:219], v150 offset:21504
	ds_read_b128 v[220:223], v150 offset:22528
	ds_read_b128 v[224:227], v150 offset:23552
	global_load_lds_dwordx4 v[146:147], off
	s_add_i32 m0, s40, 0x2000
	s_add_u32 s40, s36, 0x80000
	v_lshl_add_u64 v[200:201], s[36:37], 0, v[130:131]
	s_addc_u32 s41, s37, 0
	s_add_i32 s42, s42, s79
	global_load_lds_dwordx4 v[200:201], off
	v_lshl_add_u64 v[202:203], s[40:41], 0, v[134:135]
	s_mov_b32 m0, s42
	v_lshl_add_u64 v[208:209], s[38:39], 0, v[132:133]
	global_load_lds_dwordx4 v[202:203], off
	v_lshl_add_u64 v[202:203], s[40:41], 0, v[130:131]
	s_add_i32 m0, s42, 0x2000
	s_nop 0
	global_load_lds_dwordx4 v[202:203], off
	v_lshl_add_u64 v[202:203], s[38:39], 0, v[136:137]
	s_mov_b32 m0, s92
	s_nop 0
	global_load_lds_dwordx4 v[202:203], off
	s_mov_b32 m0, s93
	s_nop 0
	global_load_lds_dwordx4 v[208:209], off
	s_waitcnt vmcnt(8)
	s_waitcnt lgkmcnt(0)
	s_setprio 1
	s_barrier
; #define PG8_STAGE(bufoff, gbase, voff) do { _Pragma("unroll") for (int _i = 0; _i < 2; ++_i) \
;         __builtin_amdgcn_global_load_lds((const unsigned*)((const char*)(gbase) + (voff)[_i]), (PG8_LAS unsigned*)(lds + (bufoff) + ldsw + _i * 8192), 16, 0, 0); } while (0)
; #define PG8_LDA(dst, b, h) do { _Pragma("unroll") for (int m = 0; m < 4; ++m) _Pragma("unroll") for (int k = 0; k < 2; ++k) dst[m][k] = *(const PG8_LAS bf16x8*)(lds + PG8_SA(b, h) + aoff + m * 2048 + k * 1024); } while (0)
; #define PG8_LDB(dst, b, h) do { _Pragma("unroll") for (int n = 0; n < 2; ++n) _Pragma("unroll") for (int k = 0; k < 2; ++k) dst[n][k] = *(const PG8_LAS bf16x8*)(lds + PG8_SB(b, h) + boff + n * 2048 + k * 1024); } while (0)
; #define PG8_MMA(ai, bj, At, Bt) do { __builtin_amdgcn_s_setprio(1); _Pragma("unroll") for (int m = 0; m < 4; ++m) _Pragma("unroll") for (int n = 0; n < 2; ++n) _Pragma("unroll") for (int k = 0; k < 2; ++k) \
;         acc[ai][bj][m][n] = __builtin_amdgcn_mfma_f32_16x16x32_bf16(Bt[n][k], At[m][k], acc[ai][bj][m][n], 0, 0, 0); __builtin_amdgcn_s_setprio(0); } while (0)
; #define PG8_WAIT_V(n) asm volatile("s_waitcnt vmcnt(" #n ")" ::: "memory")
; #define PG8_WAIT_L(n) asm volatile("s_waitcnt lgkmcnt(" #n ")" ::: "memory")
; #define PG8_BAR __builtin_amdgcn_s_barrier()
; #define PG8_SCHED __builtin_amdgcn_sched_barrier(0)
; template <class Epi, class Sched, bool ALIGN_EPI = false, bool SP2 = false>
; __device__ __forceinline__ void gemm_phase(PG8_LAS unsigned char* lds, const Gemm g, const Sched& S, const Epi& E, const int wid) {
;     ...
;             PG8_WAIT_V(8); PG8_WAIT_L(0); PG8_BAR; PG8_MMA(1, 0, At, B0); PG8_MMA(1, 1, At, B1); PG8_BAR; PG8_SCHED;
;             PG8_LDB(B0, 1, 0); PG8_LDB(B1, 1, 1); PG8_SCHED; PG8_LDA(At, 1, 0); PG8_STAGE(PG8_SA(0, 1), a2 + hstep, voffA);
;             PG8_WAIT_V(8); PG8_WAIT_L(0); PG8_BAR; PG8_MMA(0, 0, At, B0); PG8_MMA(0, 1, At, B1); PG8_BAR; PG8_SCHED;
	v_mfma_f32_16x16x32_bf16 v[62:65], v[142:145], v[180:183], v[62:65]
	v_mfma_f32_16x16x32_bf16 v[58:61], v[156:159], v[180:183], v[58:61]
	v_mfma_f32_16x16x32_bf16 v[46:49], v[142:145], v[188:191], v[46:49]
	v_mfma_f32_16x16x32_bf16 v[42:45], v[156:159], v[188:191], v[42:45]
	v_mfma_f32_16x16x32_bf16 v[30:33], v[142:145], v[212:215], v[30:33]
	v_mfma_f32_16x16x32_bf16 v[26:29], v[156:159], v[212:215], v[26:29]
	v_mfma_f32_16x16x32_bf16 v[14:17], v[142:145], v[220:223], v[14:17]
	v_mfma_f32_16x16x32_bf16 v[10:13], v[156:159], v[220:223], v[10:13]
	v_mfma_f32_16x16x32_bf16 v[62:65], v[152:155], v[184:187], v[62:65]
	v_mfma_f32_16x16x32_bf16 v[58:61], v[160:163], v[184:187], v[58:61]
	v_mfma_f32_16x16x32_bf16 v[46:49], v[152:155], v[192:195], v[46:49]
	v_mfma_f32_16x16x32_bf16 v[42:45], v[160:163], v[192:195], v[42:45]
	v_mfma_f32_16x16x32_bf16 v[30:33], v[152:155], v[216:219], v[30:33]
	v_mfma_f32_16x16x32_bf16 v[26:29], v[160:163], v[216:219], v[26:29]
	v_mfma_f32_16x16x32_bf16 v[14:17], v[152:155], v[224:227], v[14:17]
	v_mfma_f32_16x16x32_bf16 v[10:13], v[160:163], v[224:227], v[10:13]
	s_setprio 0
	s_setprio 1
	v_mfma_f32_16x16x32_bf16 v[54:57], v[164:167], v[180:183], v[54:57]
	v_mfma_f32_16x16x32_bf16 v[50:53], v[172:175], v[180:183], v[50:53]
	v_mfma_f32_16x16x32_bf16 v[38:41], v[164:167], v[188:191], v[38:41]
	v_mfma_f32_16x16x32_bf16 v[34:37], v[172:175], v[188:191], v[34:37]
	v_mfma_f32_16x16x32_bf16 v[22:25], v[164:167], v[212:215], v[22:25]
	v_mfma_f32_16x16x32_bf16 v[18:21], v[172:175], v[212:215], v[18:21]
	v_mfma_f32_16x16x32_bf16 v[6:9], v[164:167], v[220:223], v[6:9]
	v_mfma_f32_16x16x32_bf16 v[2:5], v[172:175], v[220:223], v[2:5]
	v_mfma_f32_16x16x32_bf16 v[54:57], v[168:171], v[184:187], v[54:57]
	v_mfma_f32_16x16x32_bf16 v[50:53], v[176:179], v[184:187], v[50:53]
	v_mfma_f32_16x16x32_bf16 v[38:41], v[168:171], v[192:195], v[38:41]
	v_mfma_f32_16x16x32_bf16 v[34:37], v[176:179], v[192:195], v[34:37]
	v_mfma_f32_16x16x32_bf16 v[22:25], v[168:171], v[216:219], v[22:25]
	v_mfma_f32_16x16x32_bf16 v[18:21], v[176:179], v[216:219], v[18:21]
	v_mfma_f32_16x16x32_bf16 v[6:9], v[168:171], v[224:227], v[6:9]
	v_mfma_f32_16x16x32_bf16 v[2:5], v[176:179], v[224:227], v[2:5]
	s_setprio 0
	s_barrier
	s_add_i32 s40, 0, 0x18000
	v_add_u32_e32 v0, s40, v149
	s_add_i32 s41, 0, 0x1c000
	ds_read_b128 v[142:145], v0
	ds_read_b128 v[152:155], v0 offset:1024
	ds_read_b128 v[156:159], v0 offset:2048
	ds_read_b128 v[160:163], v0 offset:3072
	v_add_u32_e32 v0, s41, v149
	ds_read_b128 v[164:167], v0
	ds_read_b128 v[168:171], v0 offset:1024
	ds_read_b128 v[172:175], v0 offset:2048
	ds_read_b128 v[176:179], v0 offset:3072
	s_add_u32 s38, s38, 0x80000
	s_addc_u32 s39, s39, 0
	s_mov_b32 m0, s94
	v_lshl_add_u64 v[210:211], s[38:39], 0, v[136:137]
	ds_read_b128 v[180:183], v150 offset:32768
	ds_read_b128 v[184:187], v150 offset:33792
	ds_read_b128 v[188:191], v150 offset:34816
	ds_read_b128 v[192:195], v150 offset:35840
	ds_read_b128 v[212:215], v150 offset:36864
	ds_read_b128 v[216:219], v150 offset:37888
	ds_read_b128 v[220:223], v150 offset:38912
	ds_read_b128 v[224:227], v150 offset:39936
	global_load_lds_dwordx4 v[210:211], off
	v_lshl_add_u64 v[210:211], s[38:39], 0, v[132:133]
	s_mov_b32 m0, s95
	s_nop 0
	global_load_lds_dwordx4 v[210:211], off
	s_waitcnt vmcnt(8)
	s_waitcnt lgkmcnt(0)
	s_setprio 1
	s_barrier
	v_mfma_f32_16x16x32_bf16 v[126:129], v[142:145], v[180:183], v[126:129]
	v_mfma_f32_16x16x32_bf16 v[122:125], v[156:159], v[180:183], v[122:125]
	v_mfma_f32_16x16x32_bf16 v[110:113], v[142:145], v[188:191], v[110:113]
	v_mfma_f32_16x16x32_bf16 v[106:109], v[156:159], v[188:191], v[106:109]
	v_mfma_f32_16x16x32_bf16 v[94:97], v[142:145], v[212:215], v[94:97]
	v_mfma_f32_16x16x32_bf16 v[90:93], v[156:159], v[212:215], v[90:93]
	v_mfma_f32_16x16x32_bf16 v[78:81], v[142:145], v[220:223], v[78:81]
	v_mfma_f32_16x16x32_bf16 v[74:77], v[156:159], v[220:223], v[74:77]
	v_mfma_f32_16x16x32_bf16 v[126:129], v[152:155], v[184:187], v[126:129]
	v_mfma_f32_16x16x32_bf16 v[122:125], v[160:163], v[184:187], v[122:125]
	v_mfma_f32_16x16x32_bf16 v[110:113], v[152:155], v[192:195], v[110:113]
	v_mfma_f32_16x16x32_bf16 v[106:109], v[160:163], v[192:195], v[106:109]
	v_mfma_f32_16x16x32_bf16 v[94:97], v[152:155], v[216:219], v[94:97]
	v_mfma_f32_16x16x32_bf16 v[90:93], v[160:163], v[216:219], v[90:93]
	v_mfma_f32_16x16x32_bf16 v[78:81], v[152:155], v[224:227], v[78:81]
	v_mfma_f32_16x16x32_bf16 v[74:77], v[160:163], v[224:227], v[74:77]
	s_setprio 0
	s_setprio 1
	v_mfma_f32_16x16x32_bf16 v[118:121], v[164:167], v[180:183], v[118:121]
	v_mfma_f32_16x16x32_bf16 v[114:117], v[172:175], v[180:183], v[114:117]
	v_mfma_f32_16x16x32_bf16 v[102:105], v[164:167], v[188:191], v[102:105]
	v_mfma_f32_16x16x32_bf16 v[98:101], v[172:175], v[188:191], v[98:101]
	v_mfma_f32_16x16x32_bf16 v[86:89], v[164:167], v[212:215], v[86:89]
	v_mfma_f32_16x16x32_bf16 v[82:85], v[172:175], v[212:215], v[82:85]
	v_mfma_f32_16x16x32_bf16 v[70:73], v[164:167], v[220:223], v[70:73]
	v_mfma_f32_16x16x32_bf16 v[66:69], v[172:175], v[220:223], v[66:69]
	v_mfma_f32_16x16x32_bf16 v[118:121], v[168:171], v[184:187], v[118:121]
	v_mfma_f32_16x16x32_bf16 v[114:117], v[176:179], v[184:187], v[114:117]
	v_mfma_f32_16x16x32_bf16 v[102:105], v[168:171], v[192:195], v[102:105]
	v_mfma_f32_16x16x32_bf16 v[98:101], v[176:179], v[192:195], v[98:101]
	v_mfma_f32_16x16x32_bf16 v[86:89], v[168:171], v[216:219], v[86:89]
	v_mfma_f32_16x16x32_bf16 v[82:85], v[176:179], v[216:219], v[82:85]
	v_mfma_f32_16x16x32_bf16 v[70:73], v[168:171], v[224:227], v[70:73]
	v_mfma_f32_16x16x32_bf16 v[66:69], v[176:179], v[224:227], v[66:69]
	s_setprio 0
	s_barrier
; #define PG8_STAGE(bufoff, gbase, voff) do { _Pragma("unroll") for (int _i = 0; _i < 2; ++_i) \
;         __builtin_amdgcn_global_load_lds((const unsigned*)((const char*)(gbase) + (voff)[_i]), (PG8_LAS unsigned*)(lds + (bufoff) + ldsw + _i * 8192), 16, 0, 0); } while (0)
; #define PG8_LDA(dst, b, h) do { _Pragma("unroll") for (int m = 0; m < 4; ++m) _Pragma("unroll") for (int k = 0; k < 2; ++k) dst[m][k] = *(const PG8_LAS bf16x8*)(lds + PG8_SA(b, h) + aoff + m * 2048 + k * 1024); } while (0)
; #define PG8_MMA(ai, bj, At, Bt) do { __builtin_amdgcn_s_setprio(1); _Pragma("unroll") for (int m = 0; m < 4; ++m) _Pragma("unroll") for (int n = 0; n < 2; ++n) _Pragma("unroll") for (int k = 0; k < 2; ++k) \
;         acc[ai][bj][m][n] = __builtin_amdgcn_mfma_f32_16x16x32_bf16(Bt[n][k], At[m][k], acc[ai][bj][m][n], 0, 0, 0); __builtin_amdgcn_s_setprio(0); } while (0)
; #define PG8_WAIT_V(n) asm volatile("s_waitcnt vmcnt(" #n ")" ::: "memory")
; #define PG8_WAIT_L(n) asm volatile("s_waitcnt lgkmcnt(" #n ")" ::: "memory")
; #define PG8_BAR __builtin_amdgcn_s_barrier()
; #define PG8_SCHED __builtin_amdgcn_sched_barrier(0)
; template <class Epi, class Sched, bool ALIGN_EPI = false, bool SP2 = false>
; __device__ __forceinline__ void gemm_phase(PG8_LAS unsigned char* lds, const Gemm g, const Sched& S, const Epi& E, const int wid) {
;     ...
;         for (int t = 0; t < nt; t += 2) {
;     ...
;             PG8_LDA(At, 1, 1); PG8_STAGE(PG8_SB(1, 0), b3, voffB); PG8_STAGE(PG8_SB(1, 1), b3 + hstep, voffB); PG8_STAGE(PG8_SA(1, 0), a3, voffA);
;             PG8_WAIT_V(8); PG8_WAIT_L(0); PG8_BAR; PG8_MMA(1, 0, At, B0); PG8_MMA(1, 1, At, B1); PG8_BAR; PG8_SCHED;
;     ...
;         if constexpr (ALIGN_EPI) { if (wr == 0) PG8_BAR; }
	s_add_i32 s38, s40, s79
	v_lshl_add_u64 v[146:147], v[146:147], 0, s[58:59]
	s_mov_b32 m0, s38
	ds_read_b128 v[180:183], v150 offset:49152
	ds_read_b128 v[184:187], v150 offset:50176
	ds_read_b128 v[188:191], v150 offset:51200
	ds_read_b128 v[192:195], v150 offset:52224
	ds_read_b128 v[212:215], v150 offset:53248
	ds_read_b128 v[216:219], v150 offset:54272
	ds_read_b128 v[220:223], v150 offset:55296
	ds_read_b128 v[224:227], v150 offset:56320
	global_load_lds_dwordx4 v[146:147], off
	s_add_i32 m0, s38, 0x2000
	s_add_u32 s36, s36, 0x80080
	v_lshl_add_u64 v[146:147], v[200:201], 0, s[58:59]
	s_addc_u32 s37, s37, 0
	s_add_i32 s38, s41, s79
	global_load_lds_dwordx4 v[146:147], off
	v_lshl_add_u64 v[146:147], s[36:37], 0, v[134:135]
	s_mov_b32 m0, s38
	s_nop 0
	global_load_lds_dwordx4 v[146:147], off
	v_lshl_add_u64 v[146:147], s[36:37], 0, v[130:131]
	s_add_i32 m0, s38, 0x2000
	s_nop 0
	global_load_lds_dwordx4 v[146:147], off
	v_lshl_add_u64 v[146:147], v[202:203], 0, s[58:59]
	s_mov_b32 m0, s44
	s_nop 0
	global_load_lds_dwordx4 v[146:147], off
	v_lshl_add_u64 v[146:147], v[208:209], 0, s[58:59]
	s_mov_b32 m0, s68
	s_nop 0
	global_load_lds_dwordx4 v[146:147], off
	s_waitcnt vmcnt(8)
	s_waitcnt lgkmcnt(0)
	s_setprio 1
	s_barrier
	v_mfma_f32_16x16x32_bf16 v[62:65], v[142:145], v[180:183], v[62:65]
	v_mfma_f32_16x16x32_bf16 v[58:61], v[156:159], v[180:183], v[58:61]
	v_mfma_f32_16x16x32_bf16 v[46:49], v[142:145], v[188:191], v[46:49]
	v_mfma_f32_16x16x32_bf16 v[42:45], v[156:159], v[188:191], v[42:45]
	v_mfma_f32_16x16x32_bf16 v[30:33], v[142:145], v[212:215], v[30:33]
	v_mfma_f32_16x16x32_bf16 v[26:29], v[156:159], v[212:215], v[26:29]
	v_mfma_f32_16x16x32_bf16 v[14:17], v[142:145], v[220:223], v[14:17]
	v_mfma_f32_16x16x32_bf16 v[10:13], v[156:159], v[220:223], v[10:13]
	v_mfma_f32_16x16x32_bf16 v[62:65], v[152:155], v[184:187], v[62:65]
	v_mfma_f32_16x16x32_bf16 v[58:61], v[160:163], v[184:187], v[58:61]
	v_mfma_f32_16x16x32_bf16 v[46:49], v[152:155], v[192:195], v[46:49]
	v_mfma_f32_16x16x32_bf16 v[42:45], v[160:163], v[192:195], v[42:45]
	v_mfma_f32_16x16x32_bf16 v[30:33], v[152:155], v[216:219], v[30:33]
	v_mfma_f32_16x16x32_bf16 v[26:29], v[160:163], v[216:219], v[26:29]
	v_mfma_f32_16x16x32_bf16 v[14:17], v[152:155], v[224:227], v[14:17]
	v_mfma_f32_16x16x32_bf16 v[10:13], v[160:163], v[224:227], v[10:13]
	s_setprio 0
	s_setprio 1
	v_mfma_f32_16x16x32_bf16 v[54:57], v[164:167], v[180:183], v[54:57]
	v_mfma_f32_16x16x32_bf16 v[50:53], v[172:175], v[180:183], v[50:53]
	v_mfma_f32_16x16x32_bf16 v[38:41], v[164:167], v[188:191], v[38:41]
	v_mfma_f32_16x16x32_bf16 v[34:37], v[172:175], v[188:191], v[34:37]
	v_mfma_f32_16x16x32_bf16 v[22:25], v[164:167], v[212:215], v[22:25]
	v_mfma_f32_16x16x32_bf16 v[18:21], v[172:175], v[212:215], v[18:21]
	v_mfma_f32_16x16x32_bf16 v[6:9], v[164:167], v[220:223], v[6:9]
	v_mfma_f32_16x16x32_bf16 v[2:5], v[172:175], v[220:223], v[2:5]
	v_mfma_f32_16x16x32_bf16 v[54:57], v[168:171], v[184:187], v[54:57]
	v_mfma_f32_16x16x32_bf16 v[50:53], v[176:179], v[184:187], v[50:53]
	v_mfma_f32_16x16x32_bf16 v[38:41], v[168:171], v[192:195], v[38:41]
	v_mfma_f32_16x16x32_bf16 v[34:37], v[176:179], v[192:195], v[34:37]
	v_mfma_f32_16x16x32_bf16 v[22:25], v[168:171], v[216:219], v[22:25]
	v_mfma_f32_16x16x32_bf16 v[18:21], v[176:179], v[216:219], v[18:21]
	v_mfma_f32_16x16x32_bf16 v[6:9], v[168:171], v[224:227], v[6:9]
	v_mfma_f32_16x16x32_bf16 v[2:5], v[176:179], v[224:227], v[2:5]
	s_setprio 0
	s_barrier
	s_add_i32 s55, s55, 2
	s_add_u32 s34, s34, 0x100
	s_addc_u32 s35, s35, 0
	s_add_u32 s47, s47, 0x100
	s_addc_u32 s50, s50, 0
	s_cmp_gt_u32 s55, 29
	s_cbranch_scc0 .LBB0_500
	s_and_b64 vcc, exec, s[18:19]
	s_cbranch_vccz .LBB0_503
	s_barrier

; #define PG8_STAGE(bufoff, gbase, voff) do { _Pragma("unroll") for (int _i = 0; _i < 2; ++_i) \
;         __builtin_amdgcn_global_load_lds((const unsigned*)((const char*)(gbase) + (voff)[_i]), (PG8_LAS unsigned*)(lds + (bufoff) + ldsw + _i * 8192), 16, 0, 0); } while (0)
; #define PG8_LDA(dst, b, h) do { _Pragma("unroll") for (int m = 0; m < 4; ++m) _Pragma("unroll") for (int k = 0; k < 2; ++k) dst[m][k] = *(const PG8_LAS bf16x8*)(lds + PG8_SA(b, h) + aoff + m * 2048 + k * 1024); } while (0)
; #define PG8_LDB(dst, b, h) do { _Pragma("unroll") for (int n = 0; n < 2; ++n) _Pragma("unroll") for (int k = 0; k < 2; ++k) dst[n][k] = *(const PG8_LAS bf16x8*)(lds + PG8_SB(b, h) + boff + n * 2048 + k * 1024); } while (0)
; #define PG8_MMA(ai, bj, At, Bt) do { __builtin_amdgcn_s_setprio(1); _Pragma("unroll") for (int m = 0; m < 4; ++m) _Pragma("unroll") for (int n = 0; n < 2; ++n) _Pragma("unroll") for (int k = 0; k < 2; ++k) \
;         acc[ai][bj][m][n] = __builtin_amdgcn_mfma_f32_16x16x32_bf16(Bt[n][k], At[m][k], acc[ai][bj][m][n], 0, 0, 0); __builtin_amdgcn_s_setprio(0); } while (0)
; #define PG8_WAIT_V(n) asm volatile("s_waitcnt vmcnt(" #n ")" ::: "memory")
; #define PG8_WAIT_L(n) asm volatile("s_waitcnt lgkmcnt(" #n ")" ::: "memory")
; template <class Epi, class Sched, bool ALIGN_EPI = false, bool SP2 = false>
; __device__ __forceinline__ void gemm_phase(PG8_LAS unsigned char* lds, const Gemm g, const Sched& S, const Epi& E, const int wid) {
;     ...
;             const bool last = (t == nt - 2);
;             const char* a1 = cA + (size_t)(t + 1) * kstep;
;             const char* a2 = last ? nA : cA + (size_t)(t + 2) * kstep; const char* b2 = last ? nB : cB + (size_t)(t + 2) * kstep;
;             const char* a3 = a2 + kstep; const char* b3 = b2 + kstep;
;             if (last && has_next) S.a_ready(nxt);
;             if constexpr (SP2) {
;             PG8_LDB(B0, 0, 0); PG8_LDB(B1, 0, 1); PG8_SCHED; PG8_LDA(At, 0, 0); PG8_STAGE(PG8_SA(1, 1), a1 + hstep, voffA);
;             PG8_WAIT_V(8); PG8_WAIT_L(0); PG8_BAR; PG8_MMA(0, 0, At, B0); PG8_MMA(0, 1, At, B1); PG8_BAR; PG8_SCHED;
;             PG8_LDA(At, 0, 1); PG8_STAGE(PG8_SB(0, 0), b2, voffB); PG8_STAGE(PG8_SB(0, 1), b2 + hstep, voffB); PG8_STAGE(PG8_SA(0, 0), a2, voffA);
;             PG8_WAIT_V(8); PG8_WAIT_L(0); PG8_BAR; PG8_MMA(1, 0, At, B0); PG8_MMA(1, 1, At, B1); PG8_BAR; PG8_SCHED;
.LBB0_530:
	s_add_u32 s30, s28, 0xfff80080
	s_addc_u32 s31, s29, -1
	s_add_i32 s40, 0, 0x10000
	s_cmp_eq_u32 s85, 28
	s_cselect_b32 s35, s21, s31
	s_cselect_b32 s34, s66, s30
	v_add_u32_e32 v0, s40, v163
	s_cselect_b32 s31, s19, s84
	s_cselect_b32 s30, s67, s68
	s_add_i32 s42, 0, 0x14000
	ds_read_b128 v[130:133], v0
	ds_read_b128 v[134:137], v0 offset:1024
	ds_read_b128 v[138:141], v0 offset:2048
	ds_read_b128 v[142:145], v0 offset:3072
	v_add_u32_e32 v0, s42, v163
	ds_read_b128 v[158:161], v0
	ds_read_b128 v[166:169], v0 offset:1024
	ds_read_b128 v[170:173], v0 offset:2048
	ds_read_b128 v[174:177], v0 offset:3072
	v_lshl_add_u64 v[194:195], s[28:29], 0, v[154:155]
	s_add_i32 m0, s27, 0xc000
	ds_read_b128 v[178:181], v164
	ds_read_b128 v[182:185], v164 offset:1024
	ds_read_b128 v[186:189], v164 offset:2048
	ds_read_b128 v[190:193], v164 offset:3072
	ds_read_b128 v[212:215], v164 offset:4096
	ds_read_b128 v[216:219], v164 offset:5120
	ds_read_b128 v[220:223], v164 offset:6144
	ds_read_b128 v[224:227], v164 offset:7168
	global_load_lds_dwordx4 v[194:195], off
	v_lshl_add_u64 v[194:195], s[28:29], 0, v[156:157]
	s_add_i32 m0, s27, 0xe000
	s_nop 0
	global_load_lds_dwordx4 v[194:195], off
	s_waitcnt vmcnt(8)
	s_waitcnt lgkmcnt(0)
	s_setprio 1
	s_barrier
	v_mfma_f32_16x16x32_bf16 v[126:129], v[130:133], v[178:181], v[126:129]
	v_mfma_f32_16x16x32_bf16 v[122:125], v[138:141], v[178:181], v[122:125]
	v_mfma_f32_16x16x32_bf16 v[118:121], v[130:133], v[186:189], v[118:121]
	v_mfma_f32_16x16x32_bf16 v[110:113], v[138:141], v[186:189], v[110:113]
	v_mfma_f32_16x16x32_bf16 v[102:105], v[130:133], v[212:215], v[102:105]
	v_mfma_f32_16x16x32_bf16 v[94:97], v[138:141], v[212:215], v[94:97]
	v_mfma_f32_16x16x32_bf16 v[86:89], v[130:133], v[220:223], v[86:89]
	v_mfma_f32_16x16x32_bf16 v[78:81], v[138:141], v[220:223], v[78:81]
	v_mfma_f32_16x16x32_bf16 v[126:129], v[134:137], v[182:185], v[126:129]
	v_mfma_f32_16x16x32_bf16 v[122:125], v[142:145], v[182:185], v[122:125]
	v_mfma_f32_16x16x32_bf16 v[118:121], v[134:137], v[190:193], v[118:121]
	v_mfma_f32_16x16x32_bf16 v[110:113], v[142:145], v[190:193], v[110:113]
	v_mfma_f32_16x16x32_bf16 v[102:105], v[134:137], v[216:219], v[102:105]
	v_mfma_f32_16x16x32_bf16 v[94:97], v[142:145], v[216:219], v[94:97]
	v_mfma_f32_16x16x32_bf16 v[86:89], v[134:137], v[224:227], v[86:89]
	v_mfma_f32_16x16x32_bf16 v[78:81], v[142:145], v[224:227], v[78:81]
	s_setprio 0
	s_setprio 1
	v_mfma_f32_16x16x32_bf16 v[114:117], v[158:161], v[178:181], v[114:117]
	v_mfma_f32_16x16x32_bf16 v[106:109], v[170:173], v[178:181], v[106:109]
	v_mfma_f32_16x16x32_bf16 v[98:101], v[158:161], v[186:189], v[98:101]
	v_mfma_f32_16x16x32_bf16 v[90:93], v[170:173], v[186:189], v[90:93]
	v_mfma_f32_16x16x32_bf16 v[82:85], v[158:161], v[212:215], v[82:85]
	v_mfma_f32_16x16x32_bf16 v[74:77], v[170:173], v[212:215], v[74:77]
	v_mfma_f32_16x16x32_bf16 v[70:73], v[158:161], v[220:223], v[70:73]
	v_mfma_f32_16x16x32_bf16 v[66:69], v[170:173], v[220:223], v[66:69]
	v_mfma_f32_16x16x32_bf16 v[114:117], v[166:169], v[182:185], v[114:117]
	v_mfma_f32_16x16x32_bf16 v[106:109], v[174:177], v[182:185], v[106:109]
	v_mfma_f32_16x16x32_bf16 v[98:101], v[166:169], v[190:193], v[98:101]
	v_mfma_f32_16x16x32_bf16 v[90:93], v[174:177], v[190:193], v[90:93]
	v_mfma_f32_16x16x32_bf16 v[82:85], v[166:169], v[216:219], v[82:85]
	v_mfma_f32_16x16x32_bf16 v[74:77], v[174:177], v[216:219], v[74:77]
	v_mfma_f32_16x16x32_bf16 v[70:73], v[166:169], v[224:227], v[70:73]
	v_mfma_f32_16x16x32_bf16 v[66:69], v[174:177], v[224:227], v[66:69]
	s_setprio 0
	s_barrier
	s_add_i32 s40, s40, s79
	v_lshl_add_u64 v[194:195], s[30:31], 0, v[148:149]
	s_mov_b32 m0, s40
	ds_read_b128 v[178:181], v164 offset:16384
	ds_read_b128 v[182:185], v164 offset:17408
	ds_read_b128 v[186:189], v164 offset:18432
	ds_read_b128 v[190:193], v164 offset:19456
	ds_read_b128 v[212:215], v164 offset:20480
	ds_read_b128 v[216:219], v164 offset:21504
	ds_read_b128 v[220:223], v164 offset:22528
	ds_read_b128 v[224:227], v164 offset:23552
	global_load_lds_dwordx4 v[194:195], off
	s_add_i32 m0, s40, 0x2000
	s_add_u32 s40, s30, 0x80000
	v_lshl_add_u64 v[200:201], s[30:31], 0, v[152:153]
	s_addc_u32 s41, s31, 0
	s_add_i32 s42, s42, s79
	global_load_lds_dwordx4 v[200:201], off
	v_lshl_add_u64 v[202:203], s[40:41], 0, v[148:149]
	s_mov_b32 m0, s42
	v_lshl_add_u64 v[208:209], s[34:35], 0, v[150:151]
	global_load_lds_dwordx4 v[202:203], off
	v_lshl_add_u64 v[202:203], s[40:41], 0, v[152:153]
	s_add_i32 m0, s42, 0x2000
	s_nop 0
	global_load_lds_dwordx4 v[202:203], off
	v_lshl_add_u64 v[202:203], s[34:35], 0, v[146:147]
	s_mov_b32 m0, s27
	s_nop 0
	global_load_lds_dwordx4 v[202:203], off
	s_mov_b32 m0, s38
	s_nop 0
	global_load_lds_dwordx4 v[208:209], off
	s_waitcnt vmcnt(8)
	s_waitcnt lgkmcnt(0)
	s_setprio 1
	s_barrier
; #define PG8_STAGE(bufoff, gbase, voff) do { _Pragma("unroll") for (int _i = 0; _i < 2; ++_i) \
;         __builtin_amdgcn_global_load_lds((const unsigned*)((const char*)(gbase) + (voff)[_i]), (PG8_LAS unsigned*)(lds + (bufoff) + ldsw + _i * 8192), 16, 0, 0); } while (0)
; #define PG8_LDA(dst, b, h) do { _Pragma("unroll") for (int m = 0; m < 4; ++m) _Pragma("unroll") for (int k = 0; k < 2; ++k) dst[m][k] = *(const PG8_LAS bf16x8*)(lds + PG8_SA(b, h) + aoff + m * 2048 + k * 1024); } while (0)
; #define PG8_LDB(dst, b, h) do { _Pragma("unroll") for (int n = 0; n < 2; ++n) _Pragma("unroll") for (int k = 0; k < 2; ++k) dst[n][k] = *(const PG8_LAS bf16x8*)(lds + PG8_SB(b, h) + boff + n * 2048 + k * 1024); } while (0)
; #define PG8_MMA(ai, bj, At, Bt) do { __builtin_amdgcn_s_setprio(1); _Pragma("unroll") for (int m = 0; m < 4; ++m) _Pragma("unroll") for (int n = 0; n < 2; ++n) _Pragma("unroll") for (int k = 0; k < 2; ++k) \
;         acc[ai][bj][m][n] = __builtin_amdgcn_mfma_f32_16x16x32_bf16(Bt[n][k], At[m][k], acc[ai][bj][m][n], 0, 0, 0); __builtin_amdgcn_s_setprio(0); } while (0)
; #define PG8_WAIT_V(n) asm volatile("s_waitcnt vmcnt(" #n ")" ::: "memory")
; #define PG8_WAIT_L(n) asm volatile("s_waitcnt lgkmcnt(" #n ")" ::: "memory")
; #define PG8_BAR __builtin_amdgcn_s_barrier()
; #define PG8_SCHED __builtin_amdgcn_sched_barrier(0)
; template <class Epi, class Sched, bool ALIGN_EPI = false, bool SP2 = false>
; __device__ __forceinline__ void gemm_phase(PG8_LAS unsigned char* lds, const Gemm g, const Sched& S, const Epi& E, const int wid) {
;     ...
;             PG8_WAIT_V(8); PG8_WAIT_L(0); PG8_BAR; PG8_MMA(1, 0, At, B0); PG8_MMA(1, 1, At, B1); PG8_BAR; PG8_SCHED;
;             PG8_LDB(B0, 1, 0); PG8_LDB(B1, 1, 1); PG8_SCHED; PG8_LDA(At, 1, 0); PG8_STAGE(PG8_SA(0, 1), a2 + hstep, voffA);
;             PG8_WAIT_V(8); PG8_WAIT_L(0); PG8_BAR; PG8_MMA(0, 0, At, B0); PG8_MMA(0, 1, At, B1); PG8_BAR; PG8_SCHED;
	v_mfma_f32_16x16x32_bf16 v[62:65], v[130:133], v[178:181], v[62:65]
	v_mfma_f32_16x16x32_bf16 v[58:61], v[138:141], v[178:181], v[58:61]
	v_mfma_f32_16x16x32_bf16 v[54:57], v[130:133], v[186:189], v[54:57]
	v_mfma_f32_16x16x32_bf16 v[46:49], v[138:141], v[186:189], v[46:49]
	v_mfma_f32_16x16x32_bf16 v[38:41], v[130:133], v[212:215], v[38:41]
	v_mfma_f32_16x16x32_bf16 v[30:33], v[138:141], v[212:215], v[30:33]
	v_mfma_f32_16x16x32_bf16 v[22:25], v[130:133], v[220:223], v[22:25]
	v_mfma_f32_16x16x32_bf16 v[14:17], v[138:141], v[220:223], v[14:17]
	v_mfma_f32_16x16x32_bf16 v[62:65], v[134:137], v[182:185], v[62:65]
	v_mfma_f32_16x16x32_bf16 v[58:61], v[142:145], v[182:185], v[58:61]
	v_mfma_f32_16x16x32_bf16 v[54:57], v[134:137], v[190:193], v[54:57]
	v_mfma_f32_16x16x32_bf16 v[46:49], v[142:145], v[190:193], v[46:49]
	v_mfma_f32_16x16x32_bf16 v[38:41], v[134:137], v[216:219], v[38:41]
	v_mfma_f32_16x16x32_bf16 v[30:33], v[142:145], v[216:219], v[30:33]
	v_mfma_f32_16x16x32_bf16 v[22:25], v[134:137], v[224:227], v[22:25]
	v_mfma_f32_16x16x32_bf16 v[14:17], v[142:145], v[224:227], v[14:17]
	s_setprio 0
	s_setprio 1
	v_mfma_f32_16x16x32_bf16 v[50:53], v[158:161], v[178:181], v[50:53]
	v_mfma_f32_16x16x32_bf16 v[42:45], v[170:173], v[178:181], v[42:45]
	v_mfma_f32_16x16x32_bf16 v[34:37], v[158:161], v[186:189], v[34:37]
	v_mfma_f32_16x16x32_bf16 v[26:29], v[170:173], v[186:189], v[26:29]
	v_mfma_f32_16x16x32_bf16 v[18:21], v[158:161], v[212:215], v[18:21]
	v_mfma_f32_16x16x32_bf16 v[10:13], v[170:173], v[212:215], v[10:13]
	v_mfma_f32_16x16x32_bf16 v[6:9], v[158:161], v[220:223], v[6:9]
	v_mfma_f32_16x16x32_bf16 v[2:5], v[170:173], v[220:223], v[2:5]
	v_mfma_f32_16x16x32_bf16 v[50:53], v[166:169], v[182:185], v[50:53]
	v_mfma_f32_16x16x32_bf16 v[42:45], v[174:177], v[182:185], v[42:45]
	v_mfma_f32_16x16x32_bf16 v[34:37], v[166:169], v[190:193], v[34:37]
	v_mfma_f32_16x16x32_bf16 v[26:29], v[174:177], v[190:193], v[26:29]
	v_mfma_f32_16x16x32_bf16 v[18:21], v[166:169], v[216:219], v[18:21]
	v_mfma_f32_16x16x32_bf16 v[10:13], v[174:177], v[216:219], v[10:13]
	v_mfma_f32_16x16x32_bf16 v[6:9], v[166:169], v[224:227], v[6:9]
	v_mfma_f32_16x16x32_bf16 v[2:5], v[174:177], v[224:227], v[2:5]
	s_setprio 0
	s_barrier
	s_add_i32 s40, 0, 0x18000
	v_add_u32_e32 v0, s40, v163
	s_add_i32 s41, 0, 0x1c000
	ds_read_b128 v[130:133], v0
	ds_read_b128 v[134:137], v0 offset:1024
	ds_read_b128 v[138:141], v0 offset:2048
	ds_read_b128 v[142:145], v0 offset:3072
	v_add_u32_e32 v0, s41, v163
	ds_read_b128 v[158:161], v0
	ds_read_b128 v[166:169], v0 offset:1024
	ds_read_b128 v[170:173], v0 offset:2048
	ds_read_b128 v[174:177], v0 offset:3072
	s_add_u32 s34, s34, 0x80000
	s_addc_u32 s35, s35, 0
	s_mov_b32 m0, s39
	v_lshl_add_u64 v[210:211], s[34:35], 0, v[146:147]
	ds_read_b128 v[178:181], v164 offset:32768
	ds_read_b128 v[182:185], v164 offset:33792
	ds_read_b128 v[186:189], v164 offset:34816
	ds_read_b128 v[190:193], v164 offset:35840
	ds_read_b128 v[212:215], v164 offset:36864
	ds_read_b128 v[216:219], v164 offset:37888
	ds_read_b128 v[220:223], v164 offset:38912
	ds_read_b128 v[224:227], v164 offset:39936
	global_load_lds_dwordx4 v[210:211], off
	v_lshl_add_u64 v[210:211], s[34:35], 0, v[150:151]
	s_mov_b32 m0, s44
	s_nop 0
	global_load_lds_dwordx4 v[210:211], off
	s_waitcnt vmcnt(8)
	s_waitcnt lgkmcnt(0)
	s_setprio 1
	s_barrier
	v_mfma_f32_16x16x32_bf16 v[126:129], v[130:133], v[178:181], v[126:129]
	v_mfma_f32_16x16x32_bf16 v[122:125], v[138:141], v[178:181], v[122:125]
	v_mfma_f32_16x16x32_bf16 v[118:121], v[130:133], v[186:189], v[118:121]
	v_mfma_f32_16x16x32_bf16 v[110:113], v[138:141], v[186:189], v[110:113]
	v_mfma_f32_16x16x32_bf16 v[102:105], v[130:133], v[212:215], v[102:105]
	v_mfma_f32_16x16x32_bf16 v[94:97], v[138:141], v[212:215], v[94:97]
	v_mfma_f32_16x16x32_bf16 v[86:89], v[130:133], v[220:223], v[86:89]
	v_mfma_f32_16x16x32_bf16 v[78:81], v[138:141], v[220:223], v[78:81]
	v_mfma_f32_16x16x32_bf16 v[126:129], v[134:137], v[182:185], v[126:129]
	v_mfma_f32_16x16x32_bf16 v[122:125], v[142:145], v[182:185], v[122:125]
	v_mfma_f32_16x16x32_bf16 v[118:121], v[134:137], v[190:193], v[118:121]
	v_mfma_f32_16x16x32_bf16 v[110:113], v[142:145], v[190:193], v[110:113]
	v_mfma_f32_16x16x32_bf16 v[102:105], v[134:137], v[216:219], v[102:105]
	v_mfma_f32_16x16x32_bf16 v[94:97], v[142:145], v[216:219], v[94:97]
	v_mfma_f32_16x16x32_bf16 v[86:89], v[134:137], v[224:227], v[86:89]
	v_mfma_f32_16x16x32_bf16 v[78:81], v[142:145], v[224:227], v[78:81]
	s_setprio 0
	s_setprio 1
	v_mfma_f32_16x16x32_bf16 v[114:117], v[158:161], v[178:181], v[114:117]
	v_mfma_f32_16x16x32_bf16 v[106:109], v[170:173], v[178:181], v[106:109]
	v_mfma_f32_16x16x32_bf16 v[98:101], v[158:161], v[186:189], v[98:101]
	v_mfma_f32_16x16x32_bf16 v[90:93], v[170:173], v[186:189], v[90:93]
	v_mfma_f32_16x16x32_bf16 v[82:85], v[158:161], v[212:215], v[82:85]
	v_mfma_f32_16x16x32_bf16 v[74:77], v[170:173], v[212:215], v[74:77]
	v_mfma_f32_16x16x32_bf16 v[70:73], v[158:161], v[220:223], v[70:73]
	v_mfma_f32_16x16x32_bf16 v[66:69], v[170:173], v[220:223], v[66:69]
	v_mfma_f32_16x16x32_bf16 v[114:117], v[166:169], v[182:185], v[114:117]
	v_mfma_f32_16x16x32_bf16 v[106:109], v[174:177], v[182:185], v[106:109]
	v_mfma_f32_16x16x32_bf16 v[98:101], v[166:169], v[190:193], v[98:101]
	v_mfma_f32_16x16x32_bf16 v[90:93], v[174:177], v[190:193], v[90:93]
	v_mfma_f32_16x16x32_bf16 v[82:85], v[166:169], v[216:219], v[82:85]
	v_mfma_f32_16x16x32_bf16 v[74:77], v[174:177], v[216:219], v[74:77]
	v_mfma_f32_16x16x32_bf16 v[70:73], v[166:169], v[224:227], v[70:73]
	v_mfma_f32_16x16x32_bf16 v[66:69], v[174:177], v[224:227], v[66:69]
	s_setprio 0
	s_barrier
; #define PG8_STAGE(bufoff, gbase, voff) do { _Pragma("unroll") for (int _i = 0; _i < 2; ++_i) \
;         __builtin_amdgcn_global_load_lds((const unsigned*)((const char*)(gbase) + (voff)[_i]), (PG8_LAS unsigned*)(lds + (bufoff) + ldsw + _i * 8192), 16, 0, 0); } while (0)
; #define PG8_LDA(dst, b, h) do { _Pragma("unroll") for (int m = 0; m < 4; ++m) _Pragma("unroll") for (int k = 0; k < 2; ++k) dst[m][k] = *(const PG8_LAS bf16x8*)(lds + PG8_SA(b, h) + aoff + m * 2048 + k * 1024); } while (0)
; #define PG8_MMA(ai, bj, At, Bt) do { __builtin_amdgcn_s_setprio(1); _Pragma("unroll") for (int m = 0; m < 4; ++m) _Pragma("unroll") for (int n = 0; n < 2; ++n) _Pragma("unroll") for (int k = 0; k < 2; ++k) \
;         acc[ai][bj][m][n] = __builtin_amdgcn_mfma_f32_16x16x32_bf16(Bt[n][k], At[m][k], acc[ai][bj][m][n], 0, 0, 0); __builtin_amdgcn_s_setprio(0); } while (0)
; #define PG8_WAIT_V(n) asm volatile("s_waitcnt vmcnt(" #n ")" ::: "memory")
; #define PG8_WAIT_L(n) asm volatile("s_waitcnt lgkmcnt(" #n ")" ::: "memory")
; #define PG8_BAR __builtin_amdgcn_s_barrier()
; #define PG8_SCHED __builtin_amdgcn_sched_barrier(0)
; template <class Epi, class Sched, bool ALIGN_EPI = false, bool SP2 = false>
; __device__ __forceinline__ void gemm_phase(PG8_LAS unsigned char* lds, const Gemm g, const Sched& S, const Epi& E, const int wid) {
;     ...
;         for (int t = 0; t < nt; t += 2) {
;     ...
;             PG8_LDA(At, 1, 1); PG8_STAGE(PG8_SB(1, 0), b3, voffB); PG8_STAGE(PG8_SB(1, 1), b3 + hstep, voffB); PG8_STAGE(PG8_SA(1, 0), a3, voffA);
;             PG8_WAIT_V(8); PG8_WAIT_L(0); PG8_BAR; PG8_MMA(1, 0, At, B0); PG8_MMA(1, 1, At, B1); PG8_BAR; PG8_SCHED;
;     ...
;         if constexpr (ALIGN_EPI) { if (wr == 0) PG8_BAR; }
	s_add_i32 s34, s40, s79
	v_lshl_add_u64 v[194:195], v[194:195], 0, s[58:59]
	s_mov_b32 m0, s34
	ds_read_b128 v[178:181], v164 offset:49152
	ds_read_b128 v[182:185], v164 offset:50176
	ds_read_b128 v[186:189], v164 offset:51200
	ds_read_b128 v[190:193], v164 offset:52224
	ds_read_b128 v[212:215], v164 offset:53248
	ds_read_b128 v[216:219], v164 offset:54272
	ds_read_b128 v[220:223], v164 offset:55296
	ds_read_b128 v[224:227], v164 offset:56320
	global_load_lds_dwordx4 v[194:195], off
	s_add_i32 m0, s34, 0x2000
	s_add_u32 s30, s30, 0x80080
	v_lshl_add_u64 v[194:195], v[200:201], 0, s[58:59]
	s_addc_u32 s31, s31, 0
	s_add_i32 s34, s41, s79
	global_load_lds_dwordx4 v[194:195], off
	v_lshl_add_u64 v[194:195], s[30:31], 0, v[148:149]
	s_mov_b32 m0, s34
	s_nop 0
	global_load_lds_dwordx4 v[194:195], off
	v_lshl_add_u64 v[194:195], s[30:31], 0, v[152:153]
	s_add_i32 m0, s34, 0x2000
	s_nop 0
	global_load_lds_dwordx4 v[194:195], off
	v_lshl_add_u64 v[194:195], v[202:203], 0, s[58:59]
	s_mov_b32 m0, s46
	s_nop 0
	global_load_lds_dwordx4 v[194:195], off
	v_lshl_add_u64 v[194:195], v[208:209], 0, s[58:59]
	s_mov_b32 m0, s47
	s_nop 0
	global_load_lds_dwordx4 v[194:195], off
	s_waitcnt vmcnt(8)
	s_waitcnt lgkmcnt(0)
	s_setprio 1
	s_barrier
	v_mfma_f32_16x16x32_bf16 v[62:65], v[130:133], v[178:181], v[62:65]
	v_mfma_f32_16x16x32_bf16 v[58:61], v[138:141], v[178:181], v[58:61]
	v_mfma_f32_16x16x32_bf16 v[54:57], v[130:133], v[186:189], v[54:57]
	v_mfma_f32_16x16x32_bf16 v[46:49], v[138:141], v[186:189], v[46:49]
	v_mfma_f32_16x16x32_bf16 v[38:41], v[130:133], v[212:215], v[38:41]
	v_mfma_f32_16x16x32_bf16 v[30:33], v[138:141], v[212:215], v[30:33]
	v_mfma_f32_16x16x32_bf16 v[22:25], v[130:133], v[220:223], v[22:25]
	v_mfma_f32_16x16x32_bf16 v[14:17], v[138:141], v[220:223], v[14:17]
	v_mfma_f32_16x16x32_bf16 v[62:65], v[134:137], v[182:185], v[62:65]
	v_mfma_f32_16x16x32_bf16 v[58:61], v[142:145], v[182:185], v[58:61]
	v_mfma_f32_16x16x32_bf16 v[54:57], v[134:137], v[190:193], v[54:57]
	v_mfma_f32_16x16x32_bf16 v[46:49], v[142:145], v[190:193], v[46:49]
	v_mfma_f32_16x16x32_bf16 v[38:41], v[134:137], v[216:219], v[38:41]
	v_mfma_f32_16x16x32_bf16 v[30:33], v[142:145], v[216:219], v[30:33]
	v_mfma_f32_16x16x32_bf16 v[22:25], v[134:137], v[224:227], v[22:25]
	v_mfma_f32_16x16x32_bf16 v[14:17], v[142:145], v[224:227], v[14:17]
	s_setprio 0
	s_setprio 1
	v_mfma_f32_16x16x32_bf16 v[50:53], v[158:161], v[178:181], v[50:53]
	v_mfma_f32_16x16x32_bf16 v[42:45], v[170:173], v[178:181], v[42:45]
	v_mfma_f32_16x16x32_bf16 v[34:37], v[158:161], v[186:189], v[34:37]
	v_mfma_f32_16x16x32_bf16 v[26:29], v[170:173], v[186:189], v[26:29]
	v_mfma_f32_16x16x32_bf16 v[18:21], v[158:161], v[212:215], v[18:21]
	v_mfma_f32_16x16x32_bf16 v[10:13], v[170:173], v[212:215], v[10:13]
	v_mfma_f32_16x16x32_bf16 v[6:9], v[158:161], v[220:223], v[6:9]
	v_mfma_f32_16x16x32_bf16 v[2:5], v[170:173], v[220:223], v[2:5]
	v_mfma_f32_16x16x32_bf16 v[50:53], v[166:169], v[182:185], v[50:53]
	v_mfma_f32_16x16x32_bf16 v[42:45], v[174:177], v[182:185], v[42:45]
	v_mfma_f32_16x16x32_bf16 v[34:37], v[166:169], v[190:193], v[34:37]
	v_mfma_f32_16x16x32_bf16 v[26:29], v[174:177], v[190:193], v[26:29]
	v_mfma_f32_16x16x32_bf16 v[18:21], v[166:169], v[216:219], v[18:21]
	v_mfma_f32_16x16x32_bf16 v[10:13], v[174:177], v[216:219], v[10:13]
	v_mfma_f32_16x16x32_bf16 v[6:9], v[166:169], v[224:227], v[6:9]
	v_mfma_f32_16x16x32_bf16 v[2:5], v[174:177], v[224:227], v[2:5]
	s_setprio 0
	s_barrier
	s_add_i32 s85, s85, 2
	s_add_u32 s28, s28, 0x100
	s_addc_u32 s29, s29, 0
	s_add_u32 s68, s68, 0x100
	s_addc_u32 s84, s84, 0
	s_cmp_gt_u32 s85, 29
	s_cbranch_scc0 .LBB0_530
	s_and_b64 vcc, exec, s[14:15]
	s_cbranch_vccz .LBB0_533
	s_barrier

; #define PG8_STAGE(bufoff, gbase, voff) do { _Pragma("unroll") for (int _i = 0; _i < 2; ++_i) \
;         __builtin_amdgcn_global_load_lds((const unsigned*)((const char*)(gbase) + (voff)[_i]), (PG8_LAS unsigned*)(lds + (bufoff) + ldsw + _i * 8192), 16, 0, 0); } while (0)
; #define PG8_LDA(dst, b, h) do { _Pragma("unroll") for (int m = 0; m < 4; ++m) _Pragma("unroll") for (int k = 0; k < 2; ++k) dst[m][k] = *(const PG8_LAS bf16x8*)(lds + PG8_SA(b, h) + aoff + m * 2048 + k * 1024); } while (0)
; #define PG8_LDB(dst, b, h) do { _Pragma("unroll") for (int n = 0; n < 2; ++n) _Pragma("unroll") for (int k = 0; k < 2; ++k) dst[n][k] = *(const PG8_LAS bf16x8*)(lds + PG8_SB(b, h) + boff + n * 2048 + k * 1024); } while (0)
; #define PG8_MMA(ai, bj, At, Bt) do { __builtin_amdgcn_s_setprio(1); _Pragma("unroll") for (int m = 0; m < 4; ++m) _Pragma("unroll") for (int n = 0; n < 2; ++n) _Pragma("unroll") for (int k = 0; k < 2; ++k) \
;         acc[ai][bj][m][n] = __builtin_amdgcn_mfma_f32_16x16x32_bf16(Bt[n][k], At[m][k], acc[ai][bj][m][n], 0, 0, 0); __builtin_amdgcn_s_setprio(0); } while (0)
; #define PG8_WAIT_V(n) asm volatile("s_waitcnt vmcnt(" #n ")" ::: "memory")
; #define PG8_WAIT_L(n) asm volatile("s_waitcnt lgkmcnt(" #n ")" ::: "memory")
; template <class Epi, class Sched, bool ALIGN_EPI = false, bool SP2 = false>
; __device__ __forceinline__ void gemm_phase(PG8_LAS unsigned char* lds, const Gemm g, const Sched& S, const Epi& E, const int wid) {
;     ...
;             const bool last = (t == nt - 2);
;             const char* a1 = cA + (size_t)(t + 1) * kstep;
;             const char* a2 = last ? nA : cA + (size_t)(t + 2) * kstep; const char* b2 = last ? nB : cB + (size_t)(t + 2) * kstep;
;             const char* a3 = a2 + kstep; const char* b3 = b2 + kstep;
;             if (last && has_next) S.a_ready(nxt);
;             if constexpr (SP2) {
;             PG8_LDB(B0, 0, 0); PG8_LDB(B1, 0, 1); PG8_SCHED; PG8_LDA(At, 0, 0); PG8_STAGE(PG8_SA(1, 1), a1 + hstep, voffA);
;             PG8_WAIT_V(8); PG8_WAIT_L(0); PG8_BAR; PG8_MMA(0, 0, At, B0); PG8_MMA(0, 1, At, B1); PG8_BAR; PG8_SCHED;
;             PG8_LDA(At, 0, 1); PG8_STAGE(PG8_SB(0, 0), b2, voffB); PG8_STAGE(PG8_SB(0, 1), b2 + hstep, voffB); PG8_STAGE(PG8_SA(0, 0), a2, voffA);
;             PG8_WAIT_V(8); PG8_WAIT_L(0); PG8_BAR; PG8_MMA(1, 0, At, B0); PG8_MMA(1, 1, At, B1); PG8_BAR; PG8_SCHED;
.LBB0_552:
	s_add_u32 s30, s28, 0xfff80080
	s_addc_u32 s31, s29, -1
	s_add_i32 s40, 0, 0x10000
	s_cmp_eq_u32 s85, 28
	s_cselect_b32 s35, s21, s31
	s_cselect_b32 s34, s66, s30
	v_add_u32_e32 v0, s40, v163
	s_cselect_b32 s31, s19, s84
	s_cselect_b32 s30, s67, s68
	s_add_i32 s42, 0, 0x14000
	ds_read_b128 v[130:133], v0
	ds_read_b128 v[134:137], v0 offset:1024
	ds_read_b128 v[138:141], v0 offset:2048
	ds_read_b128 v[142:145], v0 offset:3072
	v_add_u32_e32 v0, s42, v163
	ds_read_b128 v[158:161], v0
	ds_read_b128 v[166:169], v0 offset:1024
	ds_read_b128 v[170:173], v0 offset:2048
	ds_read_b128 v[174:177], v0 offset:3072
	v_lshl_add_u64 v[194:195], s[28:29], 0, v[154:155]
	s_add_i32 m0, s27, 0xc000
	ds_read_b128 v[178:181], v164
	ds_read_b128 v[182:185], v164 offset:1024
	ds_read_b128 v[186:189], v164 offset:2048
	ds_read_b128 v[190:193], v164 offset:3072
	ds_read_b128 v[212:215], v164 offset:4096
	ds_read_b128 v[216:219], v164 offset:5120
	ds_read_b128 v[220:223], v164 offset:6144
	ds_read_b128 v[224:227], v164 offset:7168
	global_load_lds_dwordx4 v[194:195], off
	v_lshl_add_u64 v[194:195], s[28:29], 0, v[156:157]
	s_add_i32 m0, s27, 0xe000
	s_nop 0
	global_load_lds_dwordx4 v[194:195], off
	s_waitcnt vmcnt(8)
	s_waitcnt lgkmcnt(0)
	s_setprio 1
	s_barrier
	v_mfma_f32_16x16x32_bf16 v[126:129], v[130:133], v[178:181], v[126:129]
	v_mfma_f32_16x16x32_bf16 v[122:125], v[138:141], v[178:181], v[122:125]
	v_mfma_f32_16x16x32_bf16 v[118:121], v[130:133], v[186:189], v[118:121]
	v_mfma_f32_16x16x32_bf16 v[110:113], v[138:141], v[186:189], v[110:113]
	v_mfma_f32_16x16x32_bf16 v[102:105], v[130:133], v[212:215], v[102:105]
	v_mfma_f32_16x16x32_bf16 v[94:97], v[138:141], v[212:215], v[94:97]
	v_mfma_f32_16x16x32_bf16 v[86:89], v[130:133], v[220:223], v[86:89]
	v_mfma_f32_16x16x32_bf16 v[78:81], v[138:141], v[220:223], v[78:81]
	v_mfma_f32_16x16x32_bf16 v[126:129], v[134:137], v[182:185], v[126:129]
	v_mfma_f32_16x16x32_bf16 v[122:125], v[142:145], v[182:185], v[122:125]
	v_mfma_f32_16x16x32_bf16 v[118:121], v[134:137], v[190:193], v[118:121]
	v_mfma_f32_16x16x32_bf16 v[110:113], v[142:145], v[190:193], v[110:113]
	v_mfma_f32_16x16x32_bf16 v[102:105], v[134:137], v[216:219], v[102:105]
	v_mfma_f32_16x16x32_bf16 v[94:97], v[142:145], v[216:219], v[94:97]
	v_mfma_f32_16x16x32_bf16 v[86:89], v[134:137], v[224:227], v[86:89]
	v_mfma_f32_16x16x32_bf16 v[78:81], v[142:145], v[224:227], v[78:81]
	s_setprio 0
	s_setprio 1
	v_mfma_f32_16x16x32_bf16 v[114:117], v[158:161], v[178:181], v[114:117]
	v_mfma_f32_16x16x32_bf16 v[106:109], v[170:173], v[178:181], v[106:109]
	v_mfma_f32_16x16x32_bf16 v[98:101], v[158:161], v[186:189], v[98:101]
	v_mfma_f32_16x16x32_bf16 v[90:93], v[170:173], v[186:189], v[90:93]
	v_mfma_f32_16x16x32_bf16 v[82:85], v[158:161], v[212:215], v[82:85]
	v_mfma_f32_16x16x32_bf16 v[74:77], v[170:173], v[212:215], v[74:77]
	v_mfma_f32_16x16x32_bf16 v[70:73], v[158:161], v[220:223], v[70:73]
	v_mfma_f32_16x16x32_bf16 v[66:69], v[170:173], v[220:223], v[66:69]
	v_mfma_f32_16x16x32_bf16 v[114:117], v[166:169], v[182:185], v[114:117]
	v_mfma_f32_16x16x32_bf16 v[106:109], v[174:177], v[182:185], v[106:109]
	v_mfma_f32_16x16x32_bf16 v[98:101], v[166:169], v[190:193], v[98:101]
	v_mfma_f32_16x16x32_bf16 v[90:93], v[174:177], v[190:193], v[90:93]
	v_mfma_f32_16x16x32_bf16 v[82:85], v[166:169], v[216:219], v[82:85]
	v_mfma_f32_16x16x32_bf16 v[74:77], v[174:177], v[216:219], v[74:77]
	v_mfma_f32_16x16x32_bf16 v[70:73], v[166:169], v[224:227], v[70:73]
	v_mfma_f32_16x16x32_bf16 v[66:69], v[174:177], v[224:227], v[66:69]
	s_setprio 0
	s_barrier
	s_add_i32 s40, s40, s79
	v_lshl_add_u64 v[194:195], s[30:31], 0, v[150:151]
	s_mov_b32 m0, s40
	ds_read_b128 v[178:181], v164 offset:16384
	ds_read_b128 v[182:185], v164 offset:17408
	ds_read_b128 v[186:189], v164 offset:18432
	ds_read_b128 v[190:193], v164 offset:19456
	ds_read_b128 v[212:215], v164 offset:20480
	ds_read_b128 v[216:219], v164 offset:21504
	ds_read_b128 v[220:223], v164 offset:22528
	ds_read_b128 v[224:227], v164 offset:23552
	global_load_lds_dwordx4 v[194:195], off
	s_add_i32 m0, s40, 0x2000
	s_add_u32 s40, s30, 0x80000
	v_lshl_add_u64 v[200:201], s[30:31], 0, v[146:147]
	s_addc_u32 s41, s31, 0
	s_add_i32 s42, s42, s79
	global_load_lds_dwordx4 v[200:201], off
	v_lshl_add_u64 v[202:203], s[40:41], 0, v[150:151]
	s_mov_b32 m0, s42
	v_lshl_add_u64 v[208:209], s[34:35], 0, v[148:149]
	global_load_lds_dwordx4 v[202:203], off
	v_lshl_add_u64 v[202:203], s[40:41], 0, v[146:147]
	s_add_i32 m0, s42, 0x2000
	s_nop 0
	global_load_lds_dwordx4 v[202:203], off
	v_lshl_add_u64 v[202:203], s[34:35], 0, v[152:153]
	s_mov_b32 m0, s27
	s_nop 0
	global_load_lds_dwordx4 v[202:203], off
	s_mov_b32 m0, s38
	s_nop 0
	global_load_lds_dwordx4 v[208:209], off
	s_waitcnt vmcnt(8)
	s_waitcnt lgkmcnt(0)
	s_setprio 1
	s_barrier
; #define PG8_STAGE(bufoff, gbase, voff) do { _Pragma("unroll") for (int _i = 0; _i < 2; ++_i) \
;         __builtin_amdgcn_global_load_lds((const unsigned*)((const char*)(gbase) + (voff)[_i]), (PG8_LAS unsigned*)(lds + (bufoff) + ldsw + _i * 8192), 16, 0, 0); } while (0)
; #define PG8_LDA(dst, b, h) do { _Pragma("unroll") for (int m = 0; m < 4; ++m) _Pragma("unroll") for (int k = 0; k < 2; ++k) dst[m][k] = *(const PG8_LAS bf16x8*)(lds + PG8_SA(b, h) + aoff + m * 2048 + k * 1024); } while (0)
; #define PG8_LDB(dst, b, h) do { _Pragma("unroll") for (int n = 0; n < 2; ++n) _Pragma("unroll") for (int k = 0; k < 2; ++k) dst[n][k] = *(const PG8_LAS bf16x8*)(lds + PG8_SB(b, h) + boff + n * 2048 + k * 1024); } while (0)
; #define PG8_MMA(ai, bj, At, Bt) do { __builtin_amdgcn_s_setprio(1); _Pragma("unroll") for (int m = 0; m < 4; ++m) _Pragma("unroll") for (int n = 0; n < 2; ++n) _Pragma("unroll") for (int k = 0; k < 2; ++k) \
;         acc[ai][bj][m][n] = __builtin_amdgcn_mfma_f32_16x16x32_bf16(Bt[n][k], At[m][k], acc[ai][bj][m][n], 0, 0, 0); __builtin_amdgcn_s_setprio(0); } while (0)
; #define PG8_WAIT_V(n) asm volatile("s_waitcnt vmcnt(" #n ")" ::: "memory")
; #define PG8_WAIT_L(n) asm volatile("s_waitcnt lgkmcnt(" #n ")" ::: "memory")
; #define PG8_BAR __builtin_amdgcn_s_barrier()
; #define PG8_SCHED __builtin_amdgcn_sched_barrier(0)
; template <class Epi, class Sched, bool ALIGN_EPI = false, bool SP2 = false>
; __device__ __forceinline__ void gemm_phase(PG8_LAS unsigned char* lds, const Gemm g, const Sched& S, const Epi& E, const int wid) {
;     ...
;             PG8_WAIT_V(8); PG8_WAIT_L(0); PG8_BAR; PG8_MMA(1, 0, At, B0); PG8_MMA(1, 1, At, B1); PG8_BAR; PG8_SCHED;
;             PG8_LDB(B0, 1, 0); PG8_LDB(B1, 1, 1); PG8_SCHED; PG8_LDA(At, 1, 0); PG8_STAGE(PG8_SA(0, 1), a2 + hstep, voffA);
;             PG8_WAIT_V(8); PG8_WAIT_L(0); PG8_BAR; PG8_MMA(0, 0, At, B0); PG8_MMA(0, 1, At, B1); PG8_BAR; PG8_SCHED;
	v_mfma_f32_16x16x32_bf16 v[62:65], v[130:133], v[178:181], v[62:65]
	v_mfma_f32_16x16x32_bf16 v[58:61], v[138:141], v[178:181], v[58:61]
	v_mfma_f32_16x16x32_bf16 v[54:57], v[130:133], v[186:189], v[54:57]
	v_mfma_f32_16x16x32_bf16 v[46:49], v[138:141], v[186:189], v[46:49]
	v_mfma_f32_16x16x32_bf16 v[38:41], v[130:133], v[212:215], v[38:41]
	v_mfma_f32_16x16x32_bf16 v[30:33], v[138:141], v[212:215], v[30:33]
	v_mfma_f32_16x16x32_bf16 v[22:25], v[130:133], v[220:223], v[22:25]
	v_mfma_f32_16x16x32_bf16 v[14:17], v[138:141], v[220:223], v[14:17]
	v_mfma_f32_16x16x32_bf16 v[62:65], v[134:137], v[182:185], v[62:65]
	v_mfma_f32_16x16x32_bf16 v[58:61], v[142:145], v[182:185], v[58:61]
	v_mfma_f32_16x16x32_bf16 v[54:57], v[134:137], v[190:193], v[54:57]
	v_mfma_f32_16x16x32_bf16 v[46:49], v[142:145], v[190:193], v[46:49]
	v_mfma_f32_16x16x32_bf16 v[38:41], v[134:137], v[216:219], v[38:41]
	v_mfma_f32_16x16x32_bf16 v[30:33], v[142:145], v[216:219], v[30:33]
	v_mfma_f32_16x16x32_bf16 v[22:25], v[134:137], v[224:227], v[22:25]
	v_mfma_f32_16x16x32_bf16 v[14:17], v[142:145], v[224:227], v[14:17]
	s_setprio 0
	s_setprio 1
	v_mfma_f32_16x16x32_bf16 v[50:53], v[158:161], v[178:181], v[50:53]
	v_mfma_f32_16x16x32_bf16 v[42:45], v[170:173], v[178:181], v[42:45]
	v_mfma_f32_16x16x32_bf16 v[34:37], v[158:161], v[186:189], v[34:37]
	v_mfma_f32_16x16x32_bf16 v[26:29], v[170:173], v[186:189], v[26:29]
	v_mfma_f32_16x16x32_bf16 v[18:21], v[158:161], v[212:215], v[18:21]
	v_mfma_f32_16x16x32_bf16 v[10:13], v[170:173], v[212:215], v[10:13]
	v_mfma_f32_16x16x32_bf16 v[6:9], v[158:161], v[220:223], v[6:9]
	v_mfma_f32_16x16x32_bf16 v[2:5], v[170:173], v[220:223], v[2:5]
	v_mfma_f32_16x16x32_bf16 v[50:53], v[166:169], v[182:185], v[50:53]
	v_mfma_f32_16x16x32_bf16 v[42:45], v[174:177], v[182:185], v[42:45]
	v_mfma_f32_16x16x32_bf16 v[34:37], v[166:169], v[190:193], v[34:37]
	v_mfma_f32_16x16x32_bf16 v[26:29], v[174:177], v[190:193], v[26:29]
	v_mfma_f32_16x16x32_bf16 v[18:21], v[166:169], v[216:219], v[18:21]
	v_mfma_f32_16x16x32_bf16 v[10:13], v[174:177], v[216:219], v[10:13]
	v_mfma_f32_16x16x32_bf16 v[6:9], v[166:169], v[224:227], v[6:9]
	v_mfma_f32_16x16x32_bf16 v[2:5], v[174:177], v[224:227], v[2:5]
	s_setprio 0
	s_barrier
	s_add_i32 s40, 0, 0x18000
	v_add_u32_e32 v0, s40, v163
	s_add_i32 s41, 0, 0x1c000
	ds_read_b128 v[130:133], v0
	ds_read_b128 v[134:137], v0 offset:1024
	ds_read_b128 v[138:141], v0 offset:2048
	ds_read_b128 v[142:145], v0 offset:3072
	v_add_u32_e32 v0, s41, v163
	ds_read_b128 v[158:161], v0
	ds_read_b128 v[166:169], v0 offset:1024
	ds_read_b128 v[170:173], v0 offset:2048
	ds_read_b128 v[174:177], v0 offset:3072
	s_add_u32 s34, s34, 0x80000
	s_addc_u32 s35, s35, 0
	s_mov_b32 m0, s39
	v_lshl_add_u64 v[210:211], s[34:35], 0, v[152:153]
	ds_read_b128 v[178:181], v164 offset:32768
	ds_read_b128 v[182:185], v164 offset:33792
	ds_read_b128 v[186:189], v164 offset:34816
	ds_read_b128 v[190:193], v164 offset:35840
	ds_read_b128 v[212:215], v164 offset:36864
	ds_read_b128 v[216:219], v164 offset:37888
	ds_read_b128 v[220:223], v164 offset:38912
	ds_read_b128 v[224:227], v164 offset:39936
	global_load_lds_dwordx4 v[210:211], off
	v_lshl_add_u64 v[210:211], s[34:35], 0, v[148:149]
	s_mov_b32 m0, s44
	s_nop 0
	global_load_lds_dwordx4 v[210:211], off
	s_waitcnt vmcnt(8)
	s_waitcnt lgkmcnt(0)
	s_setprio 1
	s_barrier
	v_mfma_f32_16x16x32_bf16 v[126:129], v[130:133], v[178:181], v[126:129]
	v_mfma_f32_16x16x32_bf16 v[122:125], v[138:141], v[178:181], v[122:125]
	v_mfma_f32_16x16x32_bf16 v[118:121], v[130:133], v[186:189], v[118:121]
	v_mfma_f32_16x16x32_bf16 v[110:113], v[138:141], v[186:189], v[110:113]
	v_mfma_f32_16x16x32_bf16 v[102:105], v[130:133], v[212:215], v[102:105]
	v_mfma_f32_16x16x32_bf16 v[94:97], v[138:141], v[212:215], v[94:97]
	v_mfma_f32_16x16x32_bf16 v[86:89], v[130:133], v[220:223], v[86:89]
	v_mfma_f32_16x16x32_bf16 v[78:81], v[138:141], v[220:223], v[78:81]
	v_mfma_f32_16x16x32_bf16 v[126:129], v[134:137], v[182:185], v[126:129]
	v_mfma_f32_16x16x32_bf16 v[122:125], v[142:145], v[182:185], v[122:125]
	v_mfma_f32_16x16x32_bf16 v[118:121], v[134:137], v[190:193], v[118:121]
	v_mfma_f32_16x16x32_bf16 v[110:113], v[142:145], v[190:193], v[110:113]
	v_mfma_f32_16x16x32_bf16 v[102:105], v[134:137], v[216:219], v[102:105]
	v_mfma_f32_16x16x32_bf16 v[94:97], v[142:145], v[216:219], v[94:97]
	v_mfma_f32_16x16x32_bf16 v[86:89], v[134:137], v[224:227], v[86:89]
	v_mfma_f32_16x16x32_bf16 v[78:81], v[142:145], v[224:227], v[78:81]
	s_setprio 0
	s_setprio 1
	v_mfma_f32_16x16x32_bf16 v[114:117], v[158:161], v[178:181], v[114:117]
	v_mfma_f32_16x16x32_bf16 v[106:109], v[170:173], v[178:181], v[106:109]
	v_mfma_f32_16x16x32_bf16 v[98:101], v[158:161], v[186:189], v[98:101]
	v_mfma_f32_16x16x32_bf16 v[90:93], v[170:173], v[186:189], v[90:93]
	v_mfma_f32_16x16x32_bf16 v[82:85], v[158:161], v[212:215], v[82:85]
	v_mfma_f32_16x16x32_bf16 v[74:77], v[170:173], v[212:215], v[74:77]
	v_mfma_f32_16x16x32_bf16 v[70:73], v[158:161], v[220:223], v[70:73]
	v_mfma_f32_16x16x32_bf16 v[66:69], v[170:173], v[220:223], v[66:69]
	v_mfma_f32_16x16x32_bf16 v[114:117], v[166:169], v[182:185], v[114:117]
	v_mfma_f32_16x16x32_bf16 v[106:109], v[174:177], v[182:185], v[106:109]
	v_mfma_f32_16x16x32_bf16 v[98:101], v[166:169], v[190:193], v[98:101]
	v_mfma_f32_16x16x32_bf16 v[90:93], v[174:177], v[190:193], v[90:93]
	v_mfma_f32_16x16x32_bf16 v[82:85], v[166:169], v[216:219], v[82:85]
	v_mfma_f32_16x16x32_bf16 v[74:77], v[174:177], v[216:219], v[74:77]
	v_mfma_f32_16x16x32_bf16 v[70:73], v[166:169], v[224:227], v[70:73]
	v_mfma_f32_16x16x32_bf16 v[66:69], v[174:177], v[224:227], v[66:69]
	s_setprio 0
	s_barrier
; #define PG8_STAGE(bufoff, gbase, voff) do { _Pragma("unroll") for (int _i = 0; _i < 2; ++_i) \
;         __builtin_amdgcn_global_load_lds((const unsigned*)((const char*)(gbase) + (voff)[_i]), (PG8_LAS unsigned*)(lds + (bufoff) + ldsw + _i * 8192), 16, 0, 0); } while (0)
; #define PG8_LDA(dst, b, h) do { _Pragma("unroll") for (int m = 0; m < 4; ++m) _Pragma("unroll") for (int k = 0; k < 2; ++k) dst[m][k] = *(const PG8_LAS bf16x8*)(lds + PG8_SA(b, h) + aoff + m * 2048 + k * 1024); } while (0)
; #define PG8_MMA(ai, bj, At, Bt) do { __builtin_amdgcn_s_setprio(1); _Pragma("unroll") for (int m = 0; m < 4; ++m) _Pragma("unroll") for (int n = 0; n < 2; ++n) _Pragma("unroll") for (int k = 0; k < 2; ++k) \
;         acc[ai][bj][m][n] = __builtin_amdgcn_mfma_f32_16x16x32_bf16(Bt[n][k], At[m][k], acc[ai][bj][m][n], 0, 0, 0); __builtin_amdgcn_s_setprio(0); } while (0)
; #define PG8_WAIT_V(n) asm volatile("s_waitcnt vmcnt(" #n ")" ::: "memory")
; #define PG8_WAIT_L(n) asm volatile("s_waitcnt lgkmcnt(" #n ")" ::: "memory")
; #define PG8_BAR __builtin_amdgcn_s_barrier()
; #define PG8_SCHED __builtin_amdgcn_sched_barrier(0)
; template <class Epi, class Sched, bool ALIGN_EPI = false, bool SP2 = false>
; __device__ __forceinline__ void gemm_phase(PG8_LAS unsigned char* lds, const Gemm g, const Sched& S, const Epi& E, const int wid) {
;     ...
;         for (int t = 0; t < nt; t += 2) {
;     ...
;             PG8_LDA(At, 1, 1); PG8_STAGE(PG8_SB(1, 0), b3, voffB); PG8_STAGE(PG8_SB(1, 1), b3 + hstep, voffB); PG8_STAGE(PG8_SA(1, 0), a3, voffA);
;             PG8_WAIT_V(8); PG8_WAIT_L(0); PG8_BAR; PG8_MMA(1, 0, At, B0); PG8_MMA(1, 1, At, B1); PG8_BAR; PG8_SCHED;
;     ...
;         if constexpr (ALIGN_EPI) { if (wr == 0) PG8_BAR; }
	s_add_i32 s34, s40, s79
	v_lshl_add_u64 v[194:195], v[194:195], 0, s[58:59]
	s_mov_b32 m0, s34
	ds_read_b128 v[178:181], v164 offset:49152
	ds_read_b128 v[182:185], v164 offset:50176
	ds_read_b128 v[186:189], v164 offset:51200
	ds_read_b128 v[190:193], v164 offset:52224
	ds_read_b128 v[212:215], v164 offset:53248
	ds_read_b128 v[216:219], v164 offset:54272
	ds_read_b128 v[220:223], v164 offset:55296
	ds_read_b128 v[224:227], v164 offset:56320
	global_load_lds_dwordx4 v[194:195], off
	s_add_i32 m0, s34, 0x2000
	s_add_u32 s30, s30, 0x80080
	v_lshl_add_u64 v[194:195], v[200:201], 0, s[58:59]
	s_addc_u32 s31, s31, 0
	s_add_i32 s34, s41, s79
	global_load_lds_dwordx4 v[194:195], off
	v_lshl_add_u64 v[194:195], s[30:31], 0, v[150:151]
	s_mov_b32 m0, s34
	s_nop 0
	global_load_lds_dwordx4 v[194:195], off
	v_lshl_add_u64 v[194:195], s[30:31], 0, v[146:147]
	s_add_i32 m0, s34, 0x2000
	s_nop 0
	global_load_lds_dwordx4 v[194:195], off
	v_lshl_add_u64 v[194:195], v[202:203], 0, s[58:59]
	s_mov_b32 m0, s46
	s_nop 0
	global_load_lds_dwordx4 v[194:195], off
	v_lshl_add_u64 v[194:195], v[208:209], 0, s[58:59]
	s_mov_b32 m0, s47
	s_nop 0
	global_load_lds_dwordx4 v[194:195], off
	s_waitcnt vmcnt(8)
	s_waitcnt lgkmcnt(0)
	s_setprio 1
	s_barrier
	v_mfma_f32_16x16x32_bf16 v[62:65], v[130:133], v[178:181], v[62:65]
	v_mfma_f32_16x16x32_bf16 v[58:61], v[138:141], v[178:181], v[58:61]
	v_mfma_f32_16x16x32_bf16 v[54:57], v[130:133], v[186:189], v[54:57]
	v_mfma_f32_16x16x32_bf16 v[46:49], v[138:141], v[186:189], v[46:49]
	v_mfma_f32_16x16x32_bf16 v[38:41], v[130:133], v[212:215], v[38:41]
	v_mfma_f32_16x16x32_bf16 v[30:33], v[138:141], v[212:215], v[30:33]
	v_mfma_f32_16x16x32_bf16 v[22:25], v[130:133], v[220:223], v[22:25]
	v_mfma_f32_16x16x32_bf16 v[14:17], v[138:141], v[220:223], v[14:17]
	v_mfma_f32_16x16x32_bf16 v[62:65], v[134:137], v[182:185], v[62:65]
	v_mfma_f32_16x16x32_bf16 v[58:61], v[142:145], v[182:185], v[58:61]
	v_mfma_f32_16x16x32_bf16 v[54:57], v[134:137], v[190:193], v[54:57]
	v_mfma_f32_16x16x32_bf16 v[46:49], v[142:145], v[190:193], v[46:49]
	v_mfma_f32_16x16x32_bf16 v[38:41], v[134:137], v[216:219], v[38:41]
	v_mfma_f32_16x16x32_bf16 v[30:33], v[142:145], v[216:219], v[30:33]
	v_mfma_f32_16x16x32_bf16 v[22:25], v[134:137], v[224:227], v[22:25]
	v_mfma_f32_16x16x32_bf16 v[14:17], v[142:145], v[224:227], v[14:17]
	s_setprio 0
	s_setprio 1
	v_mfma_f32_16x16x32_bf16 v[50:53], v[158:161], v[178:181], v[50:53]
	v_mfma_f32_16x16x32_bf16 v[42:45], v[170:173], v[178:181], v[42:45]
	v_mfma_f32_16x16x32_bf16 v[34:37], v[158:161], v[186:189], v[34:37]
	v_mfma_f32_16x16x32_bf16 v[26:29], v[170:173], v[186:189], v[26:29]
	v_mfma_f32_16x16x32_bf16 v[18:21], v[158:161], v[212:215], v[18:21]
	v_mfma_f32_16x16x32_bf16 v[10:13], v[170:173], v[212:215], v[10:13]
	v_mfma_f32_16x16x32_bf16 v[6:9], v[158:161], v[220:223], v[6:9]
	v_mfma_f32_16x16x32_bf16 v[2:5], v[170:173], v[220:223], v[2:5]
	v_mfma_f32_16x16x32_bf16 v[50:53], v[166:169], v[182:185], v[50:53]
	v_mfma_f32_16x16x32_bf16 v[42:45], v[174:177], v[182:185], v[42:45]
	v_mfma_f32_16x16x32_bf16 v[34:37], v[166:169], v[190:193], v[34:37]
	v_mfma_f32_16x16x32_bf16 v[26:29], v[174:177], v[190:193], v[26:29]
	v_mfma_f32_16x16x32_bf16 v[18:21], v[166:169], v[216:219], v[18:21]
	v_mfma_f32_16x16x32_bf16 v[10:13], v[174:177], v[216:219], v[10:13]
	v_mfma_f32_16x16x32_bf16 v[6:9], v[166:169], v[224:227], v[6:9]
	v_mfma_f32_16x16x32_bf16 v[2:5], v[174:177], v[224:227], v[2:5]
	s_setprio 0
	s_barrier
	s_add_i32 s85, s85, 2
	s_add_u32 s28, s28, 0x100
	s_addc_u32 s29, s29, 0
	s_add_u32 s68, s68, 0x100
	s_addc_u32 s84, s84, 0
	s_cmp_gt_u32 s85, 29
	s_cbranch_scc0 .LBB0_552
	s_and_b64 vcc, exec, s[14:15]
	s_cbranch_vccz .LBB0_555
	s_barrier

; #define PG8_STAGE(bufoff, gbase, voff) do { _Pragma("unroll") for (int _i = 0; _i < 2; ++_i) \
;         __builtin_amdgcn_global_load_lds((const unsigned*)((const char*)(gbase) + (voff)[_i]), (PG8_LAS unsigned*)(lds + (bufoff) + ldsw + _i * 8192), 16, 0, 0); } while (0)
; #define PG8_LDA(dst, b, h) do { _Pragma("unroll") for (int m = 0; m < 4; ++m) _Pragma("unroll") for (int k = 0; k < 2; ++k) dst[m][k] = *(const PG8_LAS bf16x8*)(lds + PG8_SA(b, h) + aoff + m * 2048 + k * 1024); } while (0)
; #define PG8_LDB(dst, b, h) do { _Pragma("unroll") for (int n = 0; n < 2; ++n) _Pragma("unroll") for (int k = 0; k < 2; ++k) dst[n][k] = *(const PG8_LAS bf16x8*)(lds + PG8_SB(b, h) + boff + n * 2048 + k * 1024); } while (0)
; #define PG8_MMA(ai, bj, At, Bt) do { __builtin_amdgcn_s_setprio(1); _Pragma("unroll") for (int m = 0; m < 4; ++m) _Pragma("unroll") for (int n = 0; n < 2; ++n) _Pragma("unroll") for (int k = 0; k < 2; ++k) \
;         acc[ai][bj][m][n] = __builtin_amdgcn_mfma_f32_16x16x32_bf16(Bt[n][k], At[m][k], acc[ai][bj][m][n], 0, 0, 0); __builtin_amdgcn_s_setprio(0); } while (0)
; #define PG8_WAIT_V(n) asm volatile("s_waitcnt vmcnt(" #n ")" ::: "memory")
; #define PG8_WAIT_L(n) asm volatile("s_waitcnt lgkmcnt(" #n ")" ::: "memory")
; template <class Epi, class Sched, bool ALIGN_EPI = false, bool SP2 = false>
; __device__ __forceinline__ void gemm_phase(PG8_LAS unsigned char* lds, const Gemm g, const Sched& S, const Epi& E, const int wid) {
;     ...
;             const bool last = (t == nt - 2);
;             const char* a1 = cA + (size_t)(t + 1) * kstep;
;             const char* a2 = last ? nA : cA + (size_t)(t + 2) * kstep; const char* b2 = last ? nB : cB + (size_t)(t + 2) * kstep;
;             const char* a3 = a2 + kstep; const char* b3 = b2 + kstep;
;             if (last && has_next) S.a_ready(nxt);
;             if constexpr (SP2) {
;             PG8_LDB(B0, 0, 0); PG8_LDB(B1, 0, 1); PG8_SCHED; PG8_LDA(At, 0, 0); PG8_STAGE(PG8_SA(1, 1), a1 + hstep, voffA);
;             PG8_WAIT_V(8); PG8_WAIT_L(0); PG8_BAR; PG8_MMA(0, 0, At, B0); PG8_MMA(0, 1, At, B1); PG8_BAR; PG8_SCHED;
;             PG8_LDA(At, 0, 1); PG8_STAGE(PG8_SB(0, 0), b2, voffB); PG8_STAGE(PG8_SB(0, 1), b2 + hstep, voffB); PG8_STAGE(PG8_SA(0, 0), a2, voffA);
;             PG8_WAIT_V(8); PG8_WAIT_L(0); PG8_BAR; PG8_MMA(1, 0, At, B0); PG8_MMA(1, 1, At, B1); PG8_BAR; PG8_SCHED;
.LBB0_601:
	s_add_i32 s40, s36, 2
	s_add_u32 s41, s34, 0x80
	s_addc_u32 s37, s35, 0
	s_add_i32 s54, 0, 0x10000
	s_cmp_eq_u32 s88, s36
	s_cselect_b32 s37, s9, s37
	s_cselect_b32 s36, s8, s41
	s_cselect_b32 s43, s31, s52
	s_cselect_b32 s42, s30, s47
	s_add_i32 s41, 0, 0x14000
	v_add_u32_e32 v152, s54, v159
	v_add_u32_e32 v156, s41, v159
	ds_read_b128 v[130:133], v152
	ds_read_b128 v[134:137], v152 offset:1024
	ds_read_b128 v[148:151], v152 offset:2048
	ds_read_b128 v[152:155], v152 offset:3072
	ds_read_b128 v[162:165], v156
	ds_read_b128 v[166:169], v156 offset:1024
	ds_read_b128 v[170:173], v156 offset:2048
	ds_read_b128 v[174:177], v156 offset:3072
	v_lshl_add_u64 v[156:157], s[34:35], 0, v[144:145]
	s_add_i32 m0, s39, 0xc000
	ds_read_b128 v[178:181], v160
	ds_read_b128 v[182:185], v160 offset:1024
	ds_read_b128 v[186:189], v160 offset:2048
	ds_read_b128 v[190:193], v160 offset:3072
	ds_read_b128 v[212:215], v160 offset:4096
	ds_read_b128 v[216:219], v160 offset:5120
	ds_read_b128 v[220:223], v160 offset:6144
	ds_read_b128 v[224:227], v160 offset:7168
	global_load_lds_dwordx4 v[156:157], off
	v_lshl_add_u64 v[156:157], s[34:35], 0, v[146:147]
	s_add_i32 m0, s39, 0xe000
	s_nop 0
	global_load_lds_dwordx4 v[156:157], off
	s_waitcnt vmcnt(8)
	s_waitcnt lgkmcnt(0)
	s_setprio 1
	s_barrier
	v_mfma_f32_16x16x32_bf16 v[126:129], v[130:133], v[178:181], v[126:129]
	v_mfma_f32_16x16x32_bf16 v[122:125], v[148:151], v[178:181], v[122:125]
	v_mfma_f32_16x16x32_bf16 v[110:113], v[130:133], v[186:189], v[110:113]
	v_mfma_f32_16x16x32_bf16 v[106:109], v[148:151], v[186:189], v[106:109]
	v_mfma_f32_16x16x32_bf16 v[94:97], v[130:133], v[212:215], v[94:97]
	v_mfma_f32_16x16x32_bf16 v[90:93], v[148:151], v[212:215], v[90:93]
	v_mfma_f32_16x16x32_bf16 v[78:81], v[130:133], v[220:223], v[78:81]
	v_mfma_f32_16x16x32_bf16 v[74:77], v[148:151], v[220:223], v[74:77]
	v_mfma_f32_16x16x32_bf16 v[126:129], v[134:137], v[182:185], v[126:129]
	v_mfma_f32_16x16x32_bf16 v[122:125], v[152:155], v[182:185], v[122:125]
	v_mfma_f32_16x16x32_bf16 v[110:113], v[134:137], v[190:193], v[110:113]
	v_mfma_f32_16x16x32_bf16 v[106:109], v[152:155], v[190:193], v[106:109]
	v_mfma_f32_16x16x32_bf16 v[94:97], v[134:137], v[216:219], v[94:97]
	v_mfma_f32_16x16x32_bf16 v[90:93], v[152:155], v[216:219], v[90:93]
	v_mfma_f32_16x16x32_bf16 v[78:81], v[134:137], v[224:227], v[78:81]
	v_mfma_f32_16x16x32_bf16 v[74:77], v[152:155], v[224:227], v[74:77]
	s_setprio 0
	s_setprio 1
	v_mfma_f32_16x16x32_bf16 v[118:121], v[162:165], v[178:181], v[118:121]
	v_mfma_f32_16x16x32_bf16 v[114:117], v[170:173], v[178:181], v[114:117]
	v_mfma_f32_16x16x32_bf16 v[102:105], v[162:165], v[186:189], v[102:105]
	v_mfma_f32_16x16x32_bf16 v[98:101], v[170:173], v[186:189], v[98:101]
	v_mfma_f32_16x16x32_bf16 v[86:89], v[162:165], v[212:215], v[86:89]
	v_mfma_f32_16x16x32_bf16 v[82:85], v[170:173], v[212:215], v[82:85]
	v_mfma_f32_16x16x32_bf16 v[70:73], v[162:165], v[220:223], v[70:73]
	v_mfma_f32_16x16x32_bf16 v[66:69], v[170:173], v[220:223], v[66:69]
	v_mfma_f32_16x16x32_bf16 v[118:121], v[166:169], v[182:185], v[118:121]
	v_mfma_f32_16x16x32_bf16 v[114:117], v[174:177], v[182:185], v[114:117]
	v_mfma_f32_16x16x32_bf16 v[102:105], v[166:169], v[190:193], v[102:105]
	v_mfma_f32_16x16x32_bf16 v[98:101], v[174:177], v[190:193], v[98:101]
	v_mfma_f32_16x16x32_bf16 v[86:89], v[166:169], v[216:219], v[86:89]
	v_mfma_f32_16x16x32_bf16 v[82:85], v[174:177], v[216:219], v[82:85]
	v_mfma_f32_16x16x32_bf16 v[70:73], v[166:169], v[224:227], v[70:73]
	v_mfma_f32_16x16x32_bf16 v[66:69], v[174:177], v[224:227], v[66:69]
	s_setprio 0
	s_barrier
	s_add_i32 s54, s54, s38
	v_lshl_add_u64 v[156:157], s[42:43], 0, v[0:1]
	s_mov_b32 m0, s54
	ds_read_b128 v[178:181], v160 offset:16384
	ds_read_b128 v[182:185], v160 offset:17408
	ds_read_b128 v[186:189], v160 offset:18432
	ds_read_b128 v[190:193], v160 offset:19456
	ds_read_b128 v[212:215], v160 offset:20480
	ds_read_b128 v[216:219], v160 offset:21504
	ds_read_b128 v[220:223], v160 offset:22528
	ds_read_b128 v[224:227], v160 offset:23552
	global_load_lds_dwordx4 v[156:157], off
	s_add_i32 m0, s54, 0x2000
	v_lshl_add_u64 v[194:195], s[42:43], 0, v[142:143]
	s_add_u32 s42, s42, s16
	s_addc_u32 s43, s43, 0
	s_add_i32 s41, s41, s38
	global_load_lds_dwordx4 v[194:195], off
	v_lshl_add_u64 v[200:201], s[42:43], 0, v[0:1]
	s_mov_b32 m0, s41
	v_lshl_add_u64 v[202:203], s[42:43], 0, v[142:143]
	global_load_lds_dwordx4 v[200:201], off
	s_add_i32 m0, s41, 0x2000
	v_lshl_add_u64 v[208:209], s[36:37], 0, v[138:139]
	global_load_lds_dwordx4 v[202:203], off
	s_mov_b32 m0, s39
	v_lshl_add_u64 v[210:211], s[36:37], 0, v[140:141]
	global_load_lds_dwordx4 v[208:209], off
	s_mov_b32 m0, s44
	s_nop 0
	global_load_lds_dwordx4 v[210:211], off
	s_waitcnt vmcnt(8)
	s_waitcnt lgkmcnt(0)
	s_setprio 1
	s_barrier
; #define PG8_STAGE(bufoff, gbase, voff) do { _Pragma("unroll") for (int _i = 0; _i < 2; ++_i) \
;         __builtin_amdgcn_global_load_lds((const unsigned*)((const char*)(gbase) + (voff)[_i]), (PG8_LAS unsigned*)(lds + (bufoff) + ldsw + _i * 8192), 16, 0, 0); } while (0)
; #define PG8_LDA(dst, b, h) do { _Pragma("unroll") for (int m = 0; m < 4; ++m) _Pragma("unroll") for (int k = 0; k < 2; ++k) dst[m][k] = *(const PG8_LAS bf16x8*)(lds + PG8_SA(b, h) + aoff + m * 2048 + k * 1024); } while (0)
; #define PG8_LDB(dst, b, h) do { _Pragma("unroll") for (int n = 0; n < 2; ++n) _Pragma("unroll") for (int k = 0; k < 2; ++k) dst[n][k] = *(const PG8_LAS bf16x8*)(lds + PG8_SB(b, h) + boff + n * 2048 + k * 1024); } while (0)
; #define PG8_MMA(ai, bj, At, Bt) do { __builtin_amdgcn_s_setprio(1); _Pragma("unroll") for (int m = 0; m < 4; ++m) _Pragma("unroll") for (int n = 0; n < 2; ++n) _Pragma("unroll") for (int k = 0; k < 2; ++k) \
;         acc[ai][bj][m][n] = __builtin_amdgcn_mfma_f32_16x16x32_bf16(Bt[n][k], At[m][k], acc[ai][bj][m][n], 0, 0, 0); __builtin_amdgcn_s_setprio(0); } while (0)
; #define PG8_WAIT_V(n) asm volatile("s_waitcnt vmcnt(" #n ")" ::: "memory")
; #define PG8_WAIT_L(n) asm volatile("s_waitcnt lgkmcnt(" #n ")" ::: "memory")
; #define PG8_BAR __builtin_amdgcn_s_barrier()
; #define PG8_SCHED __builtin_amdgcn_sched_barrier(0)
; template <class Epi, class Sched, bool ALIGN_EPI = false, bool SP2 = false>
; __device__ __forceinline__ void gemm_phase(PG8_LAS unsigned char* lds, const Gemm g, const Sched& S, const Epi& E, const int wid) {
;     ...
;             PG8_WAIT_V(8); PG8_WAIT_L(0); PG8_BAR; PG8_MMA(1, 0, At, B0); PG8_MMA(1, 1, At, B1); PG8_BAR; PG8_SCHED;
;             PG8_LDB(B0, 1, 0); PG8_LDB(B1, 1, 1); PG8_SCHED; PG8_LDA(At, 1, 0); PG8_STAGE(PG8_SA(0, 1), a2 + hstep, voffA);
;             PG8_WAIT_V(8); PG8_WAIT_L(0); PG8_BAR; PG8_MMA(0, 0, At, B0); PG8_MMA(0, 1, At, B1); PG8_BAR; PG8_SCHED;
	v_mfma_f32_16x16x32_bf16 v[62:65], v[130:133], v[178:181], v[62:65]
	v_mfma_f32_16x16x32_bf16 v[58:61], v[148:151], v[178:181], v[58:61]
	v_mfma_f32_16x16x32_bf16 v[46:49], v[130:133], v[186:189], v[46:49]
	v_mfma_f32_16x16x32_bf16 v[42:45], v[148:151], v[186:189], v[42:45]
	v_mfma_f32_16x16x32_bf16 v[30:33], v[130:133], v[212:215], v[30:33]
	v_mfma_f32_16x16x32_bf16 v[26:29], v[148:151], v[212:215], v[26:29]
	v_mfma_f32_16x16x32_bf16 v[14:17], v[130:133], v[220:223], v[14:17]
	v_mfma_f32_16x16x32_bf16 v[10:13], v[148:151], v[220:223], v[10:13]
	v_mfma_f32_16x16x32_bf16 v[62:65], v[134:137], v[182:185], v[62:65]
	v_mfma_f32_16x16x32_bf16 v[58:61], v[152:155], v[182:185], v[58:61]
	v_mfma_f32_16x16x32_bf16 v[46:49], v[134:137], v[190:193], v[46:49]
	v_mfma_f32_16x16x32_bf16 v[42:45], v[152:155], v[190:193], v[42:45]
	v_mfma_f32_16x16x32_bf16 v[30:33], v[134:137], v[216:219], v[30:33]
	v_mfma_f32_16x16x32_bf16 v[26:29], v[152:155], v[216:219], v[26:29]
	v_mfma_f32_16x16x32_bf16 v[14:17], v[134:137], v[224:227], v[14:17]
	v_mfma_f32_16x16x32_bf16 v[10:13], v[152:155], v[224:227], v[10:13]
	s_setprio 0
	s_setprio 1
	v_mfma_f32_16x16x32_bf16 v[54:57], v[162:165], v[178:181], v[54:57]
	v_mfma_f32_16x16x32_bf16 v[50:53], v[170:173], v[178:181], v[50:53]
	v_mfma_f32_16x16x32_bf16 v[38:41], v[162:165], v[186:189], v[38:41]
	v_mfma_f32_16x16x32_bf16 v[34:37], v[170:173], v[186:189], v[34:37]
	v_mfma_f32_16x16x32_bf16 v[22:25], v[162:165], v[212:215], v[22:25]
	v_mfma_f32_16x16x32_bf16 v[18:21], v[170:173], v[212:215], v[18:21]
	v_mfma_f32_16x16x32_bf16 v[6:9], v[162:165], v[220:223], v[6:9]
	v_mfma_f32_16x16x32_bf16 v[2:5], v[170:173], v[220:223], v[2:5]
	v_mfma_f32_16x16x32_bf16 v[54:57], v[166:169], v[182:185], v[54:57]
	v_mfma_f32_16x16x32_bf16 v[50:53], v[174:177], v[182:185], v[50:53]
	v_mfma_f32_16x16x32_bf16 v[38:41], v[166:169], v[190:193], v[38:41]
	v_mfma_f32_16x16x32_bf16 v[34:37], v[174:177], v[190:193], v[34:37]
	v_mfma_f32_16x16x32_bf16 v[22:25], v[166:169], v[216:219], v[22:25]
	v_mfma_f32_16x16x32_bf16 v[18:21], v[174:177], v[216:219], v[18:21]
	v_mfma_f32_16x16x32_bf16 v[6:9], v[166:169], v[224:227], v[6:9]
	v_mfma_f32_16x16x32_bf16 v[2:5], v[174:177], v[224:227], v[2:5]
	s_setprio 0
	s_barrier
	s_add_i32 s41, 0, 0x18000
	s_add_i32 s42, 0, 0x1c000
	v_add_u32_e32 v152, s41, v159
	v_add_u32_e32 v161, s42, v159
	ds_read_b128 v[130:133], v152
	ds_read_b128 v[134:137], v152 offset:1024
	ds_read_b128 v[148:151], v152 offset:2048
	ds_read_b128 v[152:155], v152 offset:3072
	ds_read_b128 v[162:165], v161
	ds_read_b128 v[166:169], v161 offset:1024
	ds_read_b128 v[170:173], v161 offset:2048
	ds_read_b128 v[174:177], v161 offset:3072
	s_add_u32 s36, s36, s16
	s_addc_u32 s37, s37, 0
	s_mov_b32 m0, s45
	v_lshl_add_u64 v[228:229], s[36:37], 0, v[138:139]
	ds_read_b128 v[178:181], v160 offset:32768
	ds_read_b128 v[182:185], v160 offset:33792
	ds_read_b128 v[186:189], v160 offset:34816
	ds_read_b128 v[190:193], v160 offset:35840
	ds_read_b128 v[212:215], v160 offset:36864
	ds_read_b128 v[216:219], v160 offset:37888
	ds_read_b128 v[220:223], v160 offset:38912
	ds_read_b128 v[224:227], v160 offset:39936
	global_load_lds_dwordx4 v[228:229], off
	v_lshl_add_u64 v[228:229], s[36:37], 0, v[140:141]
	s_mov_b32 m0, s50
	s_nop 0
	global_load_lds_dwordx4 v[228:229], off
	s_waitcnt vmcnt(8)
	s_waitcnt lgkmcnt(0)
	s_setprio 1
	s_barrier
	v_mfma_f32_16x16x32_bf16 v[126:129], v[130:133], v[178:181], v[126:129]
	v_mfma_f32_16x16x32_bf16 v[122:125], v[148:151], v[178:181], v[122:125]
	v_mfma_f32_16x16x32_bf16 v[110:113], v[130:133], v[186:189], v[110:113]
	v_mfma_f32_16x16x32_bf16 v[106:109], v[148:151], v[186:189], v[106:109]
	v_mfma_f32_16x16x32_bf16 v[94:97], v[130:133], v[212:215], v[94:97]
	v_mfma_f32_16x16x32_bf16 v[90:93], v[148:151], v[212:215], v[90:93]
	v_mfma_f32_16x16x32_bf16 v[78:81], v[130:133], v[220:223], v[78:81]
	v_mfma_f32_16x16x32_bf16 v[74:77], v[148:151], v[220:223], v[74:77]
	v_mfma_f32_16x16x32_bf16 v[126:129], v[134:137], v[182:185], v[126:129]
	v_mfma_f32_16x16x32_bf16 v[122:125], v[152:155], v[182:185], v[122:125]
	v_mfma_f32_16x16x32_bf16 v[110:113], v[134:137], v[190:193], v[110:113]
	v_mfma_f32_16x16x32_bf16 v[106:109], v[152:155], v[190:193], v[106:109]
	v_mfma_f32_16x16x32_bf16 v[94:97], v[134:137], v[216:219], v[94:97]
	v_mfma_f32_16x16x32_bf16 v[90:93], v[152:155], v[216:219], v[90:93]
	v_mfma_f32_16x16x32_bf16 v[78:81], v[134:137], v[224:227], v[78:81]
	v_mfma_f32_16x16x32_bf16 v[74:77], v[152:155], v[224:227], v[74:77]
	s_setprio 0
	s_setprio 1
	v_mfma_f32_16x16x32_bf16 v[118:121], v[162:165], v[178:181], v[118:121]
	v_mfma_f32_16x16x32_bf16 v[114:117], v[170:173], v[178:181], v[114:117]
	v_mfma_f32_16x16x32_bf16 v[102:105], v[162:165], v[186:189], v[102:105]
	v_mfma_f32_16x16x32_bf16 v[98:101], v[170:173], v[186:189], v[98:101]
	v_mfma_f32_16x16x32_bf16 v[86:89], v[162:165], v[212:215], v[86:89]
	v_mfma_f32_16x16x32_bf16 v[82:85], v[170:173], v[212:215], v[82:85]
	v_mfma_f32_16x16x32_bf16 v[70:73], v[162:165], v[220:223], v[70:73]
	v_mfma_f32_16x16x32_bf16 v[66:69], v[170:173], v[220:223], v[66:69]
	v_mfma_f32_16x16x32_bf16 v[118:121], v[166:169], v[182:185], v[118:121]
	v_mfma_f32_16x16x32_bf16 v[114:117], v[174:177], v[182:185], v[114:117]
	v_mfma_f32_16x16x32_bf16 v[102:105], v[166:169], v[190:193], v[102:105]
	v_mfma_f32_16x16x32_bf16 v[98:101], v[174:177], v[190:193], v[98:101]
	v_mfma_f32_16x16x32_bf16 v[86:89], v[166:169], v[216:219], v[86:89]
	v_mfma_f32_16x16x32_bf16 v[82:85], v[174:177], v[216:219], v[82:85]
	v_mfma_f32_16x16x32_bf16 v[70:73], v[166:169], v[224:227], v[70:73]
	v_mfma_f32_16x16x32_bf16 v[66:69], v[174:177], v[224:227], v[66:69]
	s_setprio 0
	s_barrier
; #define PG8_STAGE(bufoff, gbase, voff) do { _Pragma("unroll") for (int _i = 0; _i < 2; ++_i) \
;         __builtin_amdgcn_global_load_lds((const unsigned*)((const char*)(gbase) + (voff)[_i]), (PG8_LAS unsigned*)(lds + (bufoff) + ldsw + _i * 8192), 16, 0, 0); } while (0)
; #define PG8_LDA(dst, b, h) do { _Pragma("unroll") for (int m = 0; m < 4; ++m) _Pragma("unroll") for (int k = 0; k < 2; ++k) dst[m][k] = *(const PG8_LAS bf16x8*)(lds + PG8_SA(b, h) + aoff + m * 2048 + k * 1024); } while (0)
; #define PG8_MMA(ai, bj, At, Bt) do { __builtin_amdgcn_s_setprio(1); _Pragma("unroll") for (int m = 0; m < 4; ++m) _Pragma("unroll") for (int n = 0; n < 2; ++n) _Pragma("unroll") for (int k = 0; k < 2; ++k) \
;         acc[ai][bj][m][n] = __builtin_amdgcn_mfma_f32_16x16x32_bf16(Bt[n][k], At[m][k], acc[ai][bj][m][n], 0, 0, 0); __builtin_amdgcn_s_setprio(0); } while (0)
; #define PG8_WAIT_V(n) asm volatile("s_waitcnt vmcnt(" #n ")" ::: "memory")
; #define PG8_WAIT_L(n) asm volatile("s_waitcnt lgkmcnt(" #n ")" ::: "memory")
; #define PG8_BAR __builtin_amdgcn_s_barrier()
; #define PG8_SCHED __builtin_amdgcn_sched_barrier(0)
; template <class Epi, class Sched, bool ALIGN_EPI = false, bool SP2 = false>
; __device__ __forceinline__ void gemm_phase(PG8_LAS unsigned char* lds, const Gemm g, const Sched& S, const Epi& E, const int wid) {
;     ...
;         for (int t = 0; t < nt; t += 2) {
;     ...
;             PG8_LDA(At, 1, 1); PG8_STAGE(PG8_SB(1, 0), b3, voffB); PG8_STAGE(PG8_SB(1, 1), b3 + hstep, voffB); PG8_STAGE(PG8_SA(1, 0), a3, voffA);
;             PG8_WAIT_V(8); PG8_WAIT_L(0); PG8_BAR; PG8_MMA(1, 0, At, B0); PG8_MMA(1, 1, At, B1); PG8_BAR; PG8_SCHED;
;     ...
;         if constexpr (ALIGN_EPI) { if (wr == 0) PG8_BAR; }
	s_add_i32 s36, s41, s38
	v_lshl_add_u64 v[156:157], v[156:157], 0, s[58:59]
	s_mov_b32 m0, s36
	ds_read_b128 v[178:181], v160 offset:49152
	ds_read_b128 v[182:185], v160 offset:50176
	ds_read_b128 v[186:189], v160 offset:51200
	ds_read_b128 v[190:193], v160 offset:52224
	ds_read_b128 v[212:215], v160 offset:53248
	ds_read_b128 v[216:219], v160 offset:54272
	ds_read_b128 v[220:223], v160 offset:55296
	ds_read_b128 v[224:227], v160 offset:56320
	global_load_lds_dwordx4 v[156:157], off
	v_lshl_add_u64 v[156:157], v[194:195], 0, s[58:59]
	s_add_i32 m0, s36, 0x2000
	s_add_i32 s36, s42, s38
	global_load_lds_dwordx4 v[156:157], off
	v_lshl_add_u64 v[156:157], v[200:201], 0, s[58:59]
	s_mov_b32 m0, s36
	s_nop 0
	global_load_lds_dwordx4 v[156:157], off
	v_lshl_add_u64 v[156:157], v[202:203], 0, s[58:59]
	s_add_i32 m0, s36, 0x2000
	s_nop 0
	global_load_lds_dwordx4 v[156:157], off
	v_lshl_add_u64 v[156:157], v[208:209], 0, s[58:59]
	s_mov_b32 m0, s64
	s_nop 0
	global_load_lds_dwordx4 v[156:157], off
	v_lshl_add_u64 v[156:157], v[210:211], 0, s[58:59]
	s_mov_b32 m0, s65
	s_nop 0
	global_load_lds_dwordx4 v[156:157], off
	s_waitcnt vmcnt(8)
	s_waitcnt lgkmcnt(0)
	s_setprio 1
	s_barrier
	v_mfma_f32_16x16x32_bf16 v[62:65], v[130:133], v[178:181], v[62:65]
	v_mfma_f32_16x16x32_bf16 v[58:61], v[148:151], v[178:181], v[58:61]
	v_mfma_f32_16x16x32_bf16 v[46:49], v[130:133], v[186:189], v[46:49]
	v_mfma_f32_16x16x32_bf16 v[42:45], v[148:151], v[186:189], v[42:45]
	v_mfma_f32_16x16x32_bf16 v[30:33], v[130:133], v[212:215], v[30:33]
	v_mfma_f32_16x16x32_bf16 v[26:29], v[148:151], v[212:215], v[26:29]
	v_mfma_f32_16x16x32_bf16 v[14:17], v[130:133], v[220:223], v[14:17]
	v_mfma_f32_16x16x32_bf16 v[10:13], v[148:151], v[220:223], v[10:13]
	v_mfma_f32_16x16x32_bf16 v[62:65], v[134:137], v[182:185], v[62:65]
	v_mfma_f32_16x16x32_bf16 v[58:61], v[152:155], v[182:185], v[58:61]
	v_mfma_f32_16x16x32_bf16 v[46:49], v[134:137], v[190:193], v[46:49]
	v_mfma_f32_16x16x32_bf16 v[42:45], v[152:155], v[190:193], v[42:45]
	v_mfma_f32_16x16x32_bf16 v[30:33], v[134:137], v[216:219], v[30:33]
	v_mfma_f32_16x16x32_bf16 v[26:29], v[152:155], v[216:219], v[26:29]
	v_mfma_f32_16x16x32_bf16 v[14:17], v[134:137], v[224:227], v[14:17]
	v_mfma_f32_16x16x32_bf16 v[10:13], v[152:155], v[224:227], v[10:13]
	s_setprio 0
	s_setprio 1
	v_mfma_f32_16x16x32_bf16 v[54:57], v[162:165], v[178:181], v[54:57]
	v_mfma_f32_16x16x32_bf16 v[50:53], v[170:173], v[178:181], v[50:53]
	v_mfma_f32_16x16x32_bf16 v[38:41], v[162:165], v[186:189], v[38:41]
	v_mfma_f32_16x16x32_bf16 v[34:37], v[170:173], v[186:189], v[34:37]
	v_mfma_f32_16x16x32_bf16 v[22:25], v[162:165], v[212:215], v[22:25]
	v_mfma_f32_16x16x32_bf16 v[18:21], v[170:173], v[212:215], v[18:21]
	v_mfma_f32_16x16x32_bf16 v[6:9], v[162:165], v[220:223], v[6:9]
	v_mfma_f32_16x16x32_bf16 v[2:5], v[170:173], v[220:223], v[2:5]
	v_mfma_f32_16x16x32_bf16 v[54:57], v[166:169], v[182:185], v[54:57]
	v_mfma_f32_16x16x32_bf16 v[50:53], v[174:177], v[182:185], v[50:53]
	v_mfma_f32_16x16x32_bf16 v[38:41], v[166:169], v[190:193], v[38:41]
	v_mfma_f32_16x16x32_bf16 v[34:37], v[174:177], v[190:193], v[34:37]
	v_mfma_f32_16x16x32_bf16 v[22:25], v[166:169], v[216:219], v[22:25]
	v_mfma_f32_16x16x32_bf16 v[18:21], v[174:177], v[216:219], v[18:21]
	v_mfma_f32_16x16x32_bf16 v[6:9], v[166:169], v[224:227], v[6:9]
	v_mfma_f32_16x16x32_bf16 v[2:5], v[174:177], v[224:227], v[2:5]
	s_setprio 0
	s_barrier
	s_add_u32 s34, s34, 0x100
	s_addc_u32 s35, s35, 0
	s_add_u32 s47, s47, 0x100
	s_addc_u32 s52, s52, 0
	s_cmp_ge_u32 s40, s79
	s_mov_b32 s36, s40
	s_cbranch_scc0 .LBB0_601
	s_and_b64 vcc, exec, s[28:29]
	s_cbranch_vccz .LBB0_604
	s_barrier

; #define PG8_STAGE(bufoff, gbase, voff) do { _Pragma("unroll") for (int _i = 0; _i < 2; ++_i) \
;         __builtin_amdgcn_global_load_lds((const unsigned*)((const char*)(gbase) + (voff)[_i]), (PG8_LAS unsigned*)(lds + (bufoff) + ldsw + _i * 8192), 16, 0, 0); } while (0)
; #define PG8_LDA(dst, b, h) do { _Pragma("unroll") for (int m = 0; m < 4; ++m) _Pragma("unroll") for (int k = 0; k < 2; ++k) dst[m][k] = *(const PG8_LAS bf16x8*)(lds + PG8_SA(b, h) + aoff + m * 2048 + k * 1024); } while (0)
; #define PG8_LDB(dst, b, h) do { _Pragma("unroll") for (int n = 0; n < 2; ++n) _Pragma("unroll") for (int k = 0; k < 2; ++k) dst[n][k] = *(const PG8_LAS bf16x8*)(lds + PG8_SB(b, h) + boff + n * 2048 + k * 1024); } while (0)
; #define PG8_MMA(ai, bj, At, Bt) do { __builtin_amdgcn_s_setprio(1); _Pragma("unroll") for (int m = 0; m < 4; ++m) _Pragma("unroll") for (int n = 0; n < 2; ++n) _Pragma("unroll") for (int k = 0; k < 2; ++k) \
;         acc[ai][bj][m][n] = __builtin_amdgcn_mfma_f32_16x16x32_bf16(Bt[n][k], At[m][k], acc[ai][bj][m][n], 0, 0, 0); __builtin_amdgcn_s_setprio(0); } while (0)
; #define PG8_WAIT_V(n) asm volatile("s_waitcnt vmcnt(" #n ")" ::: "memory")
; #define PG8_WAIT_L(n) asm volatile("s_waitcnt lgkmcnt(" #n ")" ::: "memory")
; template <class Epi, class Sched, bool ALIGN_EPI = false, bool SP2 = false>
; __device__ __forceinline__ void gemm_phase(PG8_LAS unsigned char* lds, const Gemm g, const Sched& S, const Epi& E, const int wid) {
;     ...
;             const bool last = (t == nt - 2);
;             const char* a1 = cA + (size_t)(t + 1) * kstep;
;             const char* a2 = last ? nA : cA + (size_t)(t + 2) * kstep; const char* b2 = last ? nB : cB + (size_t)(t + 2) * kstep;
;             const char* a3 = a2 + kstep; const char* b3 = b2 + kstep;
;             if (last && has_next) S.a_ready(nxt);
;             if constexpr (SP2) {
;             PG8_LDB(B0, 0, 0); PG8_LDB(B1, 0, 1); PG8_SCHED; PG8_LDA(At, 0, 0); PG8_STAGE(PG8_SA(1, 1), a1 + hstep, voffA);
;             PG8_WAIT_V(8); PG8_WAIT_L(0); PG8_BAR; PG8_MMA(0, 0, At, B0); PG8_MMA(0, 1, At, B1); PG8_BAR; PG8_SCHED;
;             PG8_LDA(At, 0, 1); PG8_STAGE(PG8_SB(0, 0), b2, voffB); PG8_STAGE(PG8_SB(0, 1), b2 + hstep, voffB); PG8_STAGE(PG8_SA(0, 0), a2, voffA);
;             PG8_WAIT_V(8); PG8_WAIT_L(0); PG8_BAR; PG8_MMA(1, 0, At, B0); PG8_MMA(1, 1, At, B1); PG8_BAR; PG8_SCHED;
.LBB0_634:
	s_add_u32 s34, s30, 0xfff80080
	s_addc_u32 s35, s31, -1
	s_add_i32 s54, 0, 0x10000
	s_cmp_eq_u32 s50, 28
	s_cselect_b32 s37, s19, s35
	s_cselect_b32 s36, s23, s34
	v_add_u32_e32 v0, s54, v149
	s_cselect_b32 s35, s21, s47
	s_cselect_b32 s34, s29, s46
	s_add_i32 s60, 0, 0x14000
	ds_read_b128 v[142:145], v0
	ds_read_b128 v[152:155], v0 offset:1024
	ds_read_b128 v[156:159], v0 offset:2048
	ds_read_b128 v[160:163], v0 offset:3072
	v_add_u32_e32 v0, s60, v149
	ds_read_b128 v[164:167], v0
	ds_read_b128 v[168:171], v0 offset:1024
	ds_read_b128 v[172:175], v0 offset:2048
	ds_read_b128 v[176:179], v0 offset:3072
	v_lshl_add_u64 v[146:147], s[30:31], 0, v[138:139]
	s_add_i32 m0, s44, 0xc000
	ds_read_b128 v[180:183], v150
	ds_read_b128 v[184:187], v150 offset:1024
	ds_read_b128 v[188:191], v150 offset:2048
	ds_read_b128 v[192:195], v150 offset:3072
	ds_read_b128 v[212:215], v150 offset:4096
	ds_read_b128 v[216:219], v150 offset:5120
	ds_read_b128 v[220:223], v150 offset:6144
	ds_read_b128 v[224:227], v150 offset:7168
	global_load_lds_dwordx4 v[146:147], off
	v_lshl_add_u64 v[146:147], s[30:31], 0, v[140:141]
	s_add_i32 m0, s44, 0xe000
	s_nop 0
	global_load_lds_dwordx4 v[146:147], off
	s_waitcnt vmcnt(8)
	s_waitcnt lgkmcnt(0)
	s_setprio 1
	s_barrier
	v_mfma_f32_16x16x32_bf16 v[126:129], v[142:145], v[180:183], v[126:129]
	v_mfma_f32_16x16x32_bf16 v[122:125], v[156:159], v[180:183], v[122:125]
	v_mfma_f32_16x16x32_bf16 v[110:113], v[142:145], v[188:191], v[110:113]
	v_mfma_f32_16x16x32_bf16 v[106:109], v[156:159], v[188:191], v[106:109]
	v_mfma_f32_16x16x32_bf16 v[94:97], v[142:145], v[212:215], v[94:97]
	v_mfma_f32_16x16x32_bf16 v[90:93], v[156:159], v[212:215], v[90:93]
	v_mfma_f32_16x16x32_bf16 v[78:81], v[142:145], v[220:223], v[78:81]
	v_mfma_f32_16x16x32_bf16 v[74:77], v[156:159], v[220:223], v[74:77]
	v_mfma_f32_16x16x32_bf16 v[126:129], v[152:155], v[184:187], v[126:129]
	v_mfma_f32_16x16x32_bf16 v[122:125], v[160:163], v[184:187], v[122:125]
	v_mfma_f32_16x16x32_bf16 v[110:113], v[152:155], v[192:195], v[110:113]
	v_mfma_f32_16x16x32_bf16 v[106:109], v[160:163], v[192:195], v[106:109]
	v_mfma_f32_16x16x32_bf16 v[94:97], v[152:155], v[216:219], v[94:97]
	v_mfma_f32_16x16x32_bf16 v[90:93], v[160:163], v[216:219], v[90:93]
	v_mfma_f32_16x16x32_bf16 v[78:81], v[152:155], v[224:227], v[78:81]
	v_mfma_f32_16x16x32_bf16 v[74:77], v[160:163], v[224:227], v[74:77]
	s_setprio 0
	s_setprio 1
	v_mfma_f32_16x16x32_bf16 v[118:121], v[164:167], v[180:183], v[118:121]
	v_mfma_f32_16x16x32_bf16 v[114:117], v[172:175], v[180:183], v[114:117]
	v_mfma_f32_16x16x32_bf16 v[102:105], v[164:167], v[188:191], v[102:105]
	v_mfma_f32_16x16x32_bf16 v[98:101], v[172:175], v[188:191], v[98:101]
	v_mfma_f32_16x16x32_bf16 v[86:89], v[164:167], v[212:215], v[86:89]
	v_mfma_f32_16x16x32_bf16 v[82:85], v[172:175], v[212:215], v[82:85]
	v_mfma_f32_16x16x32_bf16 v[70:73], v[164:167], v[220:223], v[70:73]
	v_mfma_f32_16x16x32_bf16 v[66:69], v[172:175], v[220:223], v[66:69]
	v_mfma_f32_16x16x32_bf16 v[118:121], v[168:171], v[184:187], v[118:121]
	v_mfma_f32_16x16x32_bf16 v[114:117], v[176:179], v[184:187], v[114:117]
	v_mfma_f32_16x16x32_bf16 v[102:105], v[168:171], v[192:195], v[102:105]
	v_mfma_f32_16x16x32_bf16 v[98:101], v[176:179], v[192:195], v[98:101]
	v_mfma_f32_16x16x32_bf16 v[86:89], v[168:171], v[216:219], v[86:89]
	v_mfma_f32_16x16x32_bf16 v[82:85], v[176:179], v[216:219], v[82:85]
	v_mfma_f32_16x16x32_bf16 v[70:73], v[168:171], v[224:227], v[70:73]
	v_mfma_f32_16x16x32_bf16 v[66:69], v[176:179], v[224:227], v[66:69]
	s_setprio 0
	s_barrier
	s_add_i32 s54, s54, s42
	v_lshl_add_u64 v[146:147], s[34:35], 0, v[134:135]
	s_mov_b32 m0, s54
	ds_read_b128 v[180:183], v150 offset:16384
	ds_read_b128 v[184:187], v150 offset:17408
	ds_read_b128 v[188:191], v150 offset:18432
	ds_read_b128 v[192:195], v150 offset:19456
	ds_read_b128 v[212:215], v150 offset:20480
	ds_read_b128 v[216:219], v150 offset:21504
	ds_read_b128 v[220:223], v150 offset:22528
	ds_read_b128 v[224:227], v150 offset:23552
	global_load_lds_dwordx4 v[146:147], off
	s_add_i32 m0, s54, 0x2000
	s_add_u32 s54, s34, 0x80000
	v_lshl_add_u64 v[200:201], s[34:35], 0, v[130:131]
	s_addc_u32 s55, s35, 0
	s_add_i32 s60, s60, s42
	global_load_lds_dwordx4 v[200:201], off
	v_lshl_add_u64 v[202:203], s[54:55], 0, v[134:135]
	s_mov_b32 m0, s60
	v_lshl_add_u64 v[208:209], s[36:37], 0, v[132:133]
	global_load_lds_dwordx4 v[202:203], off
	v_lshl_add_u64 v[202:203], s[54:55], 0, v[130:131]
	s_add_i32 m0, s60, 0x2000
	s_nop 0
	global_load_lds_dwordx4 v[202:203], off
	v_lshl_add_u64 v[202:203], s[36:37], 0, v[136:137]
	s_mov_b32 m0, s44
	s_nop 0
	global_load_lds_dwordx4 v[202:203], off
	s_mov_b32 m0, s45
	s_nop 0
	global_load_lds_dwordx4 v[208:209], off
	s_waitcnt vmcnt(8)
	s_waitcnt lgkmcnt(0)
	s_setprio 1
	s_barrier
; #define PG8_STAGE(bufoff, gbase, voff) do { _Pragma("unroll") for (int _i = 0; _i < 2; ++_i) \
;         __builtin_amdgcn_global_load_lds((const unsigned*)((const char*)(gbase) + (voff)[_i]), (PG8_LAS unsigned*)(lds + (bufoff) + ldsw + _i * 8192), 16, 0, 0); } while (0)
; #define PG8_LDA(dst, b, h) do { _Pragma("unroll") for (int m = 0; m < 4; ++m) _Pragma("unroll") for (int k = 0; k < 2; ++k) dst[m][k] = *(const PG8_LAS bf16x8*)(lds + PG8_SA(b, h) + aoff + m * 2048 + k * 1024); } while (0)
; #define PG8_LDB(dst, b, h) do { _Pragma("unroll") for (int n = 0; n < 2; ++n) _Pragma("unroll") for (int k = 0; k < 2; ++k) dst[n][k] = *(const PG8_LAS bf16x8*)(lds + PG8_SB(b, h) + boff + n * 2048 + k * 1024); } while (0)
; #define PG8_MMA(ai, bj, At, Bt) do { __builtin_amdgcn_s_setprio(1); _Pragma("unroll") for (int m = 0; m < 4; ++m) _Pragma("unroll") for (int n = 0; n < 2; ++n) _Pragma("unroll") for (int k = 0; k < 2; ++k) \
;         acc[ai][bj][m][n] = __builtin_amdgcn_mfma_f32_16x16x32_bf16(Bt[n][k], At[m][k], acc[ai][bj][m][n], 0, 0, 0); __builtin_amdgcn_s_setprio(0); } while (0)
; #define PG8_WAIT_V(n) asm volatile("s_waitcnt vmcnt(" #n ")" ::: "memory")
; #define PG8_WAIT_L(n) asm volatile("s_waitcnt lgkmcnt(" #n ")" ::: "memory")
; #define PG8_BAR __builtin_amdgcn_s_barrier()
; #define PG8_SCHED __builtin_amdgcn_sched_barrier(0)
; template <class Epi, class Sched, bool ALIGN_EPI = false, bool SP2 = false>
; __device__ __forceinline__ void gemm_phase(PG8_LAS unsigned char* lds, const Gemm g, const Sched& S, const Epi& E, const int wid) {
;     ...
;             PG8_WAIT_V(8); PG8_WAIT_L(0); PG8_BAR; PG8_MMA(1, 0, At, B0); PG8_MMA(1, 1, At, B1); PG8_BAR; PG8_SCHED;
;             PG8_LDB(B0, 1, 0); PG8_LDB(B1, 1, 1); PG8_SCHED; PG8_LDA(At, 1, 0); PG8_STAGE(PG8_SA(0, 1), a2 + hstep, voffA);
;             PG8_WAIT_V(8); PG8_WAIT_L(0); PG8_BAR; PG8_MMA(0, 0, At, B0); PG8_MMA(0, 1, At, B1); PG8_BAR; PG8_SCHED;
	v_mfma_f32_16x16x32_bf16 v[62:65], v[142:145], v[180:183], v[62:65]
	v_mfma_f32_16x16x32_bf16 v[58:61], v[156:159], v[180:183], v[58:61]
	v_mfma_f32_16x16x32_bf16 v[46:49], v[142:145], v[188:191], v[46:49]
	v_mfma_f32_16x16x32_bf16 v[42:45], v[156:159], v[188:191], v[42:45]
	v_mfma_f32_16x16x32_bf16 v[30:33], v[142:145], v[212:215], v[30:33]
	v_mfma_f32_16x16x32_bf16 v[26:29], v[156:159], v[212:215], v[26:29]
	v_mfma_f32_16x16x32_bf16 v[14:17], v[142:145], v[220:223], v[14:17]
	v_mfma_f32_16x16x32_bf16 v[10:13], v[156:159], v[220:223], v[10:13]
	v_mfma_f32_16x16x32_bf16 v[62:65], v[152:155], v[184:187], v[62:65]
	v_mfma_f32_16x16x32_bf16 v[58:61], v[160:163], v[184:187], v[58:61]
	v_mfma_f32_16x16x32_bf16 v[46:49], v[152:155], v[192:195], v[46:49]
	v_mfma_f32_16x16x32_bf16 v[42:45], v[160:163], v[192:195], v[42:45]
	v_mfma_f32_16x16x32_bf16 v[30:33], v[152:155], v[216:219], v[30:33]
	v_mfma_f32_16x16x32_bf16 v[26:29], v[160:163], v[216:219], v[26:29]
	v_mfma_f32_16x16x32_bf16 v[14:17], v[152:155], v[224:227], v[14:17]
	v_mfma_f32_16x16x32_bf16 v[10:13], v[160:163], v[224:227], v[10:13]
	s_setprio 0
	s_setprio 1
	v_mfma_f32_16x16x32_bf16 v[54:57], v[164:167], v[180:183], v[54:57]
	v_mfma_f32_16x16x32_bf16 v[50:53], v[172:175], v[180:183], v[50:53]
	v_mfma_f32_16x16x32_bf16 v[38:41], v[164:167], v[188:191], v[38:41]
	v_mfma_f32_16x16x32_bf16 v[34:37], v[172:175], v[188:191], v[34:37]
	v_mfma_f32_16x16x32_bf16 v[22:25], v[164:167], v[212:215], v[22:25]
	v_mfma_f32_16x16x32_bf16 v[18:21], v[172:175], v[212:215], v[18:21]
	v_mfma_f32_16x16x32_bf16 v[6:9], v[164:167], v[220:223], v[6:9]
	v_mfma_f32_16x16x32_bf16 v[2:5], v[172:175], v[220:223], v[2:5]
	v_mfma_f32_16x16x32_bf16 v[54:57], v[168:171], v[184:187], v[54:57]
	v_mfma_f32_16x16x32_bf16 v[50:53], v[176:179], v[184:187], v[50:53]
	v_mfma_f32_16x16x32_bf16 v[38:41], v[168:171], v[192:195], v[38:41]
	v_mfma_f32_16x16x32_bf16 v[34:37], v[176:179], v[192:195], v[34:37]
	v_mfma_f32_16x16x32_bf16 v[22:25], v[168:171], v[216:219], v[22:25]
	v_mfma_f32_16x16x32_bf16 v[18:21], v[176:179], v[216:219], v[18:21]
	v_mfma_f32_16x16x32_bf16 v[6:9], v[168:171], v[224:227], v[6:9]
	v_mfma_f32_16x16x32_bf16 v[2:5], v[176:179], v[224:227], v[2:5]
	s_setprio 0
	s_barrier
	s_add_i32 s54, 0, 0x18000
	v_add_u32_e32 v0, s54, v149
	s_add_i32 s55, 0, 0x1c000
	ds_read_b128 v[142:145], v0
	ds_read_b128 v[152:155], v0 offset:1024
	ds_read_b128 v[156:159], v0 offset:2048
	ds_read_b128 v[160:163], v0 offset:3072
	v_add_u32_e32 v0, s55, v149
	ds_read_b128 v[164:167], v0
	ds_read_b128 v[168:171], v0 offset:1024
	ds_read_b128 v[172:175], v0 offset:2048
	ds_read_b128 v[176:179], v0 offset:3072
	s_add_u32 s36, s36, 0x80000
	s_addc_u32 s37, s37, 0
	s_mov_b32 m0, s52
	v_lshl_add_u64 v[210:211], s[36:37], 0, v[136:137]
	ds_read_b128 v[180:183], v150 offset:32768
	ds_read_b128 v[184:187], v150 offset:33792
	ds_read_b128 v[188:191], v150 offset:34816
	ds_read_b128 v[192:195], v150 offset:35840
	ds_read_b128 v[212:215], v150 offset:36864
	ds_read_b128 v[216:219], v150 offset:37888
	ds_read_b128 v[220:223], v150 offset:38912
	ds_read_b128 v[224:227], v150 offset:39936
	global_load_lds_dwordx4 v[210:211], off
	v_lshl_add_u64 v[210:211], s[36:37], 0, v[132:133]
	s_mov_b32 m0, s68
	s_nop 0
	global_load_lds_dwordx4 v[210:211], off
	s_waitcnt vmcnt(8)
	s_waitcnt lgkmcnt(0)
	s_setprio 1
	s_barrier
	v_mfma_f32_16x16x32_bf16 v[126:129], v[142:145], v[180:183], v[126:129]
	v_mfma_f32_16x16x32_bf16 v[122:125], v[156:159], v[180:183], v[122:125]
	v_mfma_f32_16x16x32_bf16 v[110:113], v[142:145], v[188:191], v[110:113]
	v_mfma_f32_16x16x32_bf16 v[106:109], v[156:159], v[188:191], v[106:109]
	v_mfma_f32_16x16x32_bf16 v[94:97], v[142:145], v[212:215], v[94:97]
	v_mfma_f32_16x16x32_bf16 v[90:93], v[156:159], v[212:215], v[90:93]
	v_mfma_f32_16x16x32_bf16 v[78:81], v[142:145], v[220:223], v[78:81]
	v_mfma_f32_16x16x32_bf16 v[74:77], v[156:159], v[220:223], v[74:77]
	v_mfma_f32_16x16x32_bf16 v[126:129], v[152:155], v[184:187], v[126:129]
	v_mfma_f32_16x16x32_bf16 v[122:125], v[160:163], v[184:187], v[122:125]
	v_mfma_f32_16x16x32_bf16 v[110:113], v[152:155], v[192:195], v[110:113]
	v_mfma_f32_16x16x32_bf16 v[106:109], v[160:163], v[192:195], v[106:109]
	v_mfma_f32_16x16x32_bf16 v[94:97], v[152:155], v[216:219], v[94:97]
	v_mfma_f32_16x16x32_bf16 v[90:93], v[160:163], v[216:219], v[90:93]
	v_mfma_f32_16x16x32_bf16 v[78:81], v[152:155], v[224:227], v[78:81]
	v_mfma_f32_16x16x32_bf16 v[74:77], v[160:163], v[224:227], v[74:77]
	s_setprio 0
	s_setprio 1
	v_mfma_f32_16x16x32_bf16 v[118:121], v[164:167], v[180:183], v[118:121]
	v_mfma_f32_16x16x32_bf16 v[114:117], v[172:175], v[180:183], v[114:117]
	v_mfma_f32_16x16x32_bf16 v[102:105], v[164:167], v[188:191], v[102:105]
	v_mfma_f32_16x16x32_bf16 v[98:101], v[172:175], v[188:191], v[98:101]
	v_mfma_f32_16x16x32_bf16 v[86:89], v[164:167], v[212:215], v[86:89]
	v_mfma_f32_16x16x32_bf16 v[82:85], v[172:175], v[212:215], v[82:85]
	v_mfma_f32_16x16x32_bf16 v[70:73], v[164:167], v[220:223], v[70:73]
	v_mfma_f32_16x16x32_bf16 v[66:69], v[172:175], v[220:223], v[66:69]
	v_mfma_f32_16x16x32_bf16 v[118:121], v[168:171], v[184:187], v[118:121]
	v_mfma_f32_16x16x32_bf16 v[114:117], v[176:179], v[184:187], v[114:117]
	v_mfma_f32_16x16x32_bf16 v[102:105], v[168:171], v[192:195], v[102:105]
	v_mfma_f32_16x16x32_bf16 v[98:101], v[176:179], v[192:195], v[98:101]
	v_mfma_f32_16x16x32_bf16 v[86:89], v[168:171], v[216:219], v[86:89]
	v_mfma_f32_16x16x32_bf16 v[82:85], v[176:179], v[216:219], v[82:85]
	v_mfma_f32_16x16x32_bf16 v[70:73], v[168:171], v[224:227], v[70:73]
	v_mfma_f32_16x16x32_bf16 v[66:69], v[176:179], v[224:227], v[66:69]
	s_setprio 0
	s_barrier
; #define PG8_STAGE(bufoff, gbase, voff) do { _Pragma("unroll") for (int _i = 0; _i < 2; ++_i) \
;         __builtin_amdgcn_global_load_lds((const unsigned*)((const char*)(gbase) + (voff)[_i]), (PG8_LAS unsigned*)(lds + (bufoff) + ldsw + _i * 8192), 16, 0, 0); } while (0)
; #define PG8_LDA(dst, b, h) do { _Pragma("unroll") for (int m = 0; m < 4; ++m) _Pragma("unroll") for (int k = 0; k < 2; ++k) dst[m][k] = *(const PG8_LAS bf16x8*)(lds + PG8_SA(b, h) + aoff + m * 2048 + k * 1024); } while (0)
; #define PG8_MMA(ai, bj, At, Bt) do { __builtin_amdgcn_s_setprio(1); _Pragma("unroll") for (int m = 0; m < 4; ++m) _Pragma("unroll") for (int n = 0; n < 2; ++n) _Pragma("unroll") for (int k = 0; k < 2; ++k) \
;         acc[ai][bj][m][n] = __builtin_amdgcn_mfma_f32_16x16x32_bf16(Bt[n][k], At[m][k], acc[ai][bj][m][n], 0, 0, 0); __builtin_amdgcn_s_setprio(0); } while (0)
; #define PG8_WAIT_V(n) asm volatile("s_waitcnt vmcnt(" #n ")" ::: "memory")
; #define PG8_WAIT_L(n) asm volatile("s_waitcnt lgkmcnt(" #n ")" ::: "memory")
; #define PG8_BAR __builtin_amdgcn_s_barrier()
; #define PG8_SCHED __builtin_amdgcn_sched_barrier(0)
; template <class Epi, class Sched, bool ALIGN_EPI = false, bool SP2 = false>
; __device__ __forceinline__ void gemm_phase(PG8_LAS unsigned char* lds, const Gemm g, const Sched& S, const Epi& E, const int wid) {
;     ...
;         for (int t = 0; t < nt; t += 2) {
;     ...
;             PG8_LDA(At, 1, 1); PG8_STAGE(PG8_SB(1, 0), b3, voffB); PG8_STAGE(PG8_SB(1, 1), b3 + hstep, voffB); PG8_STAGE(PG8_SA(1, 0), a3, voffA);
;             PG8_WAIT_V(8); PG8_WAIT_L(0); PG8_BAR; PG8_MMA(1, 0, At, B0); PG8_MMA(1, 1, At, B1); PG8_BAR; PG8_SCHED;
;     ...
;         if constexpr (ALIGN_EPI) { if (wr == 0) PG8_BAR; }
	s_add_i32 s36, s54, s42
	v_lshl_add_u64 v[146:147], v[146:147], 0, s[58:59]
	s_mov_b32 m0, s36
	ds_read_b128 v[180:183], v150 offset:49152
	ds_read_b128 v[184:187], v150 offset:50176
	ds_read_b128 v[188:191], v150 offset:51200
	ds_read_b128 v[192:195], v150 offset:52224
	ds_read_b128 v[212:215], v150 offset:53248
	ds_read_b128 v[216:219], v150 offset:54272
	ds_read_b128 v[220:223], v150 offset:55296
	ds_read_b128 v[224:227], v150 offset:56320
	global_load_lds_dwordx4 v[146:147], off
	s_add_i32 m0, s36, 0x2000
	s_add_u32 s34, s34, 0x80080
	v_lshl_add_u64 v[146:147], v[200:201], 0, s[58:59]
	s_addc_u32 s35, s35, 0
	s_add_i32 s36, s55, s42
	global_load_lds_dwordx4 v[146:147], off
	v_lshl_add_u64 v[146:147], s[34:35], 0, v[134:135]
	s_mov_b32 m0, s36
	s_nop 0
	global_load_lds_dwordx4 v[146:147], off
	v_lshl_add_u64 v[146:147], s[34:35], 0, v[130:131]
	s_add_i32 m0, s36, 0x2000
	s_nop 0
	global_load_lds_dwordx4 v[146:147], off
	v_lshl_add_u64 v[146:147], v[202:203], 0, s[58:59]
	s_mov_b32 m0, s84
	s_nop 0
	global_load_lds_dwordx4 v[146:147], off
	v_lshl_add_u64 v[146:147], v[208:209], 0, s[58:59]
	s_mov_b32 m0, s85
	s_nop 0
	global_load_lds_dwordx4 v[146:147], off
	s_waitcnt vmcnt(8)
	s_waitcnt lgkmcnt(0)
	s_setprio 1
	s_barrier
	v_mfma_f32_16x16x32_bf16 v[62:65], v[142:145], v[180:183], v[62:65]
	v_mfma_f32_16x16x32_bf16 v[58:61], v[156:159], v[180:183], v[58:61]
	v_mfma_f32_16x16x32_bf16 v[46:49], v[142:145], v[188:191], v[46:49]
	v_mfma_f32_16x16x32_bf16 v[42:45], v[156:159], v[188:191], v[42:45]
	v_mfma_f32_16x16x32_bf16 v[30:33], v[142:145], v[212:215], v[30:33]
	v_mfma_f32_16x16x32_bf16 v[26:29], v[156:159], v[212:215], v[26:29]
	v_mfma_f32_16x16x32_bf16 v[14:17], v[142:145], v[220:223], v[14:17]
	v_mfma_f32_16x16x32_bf16 v[10:13], v[156:159], v[220:223], v[10:13]
	v_mfma_f32_16x16x32_bf16 v[62:65], v[152:155], v[184:187], v[62:65]
	v_mfma_f32_16x16x32_bf16 v[58:61], v[160:163], v[184:187], v[58:61]
	v_mfma_f32_16x16x32_bf16 v[46:49], v[152:155], v[192:195], v[46:49]
	v_mfma_f32_16x16x32_bf16 v[42:45], v[160:163], v[192:195], v[42:45]
	v_mfma_f32_16x16x32_bf16 v[30:33], v[152:155], v[216:219], v[30:33]
	v_mfma_f32_16x16x32_bf16 v[26:29], v[160:163], v[216:219], v[26:29]
	v_mfma_f32_16x16x32_bf16 v[14:17], v[152:155], v[224:227], v[14:17]
	v_mfma_f32_16x16x32_bf16 v[10:13], v[160:163], v[224:227], v[10:13]
	s_setprio 0
	s_setprio 1
	v_mfma_f32_16x16x32_bf16 v[54:57], v[164:167], v[180:183], v[54:57]
	v_mfma_f32_16x16x32_bf16 v[50:53], v[172:175], v[180:183], v[50:53]
	v_mfma_f32_16x16x32_bf16 v[38:41], v[164:167], v[188:191], v[38:41]
	v_mfma_f32_16x16x32_bf16 v[34:37], v[172:175], v[188:191], v[34:37]
	v_mfma_f32_16x16x32_bf16 v[22:25], v[164:167], v[212:215], v[22:25]
	v_mfma_f32_16x16x32_bf16 v[18:21], v[172:175], v[212:215], v[18:21]
	v_mfma_f32_16x16x32_bf16 v[6:9], v[164:167], v[220:223], v[6:9]
	v_mfma_f32_16x16x32_bf16 v[2:5], v[172:175], v[220:223], v[2:5]
	v_mfma_f32_16x16x32_bf16 v[54:57], v[168:171], v[184:187], v[54:57]
	v_mfma_f32_16x16x32_bf16 v[50:53], v[176:179], v[184:187], v[50:53]
	v_mfma_f32_16x16x32_bf16 v[38:41], v[168:171], v[192:195], v[38:41]
	v_mfma_f32_16x16x32_bf16 v[34:37], v[176:179], v[192:195], v[34:37]
	v_mfma_f32_16x16x32_bf16 v[22:25], v[168:171], v[216:219], v[22:25]
	v_mfma_f32_16x16x32_bf16 v[18:21], v[176:179], v[216:219], v[18:21]
	v_mfma_f32_16x16x32_bf16 v[6:9], v[168:171], v[224:227], v[6:9]
	v_mfma_f32_16x16x32_bf16 v[2:5], v[176:179], v[224:227], v[2:5]
	s_setprio 0
	s_barrier
	s_add_i32 s50, s50, 2
	s_add_u32 s30, s30, 0x100
	s_addc_u32 s31, s31, 0
	s_add_u32 s46, s46, 0x100
	s_addc_u32 s47, s47, 0
	s_cmp_gt_u32 s50, 29
	s_cbranch_scc0 .LBB0_634
	s_and_b64 vcc, exec, s[16:17]
	s_cbranch_vccz .LBB0_637
	s_barrier
